# v65 plus K-loop back-edge rotation (loop-control SALU in the last MFMA block) and mixer C interior tiles without key mask (loop split into first trip + unmasked trips)
# baseline (speedup 1.0000x reference)
; #define PG8_STAGE(bufoff, gbase, voff) do { _Pragma("unroll") for (int _i = 0; _i < 2; ++_i) \
;         __builtin_amdgcn_global_load_lds((const unsigned*)((const char*)(gbase) + (voff)[_i]), (PG8_LAS unsigned*)(lds + (bufoff) + ldsw + _i * 8192), 16, 0, 0); } while (0)
; #define PG8_LDA(dst, b, h) do { _Pragma("unroll") for (int m = 0; m < 4; ++m) _Pragma("unroll") for (int k = 0; k < 2; ++k) dst[m][k] = *(const PG8_LAS bf16x8*)(lds + PG8_SA(b, h) + aoff + m * 2048 + k * 1024); } while (0)
; #define PG8_LDB(dst, b, h) do { _Pragma("unroll") for (int n = 0; n < 2; ++n) _Pragma("unroll") for (int k = 0; k < 2; ++k) dst[n][k] = *(const PG8_LAS bf16x8*)(lds + PG8_SB(b, h) + boff + n * 2048 + k * 1024); } while (0)
; #define PG8_MMA(ai, bj, At, Bt) do { __builtin_amdgcn_s_setprio(1); _Pragma("unroll") for (int m = 0; m < 4; ++m) _Pragma("unroll") for (int n = 0; n < 2; ++n) _Pragma("unroll") for (int k = 0; k < 2; ++k) \
;         acc[ai][bj][m][n] = __builtin_amdgcn_mfma_f32_16x16x32_bf16(Bt[n][k], At[m][k], acc[ai][bj][m][n], 0, 0, 0); __builtin_amdgcn_s_setprio(0); } while (0)
; #define PG8_WAIT_V(n) asm volatile("s_waitcnt vmcnt(" #n ")" ::: "memory")
; #define PG8_BAR __builtin_amdgcn_s_barrier()
; template <class Epi, class Sched, bool ALIGN_EPI = false, bool SP2 = false>
; __device__ __forceinline__ void gemm_phase(PG8_LAS unsigned char* lds, const Gemm g, const Sched& S, const Epi& E, int tid_in) {
;     ...
;         for (int t = 0; t < nt; t += 2) {
;             const bool last = (t == nt - 2);
;             const char* a1 = cA + (size_t)(t + 1) * kstep;
;             const char* a2 = last ? nA : cA + (size_t)(t + 2) * kstep; const char* b2 = last ? nB : cB + (size_t)(t + 2) * kstep;
;             const char* a3 = a2 + kstep; const char* b3 = b2 + kstep;
;             if (last && has_next) S.a_ready(nxt);
;             if constexpr (SP2) {
;             PG8_LDB(B0, 0, 0); PG8_LDB(B1, 0, 1); PG8_SCHED; PG8_LDA(At, 0, 0); PG8_STAGE(PG8_SA(1, 1), a1 + hstep, voffA);
;             PG8_WAIT_V(8); PG8_WAIT_L(0); PG8_BAR; PG8_MMA(0, 0, At, B0); PG8_MMA(0, 1, At, B1); PG8_BAR; PG8_SCHED;
;             PG8_LDA(At, 0, 1); PG8_STAGE(PG8_SB(0, 0), b2, voffB); PG8_STAGE(PG8_SB(0, 1), b2 + hstep, voffB); PG8_STAGE(PG8_SA(0, 0), a2, voffA);
;             PG8_WAIT_V(8); PG8_WAIT_L(0); PG8_BAR; PG8_MMA(1, 0, At, B0); PG8_MMA(1, 1, At, B1); PG8_BAR; PG8_SCHED;
.Lpeel_enter_g1:
	s_add_u32 s0, s0, 0x80
	s_addc_u32 s1, s1, 0
	s_add_u32 s22, s22, 0x100
	s_addc_u32 s23, s23, 0
	s_mov_b32 s4, 0
	s_add_i32 s36, s4, 2
	s_add_u32 s37, s0, 0x80
	s_addc_u32 s5, s1, 0
	s_add_i32 s90, 0, 0x10000
	s_cmp_eq_u32 s57, s4
	s_cselect_b32 s5, s39, s5
	s_cselect_b32 s4, s38, s37
	v_add_u32_e32 v144, s90, v151
	s_cselect_b32 s89, s45, s23
	s_cselect_b32 s88, s44, s22
	s_add_i32 s37, 0, 0x14000
	ds_read_b128 v[140:143], v144
	ds_read_b128 v[166:169], v144 offset:1024
	ds_read_b128 v[170:173], v144 offset:2048
	ds_read_b128 v[174:177], v144 offset:3072
	v_add_u32_e32 v144, s37, v151
	ds_read_b128 v[178:181], v144
	ds_read_b128 v[182:185], v144 offset:1024
	ds_read_b128 v[186:189], v144 offset:2048
	ds_read_b128 v[190:193], v144 offset:3072
	v_lshl_add_u64 v[144:145], s[0:1], 0, v[136:137]
	s_add_i32 m0, s43, 0xc000
	ds_read_b128 v[194:197], v161
	ds_read_b128 v[198:201], v161 offset:1024
	ds_read_b128 v[202:205], v161 offset:2048
	ds_read_b128 v[206:209], v161 offset:3072
	ds_read_b128 v[210:213], v161 offset:4096
	ds_read_b128 v[214:217], v161 offset:5120
	ds_read_b128 v[218:221], v161 offset:6144
	ds_read_b128 v[222:225], v161 offset:7168
	global_load_lds_dwordx4 v[144:145], off
	v_lshl_add_u64 v[144:145], s[0:1], 0, v[138:139]
	s_add_i32 m0, s43, 0xe000
	s_nop 0
	global_load_lds_dwordx4 v[144:145], off
	s_waitcnt vmcnt(8)
	s_waitcnt lgkmcnt(0)
	s_barrier
	s_waitcnt lgkmcnt(0)
	v_mfma_f32_16x16x32_bf16 v[124:127], v[140:143], v[194:197], 0
	v_mfma_f32_16x16x32_bf16 v[120:123], v[170:173], v[194:197], 0
	v_mfma_f32_16x16x32_bf16 v[108:111], v[140:143], v[202:205], 0
	v_mfma_f32_16x16x32_bf16 v[104:107], v[170:173], v[202:205], 0
	v_mfma_f32_16x16x32_bf16 v[92:95], v[140:143], v[210:213], 0
	v_mfma_f32_16x16x32_bf16 v[88:91], v[170:173], v[210:213], 0
	v_mfma_f32_16x16x32_bf16 v[76:79], v[140:143], v[218:221], 0
	v_mfma_f32_16x16x32_bf16 v[72:75], v[170:173], v[218:221], 0
	v_mfma_f32_16x16x32_bf16 v[124:127], v[166:169], v[198:201], v[124:127]
	v_mfma_f32_16x16x32_bf16 v[120:123], v[174:177], v[198:201], v[120:123]
	v_mfma_f32_16x16x32_bf16 v[108:111], v[166:169], v[206:209], v[108:111]
	v_mfma_f32_16x16x32_bf16 v[104:107], v[174:177], v[206:209], v[104:107]
	v_mfma_f32_16x16x32_bf16 v[92:95], v[166:169], v[214:217], v[92:95]
	v_mfma_f32_16x16x32_bf16 v[88:91], v[174:177], v[214:217], v[88:91]
	v_mfma_f32_16x16x32_bf16 v[76:79], v[166:169], v[222:225], v[76:79]
	v_mfma_f32_16x16x32_bf16 v[72:75], v[174:177], v[222:225], v[72:75]
	v_mfma_f32_16x16x32_bf16 v[116:119], v[178:181], v[194:197], 0
	v_mfma_f32_16x16x32_bf16 v[112:115], v[186:189], v[194:197], 0
	v_mfma_f32_16x16x32_bf16 v[100:103], v[178:181], v[202:205], 0
	v_mfma_f32_16x16x32_bf16 v[96:99], v[186:189], v[202:205], 0
	v_mfma_f32_16x16x32_bf16 v[84:87], v[178:181], v[210:213], 0
	v_mfma_f32_16x16x32_bf16 v[80:83], v[186:189], v[210:213], 0
	v_mfma_f32_16x16x32_bf16 v[68:71], v[178:181], v[218:221], 0
	v_mfma_f32_16x16x32_bf16 v[64:67], v[186:189], v[218:221], 0
	v_mfma_f32_16x16x32_bf16 v[116:119], v[182:185], v[198:201], v[116:119]
	v_mfma_f32_16x16x32_bf16 v[112:115], v[190:193], v[198:201], v[112:115]
	v_mfma_f32_16x16x32_bf16 v[100:103], v[182:185], v[206:209], v[100:103]
	v_mfma_f32_16x16x32_bf16 v[96:99], v[190:193], v[206:209], v[96:99]
	v_mfma_f32_16x16x32_bf16 v[84:87], v[182:185], v[214:217], v[84:87]
	v_mfma_f32_16x16x32_bf16 v[80:83], v[190:193], v[214:217], v[80:83]
	v_mfma_f32_16x16x32_bf16 v[68:71], v[182:185], v[222:225], v[68:71]
	v_mfma_f32_16x16x32_bf16 v[64:67], v[190:193], v[222:225], v[64:67]
	s_barrier
	s_add_i32 s90, s90, s42
	v_lshl_add_u64 v[144:145], s[88:89], 0, v[156:157]
	s_mov_b32 m0, s90
	ds_read_b128 v[194:197], v161 offset:16384
	ds_read_b128 v[198:201], v161 offset:17408
	ds_read_b128 v[202:205], v161 offset:18432
	ds_read_b128 v[206:209], v161 offset:19456
	ds_read_b128 v[210:213], v161 offset:20480
	ds_read_b128 v[214:217], v161 offset:21504
	ds_read_b128 v[218:221], v161 offset:22528
	ds_read_b128 v[222:225], v161 offset:23552
	global_load_lds_dwordx4 v[144:145], off
	s_add_i32 m0, s90, 0x2000
	v_lshl_add_u64 v[226:227], s[88:89], 0, v[128:129]
	s_add_u32 s88, s88, s8
	s_addc_u32 s89, s89, s9
	s_add_i32 s37, s37, s42
	global_load_lds_dwordx4 v[226:227], off
	v_lshl_add_u64 v[228:229], s[88:89], 0, v[156:157]
	s_mov_b32 m0, s37
	v_lshl_add_u64 v[238:239], s[88:89], 0, v[128:129]
	global_load_lds_dwordx4 v[228:229], off
	s_add_i32 m0, s37, 0x2000
	v_lshl_add_u64 v[240:241], s[4:5], 0, v[132:133]
	global_load_lds_dwordx4 v[238:239], off
	s_mov_b32 m0, s43
	v_lshl_add_u64 v[242:243], s[4:5], 0, v[130:131]
	global_load_lds_dwordx4 v[240:241], off
	s_mov_b32 m0, s46
	s_nop 0
	global_load_lds_dwordx4 v[242:243], off
	s_waitcnt vmcnt(8)
	s_waitcnt lgkmcnt(0)
	s_barrier
; #define PG8_STAGE(bufoff, gbase, voff) do { _Pragma("unroll") for (int _i = 0; _i < 2; ++_i) \
;         __builtin_amdgcn_global_load_lds((const unsigned*)((const char*)(gbase) + (voff)[_i]), (PG8_LAS unsigned*)(lds + (bufoff) + ldsw + _i * 8192), 16, 0, 0); } while (0)
; #define PG8_LDA(dst, b, h) do { _Pragma("unroll") for (int m = 0; m < 4; ++m) _Pragma("unroll") for (int k = 0; k < 2; ++k) dst[m][k] = *(const PG8_LAS bf16x8*)(lds + PG8_SA(b, h) + aoff + m * 2048 + k * 1024); } while (0)
; #define PG8_LDB(dst, b, h) do { _Pragma("unroll") for (int n = 0; n < 2; ++n) _Pragma("unroll") for (int k = 0; k < 2; ++k) dst[n][k] = *(const PG8_LAS bf16x8*)(lds + PG8_SB(b, h) + boff + n * 2048 + k * 1024); } while (0)
; #define PG8_MMA(ai, bj, At, Bt) do { __builtin_amdgcn_s_setprio(1); _Pragma("unroll") for (int m = 0; m < 4; ++m) _Pragma("unroll") for (int n = 0; n < 2; ++n) _Pragma("unroll") for (int k = 0; k < 2; ++k) \
;         acc[ai][bj][m][n] = __builtin_amdgcn_mfma_f32_16x16x32_bf16(Bt[n][k], At[m][k], acc[ai][bj][m][n], 0, 0, 0); __builtin_amdgcn_s_setprio(0); } while (0)
; #define PG8_WAIT_V(n) asm volatile("s_waitcnt vmcnt(" #n ")" ::: "memory")
; #define PG8_WAIT_L(n) asm volatile("s_waitcnt lgkmcnt(" #n ")" ::: "memory")
; #define PG8_BAR __builtin_amdgcn_s_barrier()
; #define PG8_SCHED __builtin_amdgcn_sched_barrier(0)
; template <class Epi, class Sched, bool ALIGN_EPI = false, bool SP2 = false>
; __device__ __forceinline__ void gemm_phase(PG8_LAS unsigned char* lds, const Gemm g, const Sched& S, const Epi& E, int tid_in) {
;     ...
;             PG8_WAIT_V(8); PG8_WAIT_L(0); PG8_BAR; PG8_MMA(1, 0, At, B0); PG8_MMA(1, 1, At, B1); PG8_BAR; PG8_SCHED;
;             PG8_LDB(B0, 1, 0); PG8_LDB(B1, 1, 1); PG8_SCHED; PG8_LDA(At, 1, 0); PG8_STAGE(PG8_SA(0, 1), a2 + hstep, voffA);
;             PG8_WAIT_V(8); PG8_WAIT_L(0); PG8_BAR; PG8_MMA(0, 0, At, B0); PG8_MMA(0, 1, At, B1); PG8_BAR; PG8_SCHED;
;             PG8_LDA(At, 1, 1); PG8_STAGE(PG8_SB(1, 0), b3, voffB); PG8_STAGE(PG8_SB(1, 1), b3 + hstep, voffB); PG8_STAGE(PG8_SA(1, 0), a3, voffA);
	s_waitcnt lgkmcnt(0)
	v_mfma_f32_16x16x32_bf16 v[60:63], v[140:143], v[194:197], 0
	v_mfma_f32_16x16x32_bf16 v[56:59], v[170:173], v[194:197], 0
	v_mfma_f32_16x16x32_bf16 v[44:47], v[140:143], v[202:205], 0
	v_mfma_f32_16x16x32_bf16 v[40:43], v[170:173], v[202:205], 0
	v_mfma_f32_16x16x32_bf16 v[28:31], v[140:143], v[210:213], 0
	v_mfma_f32_16x16x32_bf16 v[24:27], v[170:173], v[210:213], 0
	v_mfma_f32_16x16x32_bf16 v[12:15], v[140:143], v[218:221], 0
	v_mfma_f32_16x16x32_bf16 v[8:11], v[170:173], v[218:221], 0
	v_mfma_f32_16x16x32_bf16 v[60:63], v[166:169], v[198:201], v[60:63]
	v_mfma_f32_16x16x32_bf16 v[56:59], v[174:177], v[198:201], v[56:59]
	v_mfma_f32_16x16x32_bf16 v[44:47], v[166:169], v[206:209], v[44:47]
	v_mfma_f32_16x16x32_bf16 v[40:43], v[174:177], v[206:209], v[40:43]
	v_mfma_f32_16x16x32_bf16 v[28:31], v[166:169], v[214:217], v[28:31]
	v_mfma_f32_16x16x32_bf16 v[24:27], v[174:177], v[214:217], v[24:27]
	v_mfma_f32_16x16x32_bf16 v[12:15], v[166:169], v[222:225], v[12:15]
	v_mfma_f32_16x16x32_bf16 v[8:11], v[174:177], v[222:225], v[8:11]
	v_mfma_f32_16x16x32_bf16 v[52:55], v[178:181], v[194:197], 0
	v_mfma_f32_16x16x32_bf16 v[48:51], v[186:189], v[194:197], 0
	v_mfma_f32_16x16x32_bf16 v[36:39], v[178:181], v[202:205], 0
	v_mfma_f32_16x16x32_bf16 v[32:35], v[186:189], v[202:205], 0
	v_mfma_f32_16x16x32_bf16 v[20:23], v[178:181], v[210:213], 0
	v_mfma_f32_16x16x32_bf16 v[16:19], v[186:189], v[210:213], 0
	v_mfma_f32_16x16x32_bf16 v[4:7], v[178:181], v[218:221], 0
	v_mfma_f32_16x16x32_bf16 v[0:3], v[186:189], v[218:221], 0
	v_mfma_f32_16x16x32_bf16 v[52:55], v[182:185], v[198:201], v[52:55]
	v_mfma_f32_16x16x32_bf16 v[48:51], v[190:193], v[198:201], v[48:51]
	v_mfma_f32_16x16x32_bf16 v[36:39], v[182:185], v[206:209], v[36:39]
	v_mfma_f32_16x16x32_bf16 v[32:35], v[190:193], v[206:209], v[32:35]
	v_mfma_f32_16x16x32_bf16 v[20:23], v[182:185], v[214:217], v[20:23]
	v_mfma_f32_16x16x32_bf16 v[16:19], v[190:193], v[214:217], v[16:19]
	v_mfma_f32_16x16x32_bf16 v[4:7], v[182:185], v[222:225], v[4:7]
	v_mfma_f32_16x16x32_bf16 v[0:3], v[190:193], v[222:225], v[0:3]
	s_barrier
	s_add_i32 s37, 0, 0x18000
	v_add_u32_e32 v146, s37, v151
	s_add_i32 s88, 0, 0x1c000
	ds_read_b128 v[140:143], v146
	ds_read_b128 v[166:169], v146 offset:1024
	ds_read_b128 v[170:173], v146 offset:2048
	ds_read_b128 v[174:177], v146 offset:3072
	v_add_u32_e32 v146, s88, v151
	ds_read_b128 v[178:181], v146
	ds_read_b128 v[182:185], v146 offset:1024
	ds_read_b128 v[186:189], v146 offset:2048
	ds_read_b128 v[190:193], v146 offset:3072
	s_add_u32 s4, s4, s8
	s_addc_u32 s5, s5, s9
	s_mov_b32 m0, s47
	v_lshl_add_u64 v[244:245], s[4:5], 0, v[132:133]
	ds_read_b128 v[194:197], v161 offset:32768
	ds_read_b128 v[198:201], v161 offset:33792
	ds_read_b128 v[202:205], v161 offset:34816
	ds_read_b128 v[206:209], v161 offset:35840
	ds_read_b128 v[210:213], v161 offset:36864
	ds_read_b128 v[214:217], v161 offset:37888
	ds_read_b128 v[218:221], v161 offset:38912
	ds_read_b128 v[222:225], v161 offset:39936
	global_load_lds_dwordx4 v[244:245], off
	v_lshl_add_u64 v[244:245], s[4:5], 0, v[130:131]
	s_mov_b32 m0, s52
	s_nop 0
	global_load_lds_dwordx4 v[244:245], off
	s_waitcnt vmcnt(8)
	s_waitcnt lgkmcnt(0)
	s_barrier
	s_waitcnt lgkmcnt(0)
	v_mfma_f32_16x16x32_bf16 v[124:127], v[140:143], v[194:197], v[124:127]
	v_mfma_f32_16x16x32_bf16 v[120:123], v[170:173], v[194:197], v[120:123]
	v_mfma_f32_16x16x32_bf16 v[108:111], v[140:143], v[202:205], v[108:111]
	v_mfma_f32_16x16x32_bf16 v[104:107], v[170:173], v[202:205], v[104:107]
	v_mfma_f32_16x16x32_bf16 v[92:95], v[140:143], v[210:213], v[92:95]
	v_mfma_f32_16x16x32_bf16 v[88:91], v[170:173], v[210:213], v[88:91]
	v_mfma_f32_16x16x32_bf16 v[76:79], v[140:143], v[218:221], v[76:79]
	v_mfma_f32_16x16x32_bf16 v[72:75], v[170:173], v[218:221], v[72:75]
	v_mfma_f32_16x16x32_bf16 v[124:127], v[166:169], v[198:201], v[124:127]
	v_mfma_f32_16x16x32_bf16 v[120:123], v[174:177], v[198:201], v[120:123]
	v_mfma_f32_16x16x32_bf16 v[108:111], v[166:169], v[206:209], v[108:111]
	v_mfma_f32_16x16x32_bf16 v[104:107], v[174:177], v[206:209], v[104:107]
	v_mfma_f32_16x16x32_bf16 v[92:95], v[166:169], v[214:217], v[92:95]
	v_mfma_f32_16x16x32_bf16 v[88:91], v[174:177], v[214:217], v[88:91]
	v_mfma_f32_16x16x32_bf16 v[76:79], v[166:169], v[222:225], v[76:79]
	v_mfma_f32_16x16x32_bf16 v[72:75], v[174:177], v[222:225], v[72:75]
	v_mfma_f32_16x16x32_bf16 v[116:119], v[178:181], v[194:197], v[116:119]
	v_mfma_f32_16x16x32_bf16 v[112:115], v[186:189], v[194:197], v[112:115]
	v_mfma_f32_16x16x32_bf16 v[100:103], v[178:181], v[202:205], v[100:103]
	v_mfma_f32_16x16x32_bf16 v[96:99], v[186:189], v[202:205], v[96:99]
	v_mfma_f32_16x16x32_bf16 v[84:87], v[178:181], v[210:213], v[84:87]
	v_mfma_f32_16x16x32_bf16 v[80:83], v[186:189], v[210:213], v[80:83]
	v_mfma_f32_16x16x32_bf16 v[68:71], v[178:181], v[218:221], v[68:71]
	v_mfma_f32_16x16x32_bf16 v[64:67], v[186:189], v[218:221], v[64:67]
	v_mfma_f32_16x16x32_bf16 v[116:119], v[182:185], v[198:201], v[116:119]
	v_mfma_f32_16x16x32_bf16 v[112:115], v[190:193], v[198:201], v[112:115]
	v_mfma_f32_16x16x32_bf16 v[100:103], v[182:185], v[206:209], v[100:103]
	v_mfma_f32_16x16x32_bf16 v[96:99], v[190:193], v[206:209], v[96:99]
	v_mfma_f32_16x16x32_bf16 v[84:87], v[182:185], v[214:217], v[84:87]
	v_mfma_f32_16x16x32_bf16 v[80:83], v[190:193], v[214:217], v[80:83]
	v_mfma_f32_16x16x32_bf16 v[68:71], v[182:185], v[222:225], v[68:71]
	v_mfma_f32_16x16x32_bf16 v[64:67], v[190:193], v[222:225], v[64:67]
	s_barrier
; #define PG8_STAGE(bufoff, gbase, voff) do { _Pragma("unroll") for (int _i = 0; _i < 2; ++_i) \
;         __builtin_amdgcn_global_load_lds((const unsigned*)((const char*)(gbase) + (voff)[_i]), (PG8_LAS unsigned*)(lds + (bufoff) + ldsw + _i * 8192), 16, 0, 0); } while (0)
; #define PG8_LDA(dst, b, h) do { _Pragma("unroll") for (int m = 0; m < 4; ++m) _Pragma("unroll") for (int k = 0; k < 2; ++k) dst[m][k] = *(const PG8_LAS bf16x8*)(lds + PG8_SA(b, h) + aoff + m * 2048 + k * 1024); } while (0)
; #define PG8_MMA(ai, bj, At, Bt) do { __builtin_amdgcn_s_setprio(1); _Pragma("unroll") for (int m = 0; m < 4; ++m) _Pragma("unroll") for (int n = 0; n < 2; ++n) _Pragma("unroll") for (int k = 0; k < 2; ++k) \
;         acc[ai][bj][m][n] = __builtin_amdgcn_mfma_f32_16x16x32_bf16(Bt[n][k], At[m][k], acc[ai][bj][m][n], 0, 0, 0); __builtin_amdgcn_s_setprio(0); } while (0)
; #define PG8_WAIT_V(n) asm volatile("s_waitcnt vmcnt(" #n ")" ::: "memory")
; #define PG8_WAIT_L(n) asm volatile("s_waitcnt lgkmcnt(" #n ")" ::: "memory")
; #define PG8_BAR __builtin_amdgcn_s_barrier()
; #define PG8_SCHED __builtin_amdgcn_sched_barrier(0)
; template <class Epi, class Sched, bool ALIGN_EPI = false, bool SP2 = false>
; __device__ __forceinline__ void gemm_phase(PG8_LAS unsigned char* lds, const Gemm g, const Sched& S, const Epi& E, int tid_in) {
;     ...
;         for (int t = 0; t < nt; t += 2) {
;     ...
;             PG8_WAIT_V(8); PG8_WAIT_L(0); PG8_BAR; PG8_MMA(0, 0, At, B0); PG8_MMA(0, 1, At, B1); PG8_BAR; PG8_SCHED;
;             PG8_LDA(At, 1, 1); PG8_STAGE(PG8_SB(1, 0), b3, voffB); PG8_STAGE(PG8_SB(1, 1), b3 + hstep, voffB); PG8_STAGE(PG8_SA(1, 0), a3, voffA);
;             PG8_WAIT_V(8); PG8_WAIT_L(0); PG8_BAR; PG8_MMA(1, 0, At, B0); PG8_MMA(1, 1, At, B1); PG8_BAR; PG8_SCHED;
	s_add_i32 s4, s37, s42
	v_lshl_add_u64 v[144:145], v[144:145], 0, s[64:65]
	s_mov_b32 m0, s4
	ds_read_b128 v[194:197], v161 offset:49152
	ds_read_b128 v[198:201], v161 offset:50176
	ds_read_b128 v[202:205], v161 offset:51200
	ds_read_b128 v[206:209], v161 offset:52224
	ds_read_b128 v[210:213], v161 offset:53248
	ds_read_b128 v[214:217], v161 offset:54272
	ds_read_b128 v[218:221], v161 offset:55296
	ds_read_b128 v[222:225], v161 offset:56320
	global_load_lds_dwordx4 v[144:145], off
	v_lshl_add_u64 v[144:145], v[226:227], 0, s[64:65]
	s_add_i32 m0, s4, 0x2000
	s_add_i32 s4, s88, s42
	global_load_lds_dwordx4 v[144:145], off
	v_lshl_add_u64 v[144:145], v[228:229], 0, s[64:65]
	s_mov_b32 m0, s4
	s_nop 0
	global_load_lds_dwordx4 v[144:145], off
	v_lshl_add_u64 v[144:145], v[238:239], 0, s[64:65]
	s_add_i32 m0, s4, 0x2000
	s_nop 0
	global_load_lds_dwordx4 v[144:145], off
	v_lshl_add_u64 v[144:145], v[240:241], 0, s[64:65]
	s_mov_b32 m0, s34
	s_nop 0
	global_load_lds_dwordx4 v[144:145], off
	v_lshl_add_u64 v[144:145], v[242:243], 0, s[64:65]
	s_mov_b32 m0, s35
	s_nop 0
	global_load_lds_dwordx4 v[144:145], off
	s_waitcnt vmcnt(8)
	s_waitcnt lgkmcnt(0)
	s_barrier
	s_waitcnt lgkmcnt(0)
	v_mfma_f32_16x16x32_bf16 v[60:63], v[140:143], v[194:197], v[60:63]
	v_mfma_f32_16x16x32_bf16 v[56:59], v[170:173], v[194:197], v[56:59]
	v_mfma_f32_16x16x32_bf16 v[44:47], v[140:143], v[202:205], v[44:47]
	v_mfma_f32_16x16x32_bf16 v[40:43], v[170:173], v[202:205], v[40:43]
	v_mfma_f32_16x16x32_bf16 v[28:31], v[140:143], v[210:213], v[28:31]
	v_mfma_f32_16x16x32_bf16 v[24:27], v[170:173], v[210:213], v[24:27]
	v_mfma_f32_16x16x32_bf16 v[12:15], v[140:143], v[218:221], v[12:15]
	v_mfma_f32_16x16x32_bf16 v[8:11], v[170:173], v[218:221], v[8:11]
	v_mfma_f32_16x16x32_bf16 v[60:63], v[166:169], v[198:201], v[60:63]
	v_mfma_f32_16x16x32_bf16 v[56:59], v[174:177], v[198:201], v[56:59]
	v_mfma_f32_16x16x32_bf16 v[44:47], v[166:169], v[206:209], v[44:47]
	v_mfma_f32_16x16x32_bf16 v[40:43], v[174:177], v[206:209], v[40:43]
	v_mfma_f32_16x16x32_bf16 v[28:31], v[166:169], v[214:217], v[28:31]
	v_mfma_f32_16x16x32_bf16 v[24:27], v[174:177], v[214:217], v[24:27]
	v_mfma_f32_16x16x32_bf16 v[12:15], v[166:169], v[222:225], v[12:15]
	v_mfma_f32_16x16x32_bf16 v[8:11], v[174:177], v[222:225], v[8:11]
	v_mfma_f32_16x16x32_bf16 v[52:55], v[178:181], v[194:197], v[52:55]
	v_mfma_f32_16x16x32_bf16 v[48:51], v[186:189], v[194:197], v[48:51]
	v_mfma_f32_16x16x32_bf16 v[36:39], v[178:181], v[202:205], v[36:39]
	v_mfma_f32_16x16x32_bf16 v[32:35], v[186:189], v[202:205], v[32:35]
	v_mfma_f32_16x16x32_bf16 v[20:23], v[178:181], v[210:213], v[20:23]
	v_mfma_f32_16x16x32_bf16 v[16:19], v[186:189], v[210:213], v[16:19]
	v_mfma_f32_16x16x32_bf16 v[4:7], v[178:181], v[218:221], v[4:7]
	v_mfma_f32_16x16x32_bf16 v[0:3], v[186:189], v[218:221], v[0:3]
	v_mfma_f32_16x16x32_bf16 v[52:55], v[182:185], v[198:201], v[52:55]
	v_mfma_f32_16x16x32_bf16 v[48:51], v[190:193], v[198:201], v[48:51]
	s_add_u32 s0, s0, 0x100
	v_mfma_f32_16x16x32_bf16 v[36:39], v[182:185], v[206:209], v[36:39]
	s_addc_u32 s1, s1, 0
	v_mfma_f32_16x16x32_bf16 v[32:35], v[190:193], v[206:209], v[32:35]
	s_add_u32 s22, s22, 0x100
	v_mfma_f32_16x16x32_bf16 v[20:23], v[182:185], v[214:217], v[20:23]
	s_addc_u32 s23, s23, 0
	v_mfma_f32_16x16x32_bf16 v[16:19], v[190:193], v[214:217], v[16:19]
	s_cmp_ge_i32 s36, s55
	v_mfma_f32_16x16x32_bf16 v[4:7], v[182:185], v[222:225], v[4:7]
	s_mov_b32 s4, s36
	v_mfma_f32_16x16x32_bf16 v[0:3], v[190:193], v[222:225], v[0:3]
	s_barrier
	s_cbranch_scc0 .LBB0_151
	s_branch .Lpeel_exit_g1
.LBB0_151:
	s_add_i32 s36, s4, 2
	s_add_u32 s37, s0, 0x80
	s_addc_u32 s5, s1, 0
	s_add_i32 s90, 0, 0x10000
	s_cmp_eq_u32 s57, s4
	s_cselect_b32 s5, s39, s5
	s_cselect_b32 s4, s38, s37
	v_add_u32_e32 v144, s90, v151
	s_cselect_b32 s89, s45, s23
	s_cselect_b32 s88, s44, s22
	s_add_i32 s37, 0, 0x14000
	ds_read_b128 v[140:143], v144
	ds_read_b128 v[166:169], v144 offset:1024
	ds_read_b128 v[170:173], v144 offset:2048
	ds_read_b128 v[174:177], v144 offset:3072
	v_add_u32_e32 v144, s37, v151
	ds_read_b128 v[178:181], v144
	ds_read_b128 v[182:185], v144 offset:1024
	ds_read_b128 v[186:189], v144 offset:2048
	ds_read_b128 v[190:193], v144 offset:3072
	v_lshl_add_u64 v[144:145], s[0:1], 0, v[136:137]
	s_add_i32 m0, s43, 0xc000
	ds_read_b128 v[194:197], v161
	ds_read_b128 v[198:201], v161 offset:1024
	ds_read_b128 v[202:205], v161 offset:2048
	ds_read_b128 v[206:209], v161 offset:3072
	ds_read_b128 v[210:213], v161 offset:4096
	ds_read_b128 v[214:217], v161 offset:5120
	ds_read_b128 v[218:221], v161 offset:6144
	ds_read_b128 v[222:225], v161 offset:7168
	global_load_lds_dwordx4 v[144:145], off
	v_lshl_add_u64 v[144:145], s[0:1], 0, v[138:139]
	s_add_i32 m0, s43, 0xe000
	s_nop 0
	global_load_lds_dwordx4 v[144:145], off
	s_waitcnt vmcnt(8)
	s_waitcnt lgkmcnt(0)
	s_barrier
; #define PG8_STAGE(bufoff, gbase, voff) do { _Pragma("unroll") for (int _i = 0; _i < 2; ++_i) \
;         __builtin_amdgcn_global_load_lds((const unsigned*)((const char*)(gbase) + (voff)[_i]), (PG8_LAS unsigned*)(lds + (bufoff) + ldsw + _i * 8192), 16, 0, 0); } while (0)
; #define PG8_LDA(dst, b, h) do { _Pragma("unroll") for (int m = 0; m < 4; ++m) _Pragma("unroll") for (int k = 0; k < 2; ++k) dst[m][k] = *(const PG8_LAS bf16x8*)(lds + PG8_SA(b, h) + aoff + m * 2048 + k * 1024); } while (0)
; #define PG8_LDB(dst, b, h) do { _Pragma("unroll") for (int n = 0; n < 2; ++n) _Pragma("unroll") for (int k = 0; k < 2; ++k) dst[n][k] = *(const PG8_LAS bf16x8*)(lds + PG8_SB(b, h) + boff + n * 2048 + k * 1024); } while (0)
; #define PG8_MMA(ai, bj, At, Bt) do { __builtin_amdgcn_s_setprio(1); _Pragma("unroll") for (int m = 0; m < 4; ++m) _Pragma("unroll") for (int n = 0; n < 2; ++n) _Pragma("unroll") for (int k = 0; k < 2; ++k) \
;         acc[ai][bj][m][n] = __builtin_amdgcn_mfma_f32_16x16x32_bf16(Bt[n][k], At[m][k], acc[ai][bj][m][n], 0, 0, 0); __builtin_amdgcn_s_setprio(0); } while (0)
; #define PG8_WAIT_V(n) asm volatile("s_waitcnt vmcnt(" #n ")" ::: "memory")
; #define PG8_WAIT_L(n) asm volatile("s_waitcnt lgkmcnt(" #n ")" ::: "memory")
; #define PG8_BAR __builtin_amdgcn_s_barrier()
; #define PG8_SCHED __builtin_amdgcn_sched_barrier(0)
; template <class Epi, class Sched, bool ALIGN_EPI = false, bool SP2 = false>
; __device__ __forceinline__ void gemm_phase(PG8_LAS unsigned char* lds, const Gemm g, const Sched& S, const Epi& E, int tid_in) {
;     ...
;             PG8_LDB(B0, 0, 0); PG8_LDB(B1, 0, 1); PG8_SCHED; PG8_LDA(At, 0, 0); PG8_STAGE(PG8_SA(1, 1), a1 + hstep, voffA);
;             PG8_WAIT_V(8); PG8_WAIT_L(0); PG8_BAR; PG8_MMA(0, 0, At, B0); PG8_MMA(0, 1, At, B1); PG8_BAR; PG8_SCHED;
;             PG8_LDA(At, 0, 1); PG8_STAGE(PG8_SB(0, 0), b2, voffB); PG8_STAGE(PG8_SB(0, 1), b2 + hstep, voffB); PG8_STAGE(PG8_SA(0, 0), a2, voffA);
;             PG8_WAIT_V(8); PG8_WAIT_L(0); PG8_BAR; PG8_MMA(1, 0, At, B0); PG8_MMA(1, 1, At, B1); PG8_BAR; PG8_SCHED;
;             PG8_LDB(B0, 1, 0); PG8_LDB(B1, 1, 1); PG8_SCHED; PG8_LDA(At, 1, 0); PG8_STAGE(PG8_SA(0, 1), a2 + hstep, voffA);
;             PG8_WAIT_V(8); PG8_WAIT_L(0); PG8_BAR; PG8_MMA(0, 0, At, B0); PG8_MMA(0, 1, At, B1); PG8_BAR; PG8_SCHED;
	s_waitcnt lgkmcnt(0)
	v_mfma_f32_16x16x32_bf16 v[124:127], v[140:143], v[194:197], v[124:127]
	v_mfma_f32_16x16x32_bf16 v[120:123], v[170:173], v[194:197], v[120:123]
	v_mfma_f32_16x16x32_bf16 v[108:111], v[140:143], v[202:205], v[108:111]
	v_mfma_f32_16x16x32_bf16 v[104:107], v[170:173], v[202:205], v[104:107]
	v_mfma_f32_16x16x32_bf16 v[92:95], v[140:143], v[210:213], v[92:95]
	v_mfma_f32_16x16x32_bf16 v[88:91], v[170:173], v[210:213], v[88:91]
	v_mfma_f32_16x16x32_bf16 v[76:79], v[140:143], v[218:221], v[76:79]
	v_mfma_f32_16x16x32_bf16 v[72:75], v[170:173], v[218:221], v[72:75]
	v_mfma_f32_16x16x32_bf16 v[124:127], v[166:169], v[198:201], v[124:127]
	v_mfma_f32_16x16x32_bf16 v[120:123], v[174:177], v[198:201], v[120:123]
	v_mfma_f32_16x16x32_bf16 v[108:111], v[166:169], v[206:209], v[108:111]
	v_mfma_f32_16x16x32_bf16 v[104:107], v[174:177], v[206:209], v[104:107]
	v_mfma_f32_16x16x32_bf16 v[92:95], v[166:169], v[214:217], v[92:95]
	v_mfma_f32_16x16x32_bf16 v[88:91], v[174:177], v[214:217], v[88:91]
	v_mfma_f32_16x16x32_bf16 v[76:79], v[166:169], v[222:225], v[76:79]
	v_mfma_f32_16x16x32_bf16 v[72:75], v[174:177], v[222:225], v[72:75]
	v_mfma_f32_16x16x32_bf16 v[116:119], v[178:181], v[194:197], v[116:119]
	v_mfma_f32_16x16x32_bf16 v[112:115], v[186:189], v[194:197], v[112:115]
	v_mfma_f32_16x16x32_bf16 v[100:103], v[178:181], v[202:205], v[100:103]
	v_mfma_f32_16x16x32_bf16 v[96:99], v[186:189], v[202:205], v[96:99]
	v_mfma_f32_16x16x32_bf16 v[84:87], v[178:181], v[210:213], v[84:87]
	v_mfma_f32_16x16x32_bf16 v[80:83], v[186:189], v[210:213], v[80:83]
	v_mfma_f32_16x16x32_bf16 v[68:71], v[178:181], v[218:221], v[68:71]
	v_mfma_f32_16x16x32_bf16 v[64:67], v[186:189], v[218:221], v[64:67]
	v_mfma_f32_16x16x32_bf16 v[116:119], v[182:185], v[198:201], v[116:119]
	v_mfma_f32_16x16x32_bf16 v[112:115], v[190:193], v[198:201], v[112:115]
	v_mfma_f32_16x16x32_bf16 v[100:103], v[182:185], v[206:209], v[100:103]
	v_mfma_f32_16x16x32_bf16 v[96:99], v[190:193], v[206:209], v[96:99]
	v_mfma_f32_16x16x32_bf16 v[84:87], v[182:185], v[214:217], v[84:87]
	v_mfma_f32_16x16x32_bf16 v[80:83], v[190:193], v[214:217], v[80:83]
	v_mfma_f32_16x16x32_bf16 v[68:71], v[182:185], v[222:225], v[68:71]
	v_mfma_f32_16x16x32_bf16 v[64:67], v[190:193], v[222:225], v[64:67]
	s_barrier
	s_add_i32 s90, s90, s42
	v_lshl_add_u64 v[144:145], s[88:89], 0, v[156:157]
	s_mov_b32 m0, s90
	ds_read_b128 v[194:197], v161 offset:16384
	ds_read_b128 v[198:201], v161 offset:17408
	ds_read_b128 v[202:205], v161 offset:18432
	ds_read_b128 v[206:209], v161 offset:19456
	ds_read_b128 v[210:213], v161 offset:20480
	ds_read_b128 v[214:217], v161 offset:21504
	ds_read_b128 v[218:221], v161 offset:22528
	ds_read_b128 v[222:225], v161 offset:23552
	global_load_lds_dwordx4 v[144:145], off
	s_add_i32 m0, s90, 0x2000
	v_lshl_add_u64 v[226:227], s[88:89], 0, v[128:129]
	s_add_u32 s88, s88, s8
	s_addc_u32 s89, s89, s9
	s_add_i32 s37, s37, s42
	global_load_lds_dwordx4 v[226:227], off
	v_lshl_add_u64 v[228:229], s[88:89], 0, v[156:157]
	s_mov_b32 m0, s37
	v_lshl_add_u64 v[238:239], s[88:89], 0, v[128:129]
	global_load_lds_dwordx4 v[228:229], off
	s_add_i32 m0, s37, 0x2000
	v_lshl_add_u64 v[240:241], s[4:5], 0, v[132:133]
	global_load_lds_dwordx4 v[238:239], off
	s_mov_b32 m0, s43
	v_lshl_add_u64 v[242:243], s[4:5], 0, v[130:131]
	global_load_lds_dwordx4 v[240:241], off
	s_mov_b32 m0, s46
	s_nop 0
	global_load_lds_dwordx4 v[242:243], off
	s_waitcnt vmcnt(8)
	s_waitcnt lgkmcnt(0)
	s_barrier
	s_waitcnt lgkmcnt(0)
	v_mfma_f32_16x16x32_bf16 v[60:63], v[140:143], v[194:197], v[60:63]
	v_mfma_f32_16x16x32_bf16 v[56:59], v[170:173], v[194:197], v[56:59]
	v_mfma_f32_16x16x32_bf16 v[44:47], v[140:143], v[202:205], v[44:47]
	v_mfma_f32_16x16x32_bf16 v[40:43], v[170:173], v[202:205], v[40:43]
	v_mfma_f32_16x16x32_bf16 v[28:31], v[140:143], v[210:213], v[28:31]
	v_mfma_f32_16x16x32_bf16 v[24:27], v[170:173], v[210:213], v[24:27]
	v_mfma_f32_16x16x32_bf16 v[12:15], v[140:143], v[218:221], v[12:15]
	v_mfma_f32_16x16x32_bf16 v[8:11], v[170:173], v[218:221], v[8:11]
	v_mfma_f32_16x16x32_bf16 v[60:63], v[166:169], v[198:201], v[60:63]
	v_mfma_f32_16x16x32_bf16 v[56:59], v[174:177], v[198:201], v[56:59]
	v_mfma_f32_16x16x32_bf16 v[44:47], v[166:169], v[206:209], v[44:47]
	v_mfma_f32_16x16x32_bf16 v[40:43], v[174:177], v[206:209], v[40:43]
	v_mfma_f32_16x16x32_bf16 v[28:31], v[166:169], v[214:217], v[28:31]
	v_mfma_f32_16x16x32_bf16 v[24:27], v[174:177], v[214:217], v[24:27]
	v_mfma_f32_16x16x32_bf16 v[12:15], v[166:169], v[222:225], v[12:15]
	v_mfma_f32_16x16x32_bf16 v[8:11], v[174:177], v[222:225], v[8:11]
	v_mfma_f32_16x16x32_bf16 v[52:55], v[178:181], v[194:197], v[52:55]
	v_mfma_f32_16x16x32_bf16 v[48:51], v[186:189], v[194:197], v[48:51]
	v_mfma_f32_16x16x32_bf16 v[36:39], v[178:181], v[202:205], v[36:39]
	v_mfma_f32_16x16x32_bf16 v[32:35], v[186:189], v[202:205], v[32:35]
	v_mfma_f32_16x16x32_bf16 v[20:23], v[178:181], v[210:213], v[20:23]
	v_mfma_f32_16x16x32_bf16 v[16:19], v[186:189], v[210:213], v[16:19]
	v_mfma_f32_16x16x32_bf16 v[4:7], v[178:181], v[218:221], v[4:7]
	v_mfma_f32_16x16x32_bf16 v[0:3], v[186:189], v[218:221], v[0:3]
	v_mfma_f32_16x16x32_bf16 v[52:55], v[182:185], v[198:201], v[52:55]
	v_mfma_f32_16x16x32_bf16 v[48:51], v[190:193], v[198:201], v[48:51]
	v_mfma_f32_16x16x32_bf16 v[36:39], v[182:185], v[206:209], v[36:39]
	v_mfma_f32_16x16x32_bf16 v[32:35], v[190:193], v[206:209], v[32:35]
	v_mfma_f32_16x16x32_bf16 v[20:23], v[182:185], v[214:217], v[20:23]
	v_mfma_f32_16x16x32_bf16 v[16:19], v[190:193], v[214:217], v[16:19]
	v_mfma_f32_16x16x32_bf16 v[4:7], v[182:185], v[222:225], v[4:7]
	v_mfma_f32_16x16x32_bf16 v[0:3], v[190:193], v[222:225], v[0:3]
	s_barrier
; #define PG8_STAGE(bufoff, gbase, voff) do { _Pragma("unroll") for (int _i = 0; _i < 2; ++_i) \
;         __builtin_amdgcn_global_load_lds((const unsigned*)((const char*)(gbase) + (voff)[_i]), (PG8_LAS unsigned*)(lds + (bufoff) + ldsw + _i * 8192), 16, 0, 0); } while (0)
; #define PG8_LDA(dst, b, h) do { _Pragma("unroll") for (int m = 0; m < 4; ++m) _Pragma("unroll") for (int k = 0; k < 2; ++k) dst[m][k] = *(const PG8_LAS bf16x8*)(lds + PG8_SA(b, h) + aoff + m * 2048 + k * 1024); } while (0)
; #define PG8_LDB(dst, b, h) do { _Pragma("unroll") for (int n = 0; n < 2; ++n) _Pragma("unroll") for (int k = 0; k < 2; ++k) dst[n][k] = *(const PG8_LAS bf16x8*)(lds + PG8_SB(b, h) + boff + n * 2048 + k * 1024); } while (0)
; #define PG8_MMA(ai, bj, At, Bt) do { __builtin_amdgcn_s_setprio(1); _Pragma("unroll") for (int m = 0; m < 4; ++m) _Pragma("unroll") for (int n = 0; n < 2; ++n) _Pragma("unroll") for (int k = 0; k < 2; ++k) \
;         acc[ai][bj][m][n] = __builtin_amdgcn_mfma_f32_16x16x32_bf16(Bt[n][k], At[m][k], acc[ai][bj][m][n], 0, 0, 0); __builtin_amdgcn_s_setprio(0); } while (0)
; #define PG8_WAIT_V(n) asm volatile("s_waitcnt vmcnt(" #n ")" ::: "memory")
; #define PG8_WAIT_L(n) asm volatile("s_waitcnt lgkmcnt(" #n ")" ::: "memory")
; #define PG8_BAR __builtin_amdgcn_s_barrier()
; #define PG8_SCHED __builtin_amdgcn_sched_barrier(0)
; template <class Epi, class Sched, bool ALIGN_EPI = false, bool SP2 = false>
; __device__ __forceinline__ void gemm_phase(PG8_LAS unsigned char* lds, const Gemm g, const Sched& S, const Epi& E, int tid_in) {
;     ...
;             PG8_LDB(B0, 1, 0); PG8_LDB(B1, 1, 1); PG8_SCHED; PG8_LDA(At, 1, 0); PG8_STAGE(PG8_SA(0, 1), a2 + hstep, voffA);
;             PG8_WAIT_V(8); PG8_WAIT_L(0); PG8_BAR; PG8_MMA(0, 0, At, B0); PG8_MMA(0, 1, At, B1); PG8_BAR; PG8_SCHED;
;             PG8_LDA(At, 1, 1); PG8_STAGE(PG8_SB(1, 0), b3, voffB); PG8_STAGE(PG8_SB(1, 1), b3 + hstep, voffB); PG8_STAGE(PG8_SA(1, 0), a3, voffA);
;             PG8_WAIT_V(8); PG8_WAIT_L(0); PG8_BAR; PG8_MMA(1, 0, At, B0); PG8_MMA(1, 1, At, B1); PG8_BAR; PG8_SCHED;
	s_add_i32 s37, 0, 0x18000
	v_add_u32_e32 v146, s37, v151
	s_add_i32 s88, 0, 0x1c000
	ds_read_b128 v[140:143], v146
	ds_read_b128 v[166:169], v146 offset:1024
	ds_read_b128 v[170:173], v146 offset:2048
	ds_read_b128 v[174:177], v146 offset:3072
	v_add_u32_e32 v146, s88, v151
	ds_read_b128 v[178:181], v146
	ds_read_b128 v[182:185], v146 offset:1024
	ds_read_b128 v[186:189], v146 offset:2048
	ds_read_b128 v[190:193], v146 offset:3072
	s_add_u32 s4, s4, s8
	s_addc_u32 s5, s5, s9
	s_mov_b32 m0, s47
	v_lshl_add_u64 v[244:245], s[4:5], 0, v[132:133]
	ds_read_b128 v[194:197], v161 offset:32768
	ds_read_b128 v[198:201], v161 offset:33792
	ds_read_b128 v[202:205], v161 offset:34816
	ds_read_b128 v[206:209], v161 offset:35840
	ds_read_b128 v[210:213], v161 offset:36864
	ds_read_b128 v[214:217], v161 offset:37888
	ds_read_b128 v[218:221], v161 offset:38912
	ds_read_b128 v[222:225], v161 offset:39936
	global_load_lds_dwordx4 v[244:245], off
	v_lshl_add_u64 v[244:245], s[4:5], 0, v[130:131]
	s_mov_b32 m0, s52
	s_nop 0
	global_load_lds_dwordx4 v[244:245], off
	s_waitcnt vmcnt(8)
	s_waitcnt lgkmcnt(0)
	s_barrier
	s_waitcnt lgkmcnt(0)
	v_mfma_f32_16x16x32_bf16 v[124:127], v[140:143], v[194:197], v[124:127]
	v_mfma_f32_16x16x32_bf16 v[120:123], v[170:173], v[194:197], v[120:123]
	v_mfma_f32_16x16x32_bf16 v[108:111], v[140:143], v[202:205], v[108:111]
	v_mfma_f32_16x16x32_bf16 v[104:107], v[170:173], v[202:205], v[104:107]
	v_mfma_f32_16x16x32_bf16 v[92:95], v[140:143], v[210:213], v[92:95]
	v_mfma_f32_16x16x32_bf16 v[88:91], v[170:173], v[210:213], v[88:91]
	v_mfma_f32_16x16x32_bf16 v[76:79], v[140:143], v[218:221], v[76:79]
	v_mfma_f32_16x16x32_bf16 v[72:75], v[170:173], v[218:221], v[72:75]
	v_mfma_f32_16x16x32_bf16 v[124:127], v[166:169], v[198:201], v[124:127]
	v_mfma_f32_16x16x32_bf16 v[120:123], v[174:177], v[198:201], v[120:123]
	v_mfma_f32_16x16x32_bf16 v[108:111], v[166:169], v[206:209], v[108:111]
	v_mfma_f32_16x16x32_bf16 v[104:107], v[174:177], v[206:209], v[104:107]
	v_mfma_f32_16x16x32_bf16 v[92:95], v[166:169], v[214:217], v[92:95]
	v_mfma_f32_16x16x32_bf16 v[88:91], v[174:177], v[214:217], v[88:91]
	v_mfma_f32_16x16x32_bf16 v[76:79], v[166:169], v[222:225], v[76:79]
	v_mfma_f32_16x16x32_bf16 v[72:75], v[174:177], v[222:225], v[72:75]
	v_mfma_f32_16x16x32_bf16 v[116:119], v[178:181], v[194:197], v[116:119]
	v_mfma_f32_16x16x32_bf16 v[112:115], v[186:189], v[194:197], v[112:115]
	v_mfma_f32_16x16x32_bf16 v[100:103], v[178:181], v[202:205], v[100:103]
	v_mfma_f32_16x16x32_bf16 v[96:99], v[186:189], v[202:205], v[96:99]
	v_mfma_f32_16x16x32_bf16 v[84:87], v[178:181], v[210:213], v[84:87]
	v_mfma_f32_16x16x32_bf16 v[80:83], v[186:189], v[210:213], v[80:83]
	v_mfma_f32_16x16x32_bf16 v[68:71], v[178:181], v[218:221], v[68:71]
	v_mfma_f32_16x16x32_bf16 v[64:67], v[186:189], v[218:221], v[64:67]
	v_mfma_f32_16x16x32_bf16 v[116:119], v[182:185], v[198:201], v[116:119]
	v_mfma_f32_16x16x32_bf16 v[112:115], v[190:193], v[198:201], v[112:115]
	v_mfma_f32_16x16x32_bf16 v[100:103], v[182:185], v[206:209], v[100:103]
	v_mfma_f32_16x16x32_bf16 v[96:99], v[190:193], v[206:209], v[96:99]
	v_mfma_f32_16x16x32_bf16 v[84:87], v[182:185], v[214:217], v[84:87]
	v_mfma_f32_16x16x32_bf16 v[80:83], v[190:193], v[214:217], v[80:83]
	v_mfma_f32_16x16x32_bf16 v[68:71], v[182:185], v[222:225], v[68:71]
	v_mfma_f32_16x16x32_bf16 v[64:67], v[190:193], v[222:225], v[64:67]
	s_barrier
	s_add_i32 s4, s37, s42
	v_lshl_add_u64 v[144:145], v[144:145], 0, s[64:65]
	s_mov_b32 m0, s4
	ds_read_b128 v[194:197], v161 offset:49152
	ds_read_b128 v[198:201], v161 offset:50176
	ds_read_b128 v[202:205], v161 offset:51200
	ds_read_b128 v[206:209], v161 offset:52224
	ds_read_b128 v[210:213], v161 offset:53248
	ds_read_b128 v[214:217], v161 offset:54272
	ds_read_b128 v[218:221], v161 offset:55296
	ds_read_b128 v[222:225], v161 offset:56320
	global_load_lds_dwordx4 v[144:145], off
	v_lshl_add_u64 v[144:145], v[226:227], 0, s[64:65]
	s_add_i32 m0, s4, 0x2000
	s_add_i32 s4, s88, s42
	global_load_lds_dwordx4 v[144:145], off
	v_lshl_add_u64 v[144:145], v[228:229], 0, s[64:65]
	s_mov_b32 m0, s4
	s_nop 0
	global_load_lds_dwordx4 v[144:145], off
	v_lshl_add_u64 v[144:145], v[238:239], 0, s[64:65]
	s_add_i32 m0, s4, 0x2000
	s_nop 0
	global_load_lds_dwordx4 v[144:145], off
	v_lshl_add_u64 v[144:145], v[240:241], 0, s[64:65]
	s_mov_b32 m0, s34
	s_nop 0
	global_load_lds_dwordx4 v[144:145], off
	v_lshl_add_u64 v[144:145], v[242:243], 0, s[64:65]
	s_mov_b32 m0, s35
	s_nop 0
	global_load_lds_dwordx4 v[144:145], off
	s_waitcnt vmcnt(8)
	s_waitcnt lgkmcnt(0)
	s_barrier
	s_waitcnt lgkmcnt(0)
	v_mfma_f32_16x16x32_bf16 v[60:63], v[140:143], v[194:197], v[60:63]
	v_mfma_f32_16x16x32_bf16 v[56:59], v[170:173], v[194:197], v[56:59]
	v_mfma_f32_16x16x32_bf16 v[44:47], v[140:143], v[202:205], v[44:47]
	v_mfma_f32_16x16x32_bf16 v[40:43], v[170:173], v[202:205], v[40:43]
	v_mfma_f32_16x16x32_bf16 v[28:31], v[140:143], v[210:213], v[28:31]
	v_mfma_f32_16x16x32_bf16 v[24:27], v[170:173], v[210:213], v[24:27]
	v_mfma_f32_16x16x32_bf16 v[12:15], v[140:143], v[218:221], v[12:15]
	v_mfma_f32_16x16x32_bf16 v[8:11], v[170:173], v[218:221], v[8:11]
	v_mfma_f32_16x16x32_bf16 v[60:63], v[166:169], v[198:201], v[60:63]
	v_mfma_f32_16x16x32_bf16 v[56:59], v[174:177], v[198:201], v[56:59]
	v_mfma_f32_16x16x32_bf16 v[44:47], v[166:169], v[206:209], v[44:47]
	v_mfma_f32_16x16x32_bf16 v[40:43], v[174:177], v[206:209], v[40:43]
	v_mfma_f32_16x16x32_bf16 v[28:31], v[166:169], v[214:217], v[28:31]
	v_mfma_f32_16x16x32_bf16 v[24:27], v[174:177], v[214:217], v[24:27]
	v_mfma_f32_16x16x32_bf16 v[12:15], v[166:169], v[222:225], v[12:15]
	v_mfma_f32_16x16x32_bf16 v[8:11], v[174:177], v[222:225], v[8:11]
	v_mfma_f32_16x16x32_bf16 v[52:55], v[178:181], v[194:197], v[52:55]
	v_mfma_f32_16x16x32_bf16 v[48:51], v[186:189], v[194:197], v[48:51]
	v_mfma_f32_16x16x32_bf16 v[36:39], v[178:181], v[202:205], v[36:39]
	v_mfma_f32_16x16x32_bf16 v[32:35], v[186:189], v[202:205], v[32:35]
	v_mfma_f32_16x16x32_bf16 v[20:23], v[178:181], v[210:213], v[20:23]
	v_mfma_f32_16x16x32_bf16 v[16:19], v[186:189], v[210:213], v[16:19]
	v_mfma_f32_16x16x32_bf16 v[4:7], v[178:181], v[218:221], v[4:7]
	v_mfma_f32_16x16x32_bf16 v[0:3], v[186:189], v[218:221], v[0:3]
	v_mfma_f32_16x16x32_bf16 v[52:55], v[182:185], v[198:201], v[52:55]
	v_mfma_f32_16x16x32_bf16 v[48:51], v[190:193], v[198:201], v[48:51]
	s_add_u32 s0, s0, 0x100
	v_mfma_f32_16x16x32_bf16 v[36:39], v[182:185], v[206:209], v[36:39]
	s_addc_u32 s1, s1, 0
	v_mfma_f32_16x16x32_bf16 v[32:35], v[190:193], v[206:209], v[32:35]
	s_add_u32 s22, s22, 0x100
	v_mfma_f32_16x16x32_bf16 v[20:23], v[182:185], v[214:217], v[20:23]
	s_addc_u32 s23, s23, 0
	v_mfma_f32_16x16x32_bf16 v[16:19], v[190:193], v[214:217], v[16:19]
	s_cmp_ge_i32 s36, s55
	v_mfma_f32_16x16x32_bf16 v[4:7], v[182:185], v[222:225], v[4:7]
	s_mov_b32 s4, s36
	v_mfma_f32_16x16x32_bf16 v[0:3], v[190:193], v[222:225], v[0:3]
	s_barrier
	s_cbranch_scc0 .LBB0_151

; template <bool EDGE>
; __device__ __forceinline__ void mixer_c_item(const bf16_t* kp, const bf16_t* vp, int S, int P0, const LAS float* lut, LAS unsigned char* vimg, int lane,
;                                              const bf16x8 (&q)[3][2], f32x4 (&o)[3][4], float (&m)[3], float (&l)[3]) {
;     const int i16 = lane & 15;
;     const int klo_1 = max(i16 - 128, -P0), kspan_1 = min(i16 + 128, S - 1 - P0) - klo_1; const int klo_c[3] = {klo_1, klo_1, klo_1}, kspan_c[3] = {kspan_1, kspan_1, kspan_1}, ua_c[3] = {i16, i16, i16};
;     TileLd ta, tb; tile_load<EDGE>(ta, kp, vp, S, P0, 1, -128, lane);
; __device__ __forceinline__ void mixer_c(Frame& F, const Trunk& T, int layer) {
;     ...
;     for (int j = 0; j < per; ++j) {
;         int kvh, rest;
;         if (xmap) { kvh = j; rest = (F.bx & 7) * 256 + (F.bx >> 3) * NWAVES + F.wave; }
;         else { const int it = F.gw * per + j; if (it >= NIT) break; kvh = it / (MT / 16); rest = it % (MT / 16); }
;         const int b = rest / bps, P0 = (rest % bps) * 16;
;         const size_t rowb = (size_t)b * T.S; const int posq = P0 + i16;
;         const bf16_t* kp = proj + rowb * NIN + C_KC + kvh * 64; const bf16_t* vp = proj + rowb * NIN + C_VC + kvh * 64;
;         for (int i = lane; i < 771; i += 64) lut[i] = lutC[kvh * 771 + i];
;         asm volatile("s_waitcnt lgkmcnt(0)" ::: "memory");
;         bf16x8 q[3][2]; f32x4 o[3][4]; float m[3], l[3], snk[3];
; #pragma unroll
;         for (int g = 0; g < 3; ++g) { const bf16_t* qp = proj + (rowb + posq) * NIN + C_QC + (3 * kvh + g) * 64 + quad * 8; q[g][0] = *(const bf16x8*)qp; q[g][1] = *(const bf16x8*)(qp + 32);
;             o[g][0] = z4; o[g][1] = z4; o[g][2] = z4; o[g][3] = z4; snk[g] = ((const float*)(F.ws + WS_PAR))[32 + layer * 12 + 3 * kvh + g]; m[g] = snk[g]; l[g] = 0.f; }
;         if (P0 >= 128 && P0 + 160 <= T.S) mixer_c_item<false>(kp, vp, T.S, P0, lut, vimg, lane, q, o, m, l);
;         else mixer_c_item<true>(kp, vp, T.S, P0, lut, vimg, lane, q, o, m, l);
.LBB0_603:
	s_and_b64 vcc, exec, s[0:1]
	s_cbranch_vccz .LBB0_598
	s_mul_i32 s0, s46, 0x303
	v_add_u32_e32 v0, s0, v198
	v_ashrrev_i32_e32 v1, 31, v0
	v_lshl_add_u64 v[0:1], v[0:1], 2, s[92:93]
	s_mov_b64 s[0:1], 0
	v_or_b32_e32 v2, 0xffffffc0, v198
	v_mov_b32_e32 v3, v149
	global_load_dword v209, v[0:1], off
	global_load_dword v210, v[0:1], off offset:256
	global_load_dword v211, v[0:1], off offset:512
	global_load_dword v212, v[0:1], off offset:768
	global_load_dword v213, v[0:1], off offset:1024
	global_load_dword v214, v[0:1], off offset:1280
	global_load_dword v215, v[0:1], off offset:1536
	global_load_dword v216, v[0:1], off offset:1792
	global_load_dword v217, v[0:1], off offset:2048
	global_load_dword v218, v[0:1], off offset:2304
	global_load_dword v219, v[0:1], off offset:2560
	global_load_dword v220, v[0:1], off offset:2816
	v_cmp_gt_u32_e32 vcc, 3, v198
	s_and_saveexec_b64 s[0:1], vcc
	global_load_dword v221, v[0:1], off offset:3072
	s_waitcnt vmcnt(0)
	ds_write_b32 v3, v221 offset:3072
	s_mov_b64 exec, s[0:1]
	ds_write_b32 v3, v209
	ds_write_b32 v3, v210 offset:256
	ds_write_b32 v3, v211 offset:512
	ds_write_b32 v3, v212 offset:768
	ds_write_b32 v3, v213 offset:1024
	ds_write_b32 v3, v214 offset:1280
	ds_write_b32 v3, v215 offset:1536
	ds_write_b32 v3, v216 offset:1792
	ds_write_b32 v3, v217 offset:2048
	ds_write_b32 v3, v218 offset:2304
	ds_write_b32 v3, v219 offset:2560
	ds_write_b32 v3, v220 offset:2816
	s_abs_i32 s1, s47
	s_mul_hi_u32 s2, s1, s36
	s_mul_i32 s3, s2, s28
	s_sub_i32 s1, s1, s3
	s_ashr_i32 s0, s47, 31
	s_add_i32 s3, s2, 1
	s_sub_i32 s4, s1, s28
	s_cmp_ge_u32 s1, s28
	s_cselect_b32 s2, s3, s2
	s_cselect_b32 s1, s4, s1
	s_add_i32 s3, s2, 1
	s_cmp_ge_u32 s1, s28
	s_cselect_b32 s1, s3, s2
	s_xor_b32 s1, s1, s0
	s_sub_i32 s0, s1, s0
	s_mul_i32 s1, s0, s28
	s_sub_i32 s4, s47, s1
	s_ashr_i32 s1, s0, 31
	s_lshl_b64 s[0:1], s[0:1], s84
	s_mul_i32 s2, s1, 0x2800
	s_mul_hi_u32 s3, s0, 0x2800
	s_add_i32 s3, s3, s2
	s_mul_i32 s2, s0, 0x2800
	s_add_u32 s5, s88, s2
	s_addc_u32 s6, s89, s3
	s_lshl_b32 s2, s46, 6
	s_ashr_i32 s3, s2, 31
	s_lshl_b32 s52, s4, 4
	v_or_b32_e32 v0, s52, v199
	s_lshl_b64 s[2:3], s[2:3], 1
	s_add_u32 s2, s5, s2
	v_ashrrev_i32_e32 v1, 31, v0
	s_addc_u32 s3, s6, s3
	v_lshl_add_u64 v[140:141], s[0:1], 0, v[0:1]
	v_mov_b64_e32 v[0:1], s[88:89]
	s_add_u32 s44, s2, 0x2400
	v_mad_u64_u32 v[0:1], s[0:1], v140, s97, v[0:1]
	s_addc_u32 s45, s3, 0
	v_mad_i32_i24 v1, v141, s97, v1
	v_mov_b32_e32 v167, v157
	s_add_u32 s24, s2, 0x2600
	s_mul_i32 s2, s46, 3
	v_lshl_add_u64 v[0:1], v[0:1], 0, v[166:167]
	s_mov_b64 s[0:1], 0x1e00
	s_addc_u32 s25, s3, 0
	v_lshl_add_u64 v[0:1], v[0:1], 0, s[0:1]
	s_add_i32 s0, s31, s2
	s_mul_i32 s38, s46, 0xc0
	s_ashr_i32 s1, s0, 31
	s_ashr_i32 s39, s38, 31
	s_lshl_b64 s[0:1], s[0:1], 2
	s_add_u32 s0, s41, s0
	s_addc_u32 s1, s42, s1
	s_add_i32 s90, s38, 64
	s_add_i32 s66, s38, 0x80
	s_waitcnt lgkmcnt(0)
	v_lshl_add_u64 v[2:3], s[38:39], 1, v[0:1]
	s_ashr_i32 s91, s90, 31
	s_ashr_i32 s67, s66, 31
	global_load_dwordx4 v[16:19], v[2:3], off
	global_load_dwordx4 v[20:23], v[2:3], off offset:64
	global_load_dwordx3 v[136:138], v157, s[0:1]
	v_lshl_add_u64 v[2:3], s[90:91], 1, v[0:1]
	v_lshl_add_u64 v[0:1], s[66:67], 1, v[0:1]
	global_load_dwordx4 v[8:11], v[2:3], off
	global_load_dwordx4 v[12:15], v[2:3], off offset:64
	global_load_dwordx4 v[4:7], v[0:1], off
	s_nop 0
	global_load_dwordx4 v[0:3], v[0:1], off offset:64
	s_cmp_lt_i32 s4, 8
	s_cselect_b64 s[0:1], -1, 0
	s_cmp_gt_i32 s52, s35
	s_cselect_b64 s[2:3], -1, 0
	s_or_b64 s[2:3], s[0:1], s[2:3]
	s_mov_b64 s[0:1], -1
	s_andn2_b64 vcc, exec, s[2:3]
	v_lshlrev_b32_e32 v142, 1, v201
	s_waitcnt vmcnt(4)
	v_mov_b32_e32 v147, v137
	v_mov_b32_e32 v146, v138
	s_cbranch_vccz .LBB0_628
	s_mov_b32 s0, s52
	s_movk_i32 s1, 0xff80
	s_add_i32 s2, s0, s1
	v_lshl_add_u64 v[144:145], s[44:45], 0, v[156:157]
	v_add_u32_e32 v26, s2, v199
	v_mad_i64_i32 v[24:25], s[0:1], v26, s97, v[144:145]
	v_mov_b32_e32 v143, v157
	global_load_dwordx4 v[36:39], v[24:25], off
	global_load_dwordx4 v[32:35], v[24:25], off offset:64
	v_add_u32_e32 v24, 16, v26
	v_lshl_add_u64 v[146:147], s[24:25], 0, v[142:143]
	v_add_u32_e32 v44, s2, v200
	v_mad_i64_i32 v[24:25], s[0:1], v24, s97, v[144:145]
	v_mad_i64_i32 v[40:41], s[0:1], v44, s97, v[146:147]
	v_add_u32_e32 v42, 8, v44
	global_load_dwordx4 v[28:31], v[24:25], off
	s_nop 0
	global_load_dwordx4 v[24:27], v[24:25], off offset:64
	v_mad_i64_i32 v[42:43], s[0:1], v42, s97, v[146:147]
	global_load_dwordx4 v[104:107], v[40:41], off
	global_load_dwordx4 v[108:111], v[42:43], off
	v_add_u32_e32 v40, 16, v44
	v_mad_i64_i32 v[40:41], s[0:1], v40, s97, v[146:147]
	v_add_u32_e32 v42, 24, v44
	v_mad_i64_i32 v[42:43], s[0:1], v42, s97, v[146:147]
	global_load_dwordx4 v[112:115], v[40:41], off
	global_load_dwordx4 v[116:119], v[42:43], off
	s_not_b32 s0, s52
	v_readlane_b32 s1, v255, 21
	s_add_i32 s0, s1, s0
	v_min_i32_e32 v40, s0, v148
	v_mov_b32_e32 v42, v157
	v_mov_b32_e32 v43, v157
	v_sub_u32_e32 v153, v40, v139
	v_mov_b32_e32 v40, v157
	v_mov_b32_e32 v41, v157
	v_mov_b64_e32 v[46:47], v[42:43]
	v_mov_b64_e32 v[50:51], v[42:43]
	v_mov_b64_e32 v[62:63], v[42:43]
	v_mov_b64_e32 v[86:87], v[42:43]
	v_mov_b64_e32 v[82:83], v[42:43]
	v_mov_b64_e32 v[74:75], v[42:43]
	v_mov_b64_e32 v[78:79], v[42:43]
	v_mov_b64_e32 v[98:99], v[42:43]
	v_mov_b64_e32 v[90:91], v[42:43]
	v_mov_b64_e32 v[94:95], v[42:43]
	v_mov_b64_e32 v[102:103], v[42:43]
	v_mov_b32_e32 v152, 0
	s_mov_b32 s0, -2
	s_movk_i32 s1, 0xffc0
	v_mov_b64_e32 v[44:45], v[40:41]
	v_mov_b64_e32 v[48:49], v[40:41]
	v_mov_b64_e32 v[60:61], v[40:41]
	v_mov_b32_e32 v151, v138
	v_mov_b64_e32 v[84:85], v[40:41]
	v_mov_b64_e32 v[80:81], v[40:41]
	v_mov_b64_e32 v[72:73], v[40:41]
	v_mov_b64_e32 v[76:77], v[40:41]
	v_mov_b32_e32 v154, 0
	v_mov_b32_e32 v143, v137
	v_mov_b64_e32 v[96:97], v[40:41]
	v_mov_b64_e32 v[88:89], v[40:41]
	v_mov_b64_e32 v[92:93], v[40:41]
	v_mov_b64_e32 v[100:101], v[40:41]
	v_mov_b32_e32 v161, 0
	v_mov_b32_e32 v150, v136
	s_branch .Lmca_609
; __device__ __forceinline__ float shx(float v, int mask, int lane) { return __builtin_bit_cast(float, __builtin_amdgcn_ds_bpermute((lane ^ mask) << 2, __builtin_bit_cast(int, v))); }
; #define LAS __attribute__((address_space(3)))
; __device__ __forceinline__ float ex2(float x) { return __builtin_amdgcn_exp2f(x); }
; #define MFMA16(a, b, c) __builtin_amdgcn_mfma_f32_16x16x32_bf16(a, b, c, 0, 0, 0)
; template <bool EDGE>
; __device__ __forceinline__ void tile_load(TileLd& L, const bf16_t* kp, const bf16_t* vp, int S, int pos0, int dil, int k0, int lane) {
;     asm volatile("" : "+s"(k0), "+s"(pos0));
;     const int i16 = lane & 15, quad = lane >> 4;
; #pragma unroll
;     for (int st = 0; st < 2; ++st) { int pos = pos0 + dil * (k0 + 16 * st + i16); if (EDGE) pos = min(max(pos, 0), S - 1);
;         const bf16_t* p = kp + (long)pos * NIN + quad * 8; L.k[st][0] = *(const bf16x8*)p; L.k[st][1] = *(const bf16x8*)(p + 32); }
; #pragma unroll
;     for (int i = 0; i < 4; ++i) { int pos = pos0 + dil * (k0 + 8 * i + (lane >> 3)); if (EDGE) pos = min(max(pos, 0), S - 1);
;         L.v[i] = *(const u32x4*)(vp + (long)pos * NIN + (lane & 7) * 8); }
; }
; template <int G, bool EDGE> ...
;     asm volatile("" : "+s"(k0));
;     const int quad = lane >> 4; const f32x4 z4 = {0.f, 0.f, 0.f, 0.f};
;     bf16x8 vf[4]; stage_v_regs(L.v, vimg, lane, vf);
;     constexpr float C2 = 0.125f * LOG2E, THR = 6.0f;
;     const int kb = k0 + 4 * quad;
; #pragma unroll
;     for (int g = 0; g < G; ++g) {
;         const LAS float* lutb = lut + (kb - ua[g] + R);
;         float sc[8]; float mx = -1e30f;
; #pragma unroll
;         for (int st = 0; st < 2; ++st) { f32x4 s = MFMA16(L.k[st][0], q[g][0], z4); s = MFMA16(L.k[st][1], q[g][1], s);
; #pragma unroll
;             for (int jj = 0; jj < 4; ++jj) { const int c = 16 * st + jj; const bool v = (unsigned)(kb - klo[g] + c) <= (unsigned)kspan[g];
;                 float x = s[jj] * C2 + lutb[g * lutstride + c]; x = v ? x : -1e30f; sc[4 * st + jj] = x; mx = fmaxf(mx, x); } }
;         if (__any(mx - m[g] > THR)) {
;             mx = fmaxf(mx, shx(mx, 16, lane)); mx = fmaxf(mx, shx(mx, 32, lane));
;             const float mn = fmaxf(m[g], mx), al = ex2(m[g] - mn); m[g] = mn; l[g] *= al;
; #pragma unroll
;             for (int nn = 0; nn < 4; ++nn) o[g][nn] = o[g][nn] * al;
.Lmca_609:
	s_sub_i32 s34, s1, 32
	s_mov_b32 s2, s52
	s_mov_b32 s3, s34
	s_add_i32 s4, s2, s3
	v_add_u32_e32 v54, s4, v199
	v_mad_i64_i32 v[52:53], s[2:3], v54, s97, v[144:145]
	v_add_u32_e32 v132, s4, v200
	global_load_dwordx4 v[68:71], v[52:53], off
	global_load_dwordx4 v[64:67], v[52:53], off offset:64
	v_add_u32_e32 v52, 16, v54
	v_mad_i64_i32 v[120:121], s[2:3], v132, s97, v[146:147]
	v_add_u32_e32 v124, 8, v132
	v_add_u32_e32 v128, 16, v132
	v_add_u32_e32 v132, 24, v132
	v_mad_i64_i32 v[56:57], s[2:3], v52, s97, v[144:145]
	v_mad_i64_i32 v[124:125], s[2:3], v124, s97, v[146:147]
	v_mad_i64_i32 v[128:129], s[2:3], v128, s97, v[146:147]
	v_mad_i64_i32 v[132:133], s[2:3], v132, s97, v[146:147]
	global_load_dwordx4 v[52:55], v[56:57], off
	s_nop 0
	global_load_dwordx4 v[56:59], v[56:57], off offset:64
	s_sub_i32 s2, s1, 64
	global_load_dwordx4 v[120:123], v[120:121], off
	v_add_u32_e32 v155, v202, v203
	global_load_dwordx4 v[124:127], v[124:125], off
	s_waitcnt vmcnt(13)
	v_mfma_f32_16x16x32_bf16 v[170:173], v[36:39], v[16:19], 0
	global_load_dwordx4 v[128:131], v[128:129], off
	s_nop 0
	global_load_dwordx4 v[132:135], v[132:133], off
	s_waitcnt vmcnt(11)
	ds_write_b128 v155, v[104:107]
	s_waitcnt vmcnt(10)
	ds_write_b128 v155, v[108:111] offset:1152
	s_waitcnt vmcnt(9)
	ds_write_b128 v155, v[112:115] offset:2304
	s_waitcnt vmcnt(8)
	ds_write_b128 v155, v[116:119] offset:3456
	v_add_u32_e32 v162, s2, v204
	v_sub_u32_e32 v163, v162, v199
	v_lshl_add_u32 v167, v163, 2, s22
	ds_read_b64_tr_b16 v[116:117], v205
	ds_read_b64_tr_b16 v[104:105], v205 offset:32
	ds_read_b64_tr_b16 v[118:119], v205 offset:2304
	ds_read_b64_tr_b16 v[106:107], v205 offset:2336
	ds_read_b64_tr_b16 v[108:109], v205 offset:64
	ds_read_b64_tr_b16 v[110:111], v205 offset:2368
	ds_read_b64_tr_b16 v[112:113], v205 offset:96
	ds_read_b64_tr_b16 v[114:115], v205 offset:2400
	v_add_u32_e32 v163, 0x1400, v167
	v_sub_u32_e32 v178, v162, v139
	ds_read2_b32 v[162:163], v163 offset1:1
	v_mfma_f32_16x16x32_bf16 v[170:173], v[32:35], v[20:23], v[170:173]
	v_cmp_gt_u32_e64 s[2:3], v178, v153
	s_waitcnt lgkmcnt(0)
	s_nop 5
	v_fmamk_f32 v162, v170, 0x3e38aa3b, v162
	v_cndmask_b32_e64 v169, v162, v235, s[2:3]
	v_add_u32_e32 v162, 1, v178
	v_cmp_gt_u32_e64 s[4:5], v162, v153
	v_add_u32_e32 v162, 2, v178
	v_fmac_f32_e32 v163, 0x3e38aa3b, v171
	v_cmp_gt_u32_e64 s[6:7], v162, v153
	v_add_u32_e32 v162, 0x1408, v167
	v_cndmask_b32_e64 v170, v163, v235, s[4:5]
	ds_read2_b32 v[162:163], v162 offset1:1
	v_max3_f32 v174, v169, s95, v170
	s_waitcnt lgkmcnt(0)
	v_fmamk_f32 v162, v172, 0x3e38aa3b, v162
	v_cndmask_b32_e64 v171, v162, v235, s[6:7]
	v_add_u32_e32 v162, 3, v178
	v_cmp_gt_u32_e64 s[8:9], v162, v153
	v_fmac_f32_e32 v163, 0x3e38aa3b, v173
	v_add_u32_e32 v162, 16, v178
	v_cndmask_b32_e64 v172, v163, v235, s[8:9]
	v_max3_f32 v179, v174, v171, v172
	v_mfma_f32_16x16x32_bf16 v[174:177], v[28:31], v[16:19], 0
	v_cmp_gt_u32_e64 s[10:11], v162, v153
	v_add_u32_e32 v162, 0x1440, v167
	ds_read2_b32 v[162:163], v162 offset1:1
	v_mfma_f32_16x16x32_bf16 v[174:177], v[24:27], v[20:23], v[174:177]
	s_waitcnt lgkmcnt(0)
	s_nop 6
	v_fmamk_f32 v162, v174, 0x3e38aa3b, v162
	v_cndmask_b32_e64 v173, v162, v235, s[10:11]
	v_add_u32_e32 v162, 17, v178
	v_cmp_gt_u32_e64 s[12:13], v162, v153
	v_add_u32_e32 v162, 18, v178
	v_fmac_f32_e32 v163, 0x3e38aa3b, v175
	v_cmp_gt_u32_e64 s[14:15], v162, v153
	v_add_u32_e32 v162, 0x1448, v167
	v_cndmask_b32_e64 v174, v163, v235, s[12:13]
	ds_read2_b32 v[162:163], v162 offset1:1
	v_max3_f32 v179, v179, v173, v174
	s_waitcnt lgkmcnt(0)
	v_fmamk_f32 v162, v176, 0x3e38aa3b, v162
	v_cndmask_b32_e64 v175, v162, v235, s[14:15]
	v_add_u32_e32 v162, 19, v178
	v_cmp_gt_u32_e64 s[16:17], v162, v153
	v_fmac_f32_e32 v163, 0x3e38aa3b, v177
	s_nop 0
	v_cndmask_b32_e64 v176, v163, v235, s[16:17]
	v_max3_f32 v177, v179, v175, v176
	v_sub_f32_e32 v162, v177, v150
	v_cmp_lt_f32_e32 vcc, s19, v162
	s_cbranch_vccz .Lmca_611
	ds_bpermute_b32 v162, v207, v177
	v_max_f32_e32 v163, v177, v177
	s_waitcnt lgkmcnt(0)
	v_max_f32_e32 v162, v162, v162
	v_max_f32_e32 v162, v163, v162
	ds_bpermute_b32 v163, v206, v162
	s_waitcnt lgkmcnt(0)
	v_max3_f32 v162, v150, v162, v163
	v_sub_f32_e32 v150, v150, v162
	v_exp_f32_e32 v150, v150
	s_nop 0
	v_mul_f32_e32 v161, v161, v150
	v_pk_mul_f32 v[102:103], v[102:103], v[150:151] op_sel_hi:[1,0]
	v_pk_mul_f32 v[100:101], v[100:101], v[150:151] op_sel_hi:[1,0]
	v_pk_mul_f32 v[94:95], v[94:95], v[150:151] op_sel_hi:[1,0]
	v_pk_mul_f32 v[92:93], v[92:93], v[150:151] op_sel_hi:[1,0]
	v_pk_mul_f32 v[90:91], v[90:91], v[150:151] op_sel_hi:[1,0]
	v_pk_mul_f32 v[88:89], v[88:89], v[150:151] op_sel_hi:[1,0]
	v_pk_mul_f32 v[98:99], v[98:99], v[150:151] op_sel_hi:[1,0]
	v_pk_mul_f32 v[96:97], v[96:97], v[150:151] op_sel_hi:[1,0]
	v_mov_b32_e32 v150, v162

; __device__ __forceinline__ float shx(float v, int mask, int lane) { return __builtin_bit_cast(float, __builtin_amdgcn_ds_bpermute((lane ^ mask) << 2, __builtin_bit_cast(int, v))); }
; __device__ __forceinline__ unsigned cvt_pk_vis(float lo, float hi) { const f32x2_t f = {lo, hi}; const bf16x2_t v = __builtin_convertvector(f, bf16x2_t); return __builtin_bit_cast(unsigned, v); }
; #define LAS __attribute__((address_space(3)))
; __device__ __forceinline__ float ex2(float x) { return __builtin_amdgcn_exp2f(x); }
; #define MFMA16(a, b, c) __builtin_amdgcn_mfma_f32_16x16x32_bf16(a, b, c, 0, 0, 0)
; template <int G, bool EDGE> ...
;     ...
;     const int kb = k0 + 4 * quad;
; #pragma unroll
;     for (int g = 0; g < G; ++g) {
;         const LAS float* lutb = lut + (kb - ua[g] + R);
;         float sc[8]; float mx = -1e30f;
; #pragma unroll
;         for (int st = 0; st < 2; ++st) { f32x4 s = MFMA16(L.k[st][0], q[g][0], z4); s = MFMA16(L.k[st][1], q[g][1], s);
; #pragma unroll
;             for (int jj = 0; jj < 4; ++jj) { const int c = 16 * st + jj; const bool v = (unsigned)(kb - klo[g] + c) <= (unsigned)kspan[g];
;                 float x = s[jj] * C2 + lutb[g * lutstride + c]; x = v ? x : -1e30f; sc[4 * st + jj] = x; mx = fmaxf(mx, x); } }
;         if (__any(mx - m[g] > THR)) {
;             mx = fmaxf(mx, shx(mx, 16, lane)); mx = fmaxf(mx, shx(mx, 32, lane));
;             const float mn = fmaxf(m[g], mx), al = ex2(m[g] - mn); m[g] = mn; l[g] *= al;
; #pragma unroll
;             for (int nn = 0; nn < 4; ++nn) o[g][nn] = o[g][nn] * al;
;         }
;         const float mn = m[g]; float p[8], ps = 0.f;
; #pragma unroll
;         for (int e = 0; e < 8; ++e) { p[e] = ex2(sc[e] - mn); ps += p[e]; }
;         l[g] += ps;
;         const u32x4 pw = {pg8::cvt_pk_vis(p[0], p[1]), pg8::cvt_pk_vis(p[2], p[3]), pg8::cvt_pk_vis(p[4], p[5]), pg8::cvt_pk_vis(p[6], p[7])}; const bf16x8 pf = __builtin_bit_cast(bf16x8, pw);
; #pragma unroll
;         for (int nn = 0; nn < 4; ++nn) o[g][nn] = MFMA16(vf[nn], pf, o[g][nn]);
.Lmca_615:
	v_add_f32_e32 v29, 0, v169
	v_add_f32_e32 v29, v170, v29
	v_add_f32_e32 v29, v171, v29
	v_add_f32_e32 v29, v172, v29
	v_add_f32_e32 v29, v173, v29
	v_add_f32_e32 v29, v174, v29
	v_add_f32_e32 v29, v175, v29
	v_add_f32_e32 v29, v176, v29
	v_sub_f32_e32 v24, v24, v151
	v_add_f32_e32 v161, v161, v29
	v_sub_f32_e32 v29, v32, v151
	v_exp_f32_e32 v173, v24
	v_sub_f32_e32 v24, v25, v151
	v_exp_f32_e32 v169, v29
	v_sub_f32_e32 v29, v33, v151
	v_exp_f32_e32 v174, v24
	v_sub_f32_e32 v24, v26, v151
	v_exp_f32_e32 v170, v29
	v_sub_f32_e32 v29, v34, v151
	v_sub_f32_e32 v28, v28, v151
	v_exp_f32_e32 v175, v24
	v_sub_f32_e32 v24, v27, v151
	v_exp_f32_e32 v171, v29
	v_exp_f32_e32 v172, v28
	v_exp_f32_e32 v176, v24
	s_mov_b32 s2, s1
	s_mov_b32 s3, s52
	v_cvt_pk_bf16_f32 v24, v169, v170
	v_cvt_pk_bf16_f32 v25, v171, v172
	v_cvt_pk_bf16_f32 v26, v173, v174
	v_cvt_pk_bf16_f32 v27, v175, v176
	s_add_i32 s4, s3, s2
	s_waitcnt vmcnt(7)
	v_mfma_f32_16x16x32_bf16 v[186:189], v[68:71], v[16:19], 0
	v_mfma_f32_16x16x32_bf16 v[60:63], v[116:119], v[24:27], v[60:63]
	v_add_u32_e32 v116, s4, v200
	v_mfma_f32_16x16x32_bf16 v[48:51], v[104:107], v[24:27], v[48:51]
	v_mad_i64_i32 v[104:105], s[2:3], v116, s97, v[146:147]
	v_mfma_f32_16x16x32_bf16 v[44:47], v[108:111], v[24:27], v[44:47]
	v_add_u32_e32 v108, 8, v116
	v_mad_i64_i32 v[108:109], s[2:3], v108, s97, v[146:147]
	v_mfma_f32_16x16x32_bf16 v[40:43], v[112:115], v[24:27], v[40:43]
	v_add_u32_e32 v26, s4, v199
	v_mad_i64_i32 v[24:25], s[2:3], v26, s97, v[144:145]
	global_load_dwordx4 v[36:39], v[24:25], off
	global_load_dwordx4 v[32:35], v[24:25], off offset:64
	v_add_u32_e32 v24, 16, v26
	v_add_u32_e32 v112, 16, v116
	v_add_u32_e32 v116, 24, v116
	v_mad_i64_i32 v[24:25], s[2:3], v24, s97, v[144:145]
	v_mad_i64_i32 v[112:113], s[2:3], v112, s97, v[146:147]
	v_mad_i64_i32 v[116:117], s[2:3], v116, s97, v[146:147]
	global_load_dwordx4 v[28:31], v[24:25], off
	s_nop 0
	global_load_dwordx4 v[24:27], v[24:25], off offset:64
	s_waitcnt vmcnt(10)
	v_mfma_f32_16x16x32_bf16 v[186:189], v[64:67], v[20:23], v[186:189]
	global_load_dwordx4 v[104:107], v[104:105], off
	s_nop 0
	global_load_dwordx4 v[108:111], v[108:109], off
	s_nop 0
	global_load_dwordx4 v[112:115], v[112:113], off
	s_nop 0
	global_load_dwordx4 v[116:119], v[116:117], off
	s_waitcnt vmcnt(11)
	ds_write_b128 v155, v[120:123]
	s_waitcnt vmcnt(10)
	ds_write_b128 v155, v[124:127] offset:1152
	s_waitcnt vmcnt(9)
	ds_write_b128 v155, v[128:131] offset:2304
	s_waitcnt vmcnt(8)
	ds_write_b128 v155, v[132:135] offset:3456
	v_add_u32_e32 v162, s34, v204
	v_sub_u32_e32 v163, v162, v199
	v_lshl_add_u32 v167, v163, 2, s22
	ds_read_b64_tr_b16 v[124:125], v205
	ds_read_b64_tr_b16 v[120:121], v205 offset:32
	ds_read_b64_tr_b16 v[126:127], v205 offset:2304
	ds_read_b64_tr_b16 v[122:123], v205 offset:2336
	ds_read_b64_tr_b16 v[132:133], v205 offset:64
	ds_read_b64_tr_b16 v[134:135], v205 offset:2368
	ds_read_b64_tr_b16 v[128:129], v205 offset:96
	ds_read_b64_tr_b16 v[130:131], v205 offset:2400
	v_add_u32_e32 v163, 0x1400, v167
	ds_read2_b32 v[162:163], v163 offset1:1
	s_waitcnt lgkmcnt(0)
	v_fmamk_f32 v185, v186, 0x3e38aa3b, v162
	v_fmamk_f32 v186, v187, 0x3e38aa3b, v163
	v_add_u32_e32 v162, 0x1408, v167
	ds_read2_b32 v[162:163], v162 offset1:1
	v_max3_f32 v190, v185, s95, v186
	s_waitcnt lgkmcnt(0)
	v_fmamk_f32 v187, v188, 0x3e38aa3b, v162
	v_fmamk_f32 v188, v189, 0x3e38aa3b, v163
	v_max3_f32 v195, v190, v187, v188
	v_mfma_f32_16x16x32_bf16 v[190:193], v[52:55], v[16:19], 0
	v_add_u32_e32 v162, 0x1440, v167
	ds_read2_b32 v[162:163], v162 offset1:1
	v_mfma_f32_16x16x32_bf16 v[190:193], v[56:59], v[20:23], v[190:193]
	s_waitcnt lgkmcnt(0)
	s_nop 6
	v_fmamk_f32 v189, v190, 0x3e38aa3b, v162
	v_fmamk_f32 v190, v191, 0x3e38aa3b, v163
	v_add_u32_e32 v162, 0x1448, v167
	ds_read2_b32 v[162:163], v162 offset1:1
	v_max3_f32 v195, v195, v189, v190
	s_waitcnt lgkmcnt(0)
	v_fmamk_f32 v191, v192, 0x3e38aa3b, v162
	v_fmac_f32_e32 v163, 0x3e38aa3b, v193
	s_nop 0
	v_mov_b32_e32 v192, v163
	v_max3_f32 v193, v195, v191, v192
	v_sub_f32_e32 v162, v193, v150
	v_cmp_lt_f32_e32 vcc, s19, v162
	s_cbranch_vccz .Lmca_617
	ds_bpermute_b32 v162, v207, v193
	v_max_f32_e32 v163, v193, v193
	s_waitcnt lgkmcnt(0)
	v_max_f32_e32 v162, v162, v162
	v_max_f32_e32 v162, v163, v162
	ds_bpermute_b32 v163, v206, v162
	s_waitcnt lgkmcnt(0)
	v_max3_f32 v162, v150, v162, v163
	v_sub_f32_e32 v150, v150, v162
	v_exp_f32_e32 v150, v150
	s_nop 0
	v_mul_f32_e32 v161, v161, v150
	v_pk_mul_f32 v[102:103], v[102:103], v[150:151] op_sel_hi:[1,0]
	v_pk_mul_f32 v[100:101], v[100:101], v[150:151] op_sel_hi:[1,0]
	v_pk_mul_f32 v[94:95], v[94:95], v[150:151] op_sel_hi:[1,0]
	v_pk_mul_f32 v[92:93], v[92:93], v[150:151] op_sel_hi:[1,0]
	v_pk_mul_f32 v[90:91], v[90:91], v[150:151] op_sel_hi:[1,0]
	v_pk_mul_f32 v[88:89], v[88:89], v[150:151] op_sel_hi:[1,0]
	v_pk_mul_f32 v[98:99], v[98:99], v[150:151] op_sel_hi:[1,0]
	v_pk_mul_f32 v[96:97], v[96:97], v[150:151] op_sel_hi:[1,0]
	v_mov_b32_e32 v150, v162
; __device__ __forceinline__ float shx(float v, int mask, int lane) { return __builtin_bit_cast(float, __builtin_amdgcn_ds_bpermute((lane ^ mask) << 2, __builtin_bit_cast(int, v))); }
; __device__ __forceinline__ unsigned cvt_pk_vis(float lo, float hi) { const f32x2_t f = {lo, hi}; const bf16x2_t v = __builtin_convertvector(f, bf16x2_t); return __builtin_bit_cast(unsigned, v); }
; #define LAS __attribute__((address_space(3)))
; __device__ __forceinline__ float ex2(float x) { return __builtin_amdgcn_exp2f(x); }
; #define MFMA16(a, b, c) __builtin_amdgcn_mfma_f32_16x16x32_bf16(a, b, c, 0, 0, 0)
; template <int G, bool EDGE> ...
;     ...
;     for (int g = 0; g < G; ++g) {
;         const LAS float* lutb = lut + (kb - ua[g] + R);
;         float sc[8]; float mx = -1e30f;
; #pragma unroll
;         for (int st = 0; st < 2; ++st) { f32x4 s = MFMA16(L.k[st][0], q[g][0], z4); s = MFMA16(L.k[st][1], q[g][1], s);
; #pragma unroll
;             for (int jj = 0; jj < 4; ++jj) { const int c = 16 * st + jj; const bool v = (unsigned)(kb - klo[g] + c) <= (unsigned)kspan[g];
;                 float x = s[jj] * C2 + lutb[g * lutstride + c]; x = v ? x : -1e30f; sc[4 * st + jj] = x; mx = fmaxf(mx, x); } }
;         if (__any(mx - m[g] > THR)) {
;             mx = fmaxf(mx, shx(mx, 16, lane)); mx = fmaxf(mx, shx(mx, 32, lane));
;             const float mn = fmaxf(m[g], mx), al = ex2(m[g] - mn); m[g] = mn; l[g] *= al;
; #pragma unroll
;             for (int nn = 0; nn < 4; ++nn) o[g][nn] = o[g][nn] * al;
;         }
;         const float mn = m[g]; float p[8], ps = 0.f;
; #pragma unroll
;         for (int e = 0; e < 8; ++e) { p[e] = ex2(sc[e] - mn); ps += p[e]; }
;         l[g] += ps;
;         const u32x4 pw = {pg8::cvt_pk_vis(p[0], p[1]), pg8::cvt_pk_vis(p[2], p[3]), pg8::cvt_pk_vis(p[4], p[5]), pg8::cvt_pk_vis(p[6], p[7])}; const bf16x8 pf = __builtin_bit_cast(bf16x8, pw);
; #pragma unroll
;         for (int nn = 0; nn < 4; ++nn) o[g][nn] = MFMA16(vf[nn], pf, o[g][nn]);
.Lmca_617:
	v_add_f32_e32 v162, 0, v177
	v_add_f32_e32 v162, v178, v162
	v_add_f32_e32 v162, v179, v162
	v_add_f32_e32 v162, v180, v162
	v_add_f32_e32 v162, v181, v162
	v_add_f32_e32 v162, v182, v162
	v_add_f32_e32 v162, v183, v162
	v_add_f32_e32 v162, v184, v162
	v_add_f32_e32 v154, v154, v162
	v_sub_f32_e32 v162, v185, v150
	v_exp_f32_e32 v177, v162
	v_sub_f32_e32 v162, v186, v150
	v_exp_f32_e32 v178, v162
	v_sub_f32_e32 v162, v187, v150
	v_exp_f32_e32 v179, v162
	v_sub_f32_e32 v162, v188, v150
	v_exp_f32_e32 v180, v162
	v_sub_f32_e32 v162, v189, v150
	v_exp_f32_e32 v181, v162
	v_sub_f32_e32 v162, v190, v150
	v_exp_f32_e32 v182, v162
	v_sub_f32_e32 v162, v191, v150
	v_exp_f32_e32 v183, v162
	v_sub_f32_e32 v162, v192, v150
	v_exp_f32_e32 v184, v162
	v_cvt_pk_bf16_f32 v186, v177, v178
	v_cvt_pk_bf16_f32 v187, v179, v180
	v_cvt_pk_bf16_f32 v188, v181, v182
	v_cvt_pk_bf16_f32 v189, v183, v184
	v_add_u32_e32 v162, 0x1804, v167
	ds_read2_b32 v[162:163], v162 offset1:1
	v_mfma_f32_16x16x32_bf16 v[100:103], v[124:127], v[186:189], v[100:103]
	v_mfma_f32_16x16x32_bf16 v[92:95], v[120:123], v[186:189], v[92:95]
	v_mfma_f32_16x16x32_bf16 v[88:91], v[132:135], v[186:189], v[88:91]
	v_mfma_f32_16x16x32_bf16 v[96:99], v[128:131], v[186:189], v[96:99]
	v_mfma_f32_16x16x32_bf16 v[186:189], v[68:71], v[8:11], 0
	v_mfma_f32_16x16x32_bf16 v[186:189], v[64:67], v[12:15], v[186:189]
	s_waitcnt lgkmcnt(0)
	s_nop 6
	v_fmamk_f32 v185, v186, 0x3e38aa3b, v162
	v_fmamk_f32 v186, v187, 0x3e38aa3b, v163
	v_add_u32_e32 v162, 0x180c, v167
	ds_read2_b32 v[162:163], v162 offset1:1
	v_max3_f32 v190, v185, s95, v186
	s_waitcnt lgkmcnt(0)
	v_fmamk_f32 v187, v188, 0x3e38aa3b, v162
	v_fmamk_f32 v188, v189, 0x3e38aa3b, v163
	v_max3_f32 v194, v190, v187, v188
	v_mfma_f32_16x16x32_bf16 v[190:193], v[52:55], v[8:11], 0
	v_add_u32_e32 v162, 0x1844, v167
	ds_read2_b32 v[162:163], v162 offset1:1
	v_mfma_f32_16x16x32_bf16 v[190:193], v[56:59], v[12:15], v[190:193]
	s_waitcnt lgkmcnt(0)
	s_nop 6
	v_fmamk_f32 v189, v190, 0x3e38aa3b, v162
	v_fmamk_f32 v190, v191, 0x3e38aa3b, v163
	v_add_u32_e32 v162, 0x184c, v167
	ds_read2_b32 v[162:163], v162 offset1:1
	v_max3_f32 v194, v194, v189, v190
	s_waitcnt lgkmcnt(0)
	v_fmamk_f32 v191, v192, 0x3e38aa3b, v162
	v_fmac_f32_e32 v163, 0x3e38aa3b, v193
	v_mov_b32_e32 v192, v163
	v_max3_f32 v193, v194, v191, v192
	v_sub_f32_e32 v162, v193, v143
	v_cmp_lt_f32_e32 vcc, s19, v162
	s_cbranch_vccz .Lmca_619
	ds_bpermute_b32 v162, v207, v193
	v_max_f32_e32 v163, v193, v193
	s_waitcnt lgkmcnt(0)
	v_max_f32_e32 v162, v162, v162
	v_max_f32_e32 v162, v163, v162
	ds_bpermute_b32 v163, v206, v162
	s_waitcnt lgkmcnt(0)
	v_max3_f32 v163, v143, v162, v163
	v_sub_f32_e32 v143, v143, v163
	v_exp_f32_e32 v162, v143
	v_mov_b32_e32 v143, v163
	v_mul_f32_e32 v154, v154, v162
	v_pk_mul_f32 v[78:79], v[78:79], v[162:163] op_sel_hi:[1,0]
	v_pk_mul_f32 v[76:77], v[76:77], v[162:163] op_sel_hi:[1,0]
	v_pk_mul_f32 v[74:75], v[74:75], v[162:163] op_sel_hi:[1,0]
	v_pk_mul_f32 v[72:73], v[72:73], v[162:163] op_sel_hi:[1,0]
	v_pk_mul_f32 v[82:83], v[82:83], v[162:163] op_sel_hi:[1,0]
	v_pk_mul_f32 v[80:81], v[80:81], v[162:163] op_sel_hi:[1,0]
	v_pk_mul_f32 v[86:87], v[86:87], v[162:163] op_sel_hi:[1,0]
	v_pk_mul_f32 v[84:85], v[84:85], v[162:163] op_sel_hi:[1,0]
; __device__ __forceinline__ float shx(float v, int mask, int lane) { return __builtin_bit_cast(float, __builtin_amdgcn_ds_bpermute((lane ^ mask) << 2, __builtin_bit_cast(int, v))); }
; __device__ __forceinline__ unsigned cvt_pk_vis(float lo, float hi) { const f32x2_t f = {lo, hi}; const bf16x2_t v = __builtin_convertvector(f, bf16x2_t); return __builtin_bit_cast(unsigned, v); }
; #define LAS __attribute__((address_space(3)))
; __device__ __forceinline__ float ex2(float x) { return __builtin_amdgcn_exp2f(x); }
; template <int G, bool EDGE> ...
;     ...
;     for (int g = 0; g < G; ++g) {
;         const LAS float* lutb = lut + (kb - ua[g] + R);
;         float sc[8]; float mx = -1e30f;
; #pragma unroll
;         for (int st = 0; st < 2; ++st) { f32x4 s = MFMA16(L.k[st][0], q[g][0], z4); s = MFMA16(L.k[st][1], q[g][1], s);
; #pragma unroll
;             for (int jj = 0; jj < 4; ++jj) { const int c = 16 * st + jj; const bool v = (unsigned)(kb - klo[g] + c) <= (unsigned)kspan[g];
;                 float x = s[jj] * C2 + lutb[g * lutstride + c]; x = v ? x : -1e30f; sc[4 * st + jj] = x; mx = fmaxf(mx, x); } }
;         if (__any(mx - m[g] > THR)) {
;             mx = fmaxf(mx, shx(mx, 16, lane)); mx = fmaxf(mx, shx(mx, 32, lane));
;             const float mn = fmaxf(m[g], mx), al = ex2(m[g] - mn); m[g] = mn; l[g] *= al;
; #pragma unroll
;             for (int nn = 0; nn < 4; ++nn) o[g][nn] = o[g][nn] * al;
;         }
;         const float mn = m[g]; float p[8], ps = 0.f;
; #pragma unroll
;         for (int e = 0; e < 8; ++e) { p[e] = ex2(sc[e] - mn); ps += p[e]; }
;         l[g] += ps;
;         const u32x4 pw = {pg8::cvt_pk_vis(p[0], p[1]), pg8::cvt_pk_vis(p[2], p[3]), pg8::cvt_pk_vis(p[4], p[5]), pg8::cvt_pk_vis(p[6], p[7])}; const bf16x8 pf = __builtin_bit_cast(bf16x8, pw);
; #pragma unroll
;         for (int nn = 0; nn < 4; ++nn) o[g][nn] = MFMA16(vf[nn], pf, o[g][nn]);
; template <bool EDGE>
; __device__ __forceinline__ void mixer_c_item(const bf16_t* kp, const bf16_t* vp, int S, int P0, const LAS float* lut, LAS unsigned char* vimg, int lane,
;                                              const bf16x8 (&q)[3][2], f32x4 (&o)[3][4], float (&m)[3], float (&l)[3]) {
;     ...
; #pragma unroll 1
;     for (int t = 0; t < 8; t += 2) { C_STEP(ta, tb, t, true); C_STEP(tb, ta, t + 1, true); }
;     C_STEP(ta, tb, 8, false);
.Lmca_619:
	v_add_f32_e32 v162, 0, v169
	v_add_f32_e32 v162, v170, v162
	v_add_f32_e32 v162, v171, v162
	v_add_f32_e32 v162, v172, v162
	v_add_f32_e32 v162, v173, v162
	v_add_f32_e32 v162, v174, v162
	v_add_f32_e32 v162, v175, v162
	v_add_f32_e32 v162, v176, v162
	v_add_f32_e32 v152, v152, v162
	v_sub_f32_e32 v162, v185, v143
	v_exp_f32_e32 v169, v162
	v_sub_f32_e32 v162, v186, v143
	v_exp_f32_e32 v170, v162
	v_sub_f32_e32 v162, v187, v143
	v_exp_f32_e32 v171, v162
	v_sub_f32_e32 v162, v188, v143
	v_exp_f32_e32 v172, v162
	v_sub_f32_e32 v162, v189, v143
	v_exp_f32_e32 v173, v162
	v_sub_f32_e32 v162, v190, v143
	v_mfma_f32_16x16x32_bf16 v[68:71], v[68:71], v[4:7], 0
	v_exp_f32_e32 v174, v162
	v_sub_f32_e32 v162, v191, v143
	v_exp_f32_e32 v175, v162
	v_sub_f32_e32 v162, v192, v143
	v_exp_f32_e32 v176, v162
	v_add_u32_e32 v162, 0x1c08, v167
	v_mfma_f32_16x16x32_bf16 v[66:69], v[64:67], v[0:3], v[68:71]
	v_cvt_pk_bf16_f32 v186, v169, v170
	v_cvt_pk_bf16_f32 v187, v171, v172
	v_cvt_pk_bf16_f32 v188, v173, v174
	ds_read2_b32 v[70:71], v162 offset1:1
	v_mfma_f32_16x16x32_bf16 v[52:55], v[52:55], v[4:7], 0
	v_cvt_pk_bf16_f32 v189, v175, v176
	s_waitcnt lgkmcnt(0)
	s_nop 0
	v_fmamk_f32 v65, v66, 0x3e38aa3b, v70
	v_fmamk_f32 v64, v67, 0x3e38aa3b, v71
	v_add_u32_e32 v66, 0x1c10, v167
	v_mfma_f32_16x16x32_bf16 v[54:57], v[56:59], v[0:3], v[52:55]
	ds_read2_b32 v[70:71], v66 offset1:1
	v_add_u32_e32 v52, 0x1c48, v167
	ds_read2_b32 v[58:59], v52 offset1:1
	v_max3_f32 v162, v65, s95, v64
	v_mfma_f32_16x16x32_bf16 v[76:79], v[124:127], v[186:189], v[76:79]
	s_waitcnt lgkmcnt(1)
	v_fmamk_f32 v67, v68, 0x3e38aa3b, v70
	v_fmac_f32_e32 v71, 0x3e38aa3b, v69
	s_waitcnt lgkmcnt(0)
	v_fmamk_f32 v53, v54, 0x3e38aa3b, v58
	v_add_u32_e32 v54, 0x1c50, v167
	v_fmac_f32_e32 v59, 0x3e38aa3b, v55
	ds_read2_b32 v[54:55], v54 offset1:1
	v_mov_b32_e32 v66, v71
	v_max3_f32 v68, v162, v67, v66
	v_mov_b32_e32 v52, v59
	s_waitcnt lgkmcnt(0)
	v_fmamk_f32 v54, v56, 0x3e38aa3b, v54
	v_fmac_f32_e32 v55, 0x3e38aa3b, v57
	v_mfma_f32_16x16x32_bf16 v[72:75], v[120:123], v[186:189], v[72:75]
	v_max3_f32 v58, v68, v53, v52
	v_mfma_f32_16x16x32_bf16 v[80:83], v[132:135], v[186:189], v[80:83]
	v_max3_f32 v56, v58, v54, v55
	v_sub_f32_e32 v57, v56, v151
	v_cmp_lt_f32_e32 vcc, s19, v57
	v_mfma_f32_16x16x32_bf16 v[84:87], v[128:131], v[186:189], v[84:87]
	s_cbranch_vccz .Lmca_608
	ds_bpermute_b32 v57, v207, v56
	v_max_f32_e32 v56, v56, v56
	s_waitcnt lgkmcnt(0)
	v_max_f32_e32 v57, v57, v57
	v_max_f32_e32 v56, v56, v57
	ds_bpermute_b32 v57, v206, v56
	s_waitcnt lgkmcnt(0)
	v_max3_f32 v57, v151, v56, v57
	v_sub_f32_e32 v56, v151, v57
	v_exp_f32_e32 v56, v56
	v_mov_b32_e32 v151, v57
	v_mul_f32_e32 v152, v152, v56
	v_pk_mul_f32 v[62:63], v[62:63], v[56:57] op_sel_hi:[1,0]
	v_pk_mul_f32 v[60:61], v[60:61], v[56:57] op_sel_hi:[1,0]
	v_pk_mul_f32 v[50:51], v[50:51], v[56:57] op_sel_hi:[1,0]
	v_pk_mul_f32 v[48:49], v[48:49], v[56:57] op_sel_hi:[1,0]
	v_pk_mul_f32 v[46:47], v[46:47], v[56:57] op_sel_hi:[1,0]
	v_pk_mul_f32 v[44:45], v[44:45], v[56:57] op_sel_hi:[1,0]
	v_pk_mul_f32 v[42:43], v[42:43], v[56:57] op_sel_hi:[1,0]
	v_pk_mul_f32 v[40:41], v[40:41], v[56:57] op_sel_hi:[1,0]
	s_branch .Lmca_608
.Lmca_608:
	v_add_f32_e32 v56, 0, v169
	v_add_f32_e32 v56, v170, v56
	v_add_f32_e32 v56, v171, v56
	v_add_f32_e32 v56, v172, v56
	v_add_f32_e32 v56, v173, v56
	v_add_f32_e32 v56, v174, v56
	v_add_f32_e32 v56, v175, v56
	v_add_f32_e32 v56, v176, v56
	v_add_f32_e32 v154, v154, v56
	v_add_f32_e32 v56, 0, v177
	v_add_f32_e32 v56, v178, v56
	v_add_f32_e32 v56, v179, v56
	v_add_f32_e32 v56, v180, v56
	v_sub_f32_e32 v57, v65, v151
	v_add_f32_e32 v56, v181, v56
	v_exp_f32_e32 v57, v57
	v_sub_f32_e32 v58, v64, v151
	v_add_f32_e32 v56, v182, v56
	v_exp_f32_e32 v58, v58
	v_sub_f32_e32 v59, v67, v151
	v_sub_f32_e32 v52, v52, v151
	v_add_f32_e32 v56, v183, v56
	v_exp_f32_e32 v59, v59
	v_sub_f32_e32 v64, v66, v151
	v_exp_f32_e32 v66, v52
	v_sub_f32_e32 v52, v54, v151
	v_add_f32_e32 v56, v184, v56
	v_exp_f32_e32 v64, v64
	v_sub_f32_e32 v53, v53, v151
	v_exp_f32_e32 v67, v52
	v_sub_f32_e32 v52, v55, v151
	v_add_f32_e32 v161, v161, v56
	v_add_f32_e32 v56, 0, v57
	v_exp_f32_e32 v65, v53
	v_exp_f32_e32 v68, v52
	v_add_f32_e32 v56, v58, v56
	v_add_f32_e32 v56, v59, v56
	v_add_f32_e32 v56, v64, v56
	v_cvt_pk_bf16_f32 v52, v57, v58
	v_cvt_pk_bf16_f32 v53, v59, v64
	v_cvt_pk_bf16_f32 v54, v65, v66
	v_cvt_pk_bf16_f32 v55, v67, v68
	v_add_f32_e32 v56, v65, v56
	v_add_f32_e32 v56, v66, v56
	v_mfma_f32_16x16x32_bf16 v[60:63], v[124:127], v[52:55], v[60:63]
	v_add_f32_e32 v56, v67, v56
	v_add_f32_e32 v56, v68, v56
	s_add_i32 s0, s0, 2
	v_mfma_f32_16x16x32_bf16 v[48:51], v[120:123], v[52:55], v[48:51]
	s_add_i32 s1, s1, 64
	v_add_f32_e32 v152, v152, v56
	s_cmp_gt_u32 s0, 5
	v_mfma_f32_16x16x32_bf16 v[44:47], v[132:135], v[52:55], v[44:47]
	v_mfma_f32_16x16x32_bf16 v[40:43], v[128:131], v[52:55], v[40:43]
	s_cbranch_scc1 .LBB0_621
	s_branch .LBB0_609

; __device__ __forceinline__ float shx(float v, int mask, int lane) { return __builtin_bit_cast(float, __builtin_amdgcn_ds_bpermute((lane ^ mask) << 2, __builtin_bit_cast(int, v))); }
; #define LAS __attribute__((address_space(3)))
; __device__ __forceinline__ float ex2(float x) { return __builtin_amdgcn_exp2f(x); }
; #define MFMA16(a, b, c) __builtin_amdgcn_mfma_f32_16x16x32_bf16(a, b, c, 0, 0, 0)
; template <bool EDGE>
; __device__ __forceinline__ void tile_load(TileLd& L, const bf16_t* kp, const bf16_t* vp, int S, int pos0, int dil, int k0, int lane) {
;     asm volatile("" : "+s"(k0), "+s"(pos0));
;     const int i16 = lane & 15, quad = lane >> 4;
; #pragma unroll
;     for (int st = 0; st < 2; ++st) { int pos = pos0 + dil * (k0 + 16 * st + i16); if (EDGE) pos = min(max(pos, 0), S - 1);
;         const bf16_t* p = kp + (long)pos * NIN + quad * 8; L.k[st][0] = *(const bf16x8*)p; L.k[st][1] = *(const bf16x8*)(p + 32); }
; #pragma unroll
;     for (int i = 0; i < 4; ++i) { int pos = pos0 + dil * (k0 + 8 * i + (lane >> 3)); if (EDGE) pos = min(max(pos, 0), S - 1);
;         L.v[i] = *(const u32x4*)(vp + (long)pos * NIN + (lane & 7) * 8); }
; }
; template <int G, bool EDGE> ...
;     asm volatile("" : "+s"(k0));
;     const int quad = lane >> 4; const f32x4 z4 = {0.f, 0.f, 0.f, 0.f};
;     bf16x8 vf[4]; stage_v_regs(L.v, vimg, lane, vf);
;     constexpr float C2 = 0.125f * LOG2E, THR = 6.0f;
;     const int kb = k0 + 4 * quad;
; #pragma unroll
;     for (int g = 0; g < G; ++g) {
;         const LAS float* lutb = lut + (kb - ua[g] + R);
;         float sc[8]; float mx = -1e30f;
; #pragma unroll
;         for (int st = 0; st < 2; ++st) { f32x4 s = MFMA16(L.k[st][0], q[g][0], z4); s = MFMA16(L.k[st][1], q[g][1], s);
; #pragma unroll
;             for (int jj = 0; jj < 4; ++jj) { const int c = 16 * st + jj; const bool v = (unsigned)(kb - klo[g] + c) <= (unsigned)kspan[g];
;                 float x = s[jj] * C2 + lutb[g * lutstride + c]; x = v ? x : -1e30f; sc[4 * st + jj] = x; mx = fmaxf(mx, x); } }
;         if (__any(mx - m[g] > THR)) {
;             mx = fmaxf(mx, shx(mx, 16, lane)); mx = fmaxf(mx, shx(mx, 32, lane));
;             const float mn = fmaxf(m[g], mx), al = ex2(m[g] - mn); m[g] = mn; l[g] *= al;
; #pragma unroll
;             for (int nn = 0; nn < 4; ++nn) o[g][nn] = o[g][nn] * al;
.LBB0_609:
	s_sub_i32 s34, s1, 32
	s_mov_b32 s2, s52
	s_mov_b32 s3, s34
	s_add_i32 s4, s2, s3
	v_add_u32_e32 v54, s4, v199
	v_mad_i64_i32 v[52:53], s[2:3], v54, s97, v[144:145]
	v_add_u32_e32 v132, s4, v200
	global_load_dwordx4 v[68:71], v[52:53], off
	global_load_dwordx4 v[64:67], v[52:53], off offset:64
	v_add_u32_e32 v52, 16, v54
	v_mad_i64_i32 v[120:121], s[2:3], v132, s97, v[146:147]
	v_add_u32_e32 v124, 8, v132
	v_add_u32_e32 v128, 16, v132
	v_add_u32_e32 v132, 24, v132
	v_mad_i64_i32 v[56:57], s[2:3], v52, s97, v[144:145]
	v_mad_i64_i32 v[124:125], s[2:3], v124, s97, v[146:147]
	v_mad_i64_i32 v[128:129], s[2:3], v128, s97, v[146:147]
	v_mad_i64_i32 v[132:133], s[2:3], v132, s97, v[146:147]
	global_load_dwordx4 v[52:55], v[56:57], off
	s_nop 0
	global_load_dwordx4 v[56:59], v[56:57], off offset:64
	s_sub_i32 s2, s1, 64
	global_load_dwordx4 v[120:123], v[120:121], off
	v_add_u32_e32 v155, v202, v203
	global_load_dwordx4 v[124:127], v[124:125], off
	s_waitcnt vmcnt(13)
	v_mfma_f32_16x16x32_bf16 v[170:173], v[36:39], v[16:19], 0
	global_load_dwordx4 v[128:131], v[128:129], off
	s_nop 0
	global_load_dwordx4 v[132:135], v[132:133], off
	s_waitcnt vmcnt(11)
	ds_write_b128 v155, v[104:107]
	s_waitcnt vmcnt(10)
	ds_write_b128 v155, v[108:111] offset:1152
	s_waitcnt vmcnt(9)
	ds_write_b128 v155, v[112:115] offset:2304
	s_waitcnt vmcnt(8)
	ds_write_b128 v155, v[116:119] offset:3456
	v_add_u32_e32 v162, s2, v204
	v_sub_u32_e32 v163, v162, v199
	v_lshl_add_u32 v167, v163, 2, s22
	ds_read_b64_tr_b16 v[116:117], v205
	ds_read_b64_tr_b16 v[104:105], v205 offset:32
	ds_read_b64_tr_b16 v[118:119], v205 offset:2304
	ds_read_b64_tr_b16 v[106:107], v205 offset:2336
	ds_read_b64_tr_b16 v[108:109], v205 offset:64
	ds_read_b64_tr_b16 v[110:111], v205 offset:2368
	ds_read_b64_tr_b16 v[112:113], v205 offset:96
	ds_read_b64_tr_b16 v[114:115], v205 offset:2400
	v_add_u32_e32 v163, 0x1400, v167
	ds_read2_b32 v[162:163], v163 offset1:1
	v_mfma_f32_16x16x32_bf16 v[170:173], v[32:35], v[20:23], v[170:173]
	s_waitcnt lgkmcnt(0)
	s_nop 5
	s_nop 0
	v_fmamk_f32 v169, v170, 0x3e38aa3b, v162
	v_fmamk_f32 v170, v171, 0x3e38aa3b, v163
	v_add_u32_e32 v162, 0x1408, v167
	ds_read2_b32 v[162:163], v162 offset1:1
	v_max3_f32 v174, v169, s95, v170
	s_waitcnt lgkmcnt(0)
	v_fmamk_f32 v171, v172, 0x3e38aa3b, v162
	v_fmamk_f32 v172, v173, 0x3e38aa3b, v163
	v_max3_f32 v179, v174, v171, v172
	v_mfma_f32_16x16x32_bf16 v[174:177], v[28:31], v[16:19], 0
	v_add_u32_e32 v162, 0x1440, v167
	ds_read2_b32 v[162:163], v162 offset1:1
	v_mfma_f32_16x16x32_bf16 v[174:177], v[24:27], v[20:23], v[174:177]
	s_waitcnt lgkmcnt(0)
	s_nop 6
	v_fmamk_f32 v173, v174, 0x3e38aa3b, v162
	v_fmamk_f32 v174, v175, 0x3e38aa3b, v163
	v_add_u32_e32 v162, 0x1448, v167
	ds_read2_b32 v[162:163], v162 offset1:1
	v_max3_f32 v179, v179, v173, v174
	s_waitcnt lgkmcnt(0)
	v_fmamk_f32 v175, v176, 0x3e38aa3b, v162
	v_fmac_f32_e32 v163, 0x3e38aa3b, v177
	s_nop 0
	v_mov_b32_e32 v176, v163
	v_max3_f32 v177, v179, v175, v176
	v_sub_f32_e32 v162, v177, v150
	v_cmp_lt_f32_e32 vcc, s19, v162
	s_cbranch_vccz .LBB0_611
	ds_bpermute_b32 v162, v207, v177
	v_max_f32_e32 v163, v177, v177
	s_waitcnt lgkmcnt(0)
	v_max_f32_e32 v162, v162, v162
	v_max_f32_e32 v162, v163, v162
	ds_bpermute_b32 v163, v206, v162
	s_waitcnt lgkmcnt(0)
	v_max3_f32 v162, v150, v162, v163
	v_sub_f32_e32 v150, v150, v162
	v_exp_f32_e32 v150, v150
	s_nop 0
	v_mul_f32_e32 v161, v161, v150
	v_pk_mul_f32 v[102:103], v[102:103], v[150:151] op_sel_hi:[1,0]
	v_pk_mul_f32 v[100:101], v[100:101], v[150:151] op_sel_hi:[1,0]
	v_pk_mul_f32 v[94:95], v[94:95], v[150:151] op_sel_hi:[1,0]
	v_pk_mul_f32 v[92:93], v[92:93], v[150:151] op_sel_hi:[1,0]
	v_pk_mul_f32 v[90:91], v[90:91], v[150:151] op_sel_hi:[1,0]
	v_pk_mul_f32 v[88:89], v[88:89], v[150:151] op_sel_hi:[1,0]
	v_pk_mul_f32 v[98:99], v[98:99], v[150:151] op_sel_hi:[1,0]
	v_pk_mul_f32 v[96:97], v[96:97], v[150:151] op_sel_hi:[1,0]
	v_mov_b32_e32 v150, v162
; __device__ __forceinline__ float shx(float v, int mask, int lane) { return __builtin_bit_cast(float, __builtin_amdgcn_ds_bpermute((lane ^ mask) << 2, __builtin_bit_cast(int, v))); }
; __device__ __forceinline__ unsigned cvt_pk_vis(float lo, float hi) { const f32x2_t f = {lo, hi}; const bf16x2_t v = __builtin_convertvector(f, bf16x2_t); return __builtin_bit_cast(unsigned, v); }
; #define LAS __attribute__((address_space(3)))
; __device__ __forceinline__ float ex2(float x) { return __builtin_amdgcn_exp2f(x); }
; #define MFMA16(a, b, c) __builtin_amdgcn_mfma_f32_16x16x32_bf16(a, b, c, 0, 0, 0)
; template <int G, bool EDGE> ...
;     ...
;     for (int g = 0; g < G; ++g) {
;         const LAS float* lutb = lut + (kb - ua[g] + R);
;         float sc[8]; float mx = -1e30f;
; #pragma unroll
;         for (int st = 0; st < 2; ++st) { f32x4 s = MFMA16(L.k[st][0], q[g][0], z4); s = MFMA16(L.k[st][1], q[g][1], s);
; #pragma unroll
;             for (int jj = 0; jj < 4; ++jj) { const int c = 16 * st + jj; const bool v = (unsigned)(kb - klo[g] + c) <= (unsigned)kspan[g];
;                 float x = s[jj] * C2 + lutb[g * lutstride + c]; x = v ? x : -1e30f; sc[4 * st + jj] = x; mx = fmaxf(mx, x); } }
;         if (__any(mx - m[g] > THR)) {
;             mx = fmaxf(mx, shx(mx, 16, lane)); mx = fmaxf(mx, shx(mx, 32, lane));
;             const float mn = fmaxf(m[g], mx), al = ex2(m[g] - mn); m[g] = mn; l[g] *= al;
; #pragma unroll
;             for (int nn = 0; nn < 4; ++nn) o[g][nn] = o[g][nn] * al;
;         }
;         const float mn = m[g]; float p[8], ps = 0.f;
; #pragma unroll
;         for (int e = 0; e < 8; ++e) { p[e] = ex2(sc[e] - mn); ps += p[e]; }
;         l[g] += ps;
;         const u32x4 pw = {pg8::cvt_pk_vis(p[0], p[1]), pg8::cvt_pk_vis(p[2], p[3]), pg8::cvt_pk_vis(p[4], p[5]), pg8::cvt_pk_vis(p[6], p[7])}; const bf16x8 pf = __builtin_bit_cast(bf16x8, pw);
; #pragma unroll
;         for (int nn = 0; nn < 4; ++nn) o[g][nn] = MFMA16(vf[nn], pf, o[g][nn]);
.LBB0_611:
	v_sub_f32_e32 v162, v169, v150
	v_exp_f32_e32 v169, v162
	v_sub_f32_e32 v162, v170, v150
	v_exp_f32_e32 v170, v162
	v_sub_f32_e32 v162, v171, v150
	v_exp_f32_e32 v171, v162
	v_sub_f32_e32 v162, v172, v150
	v_exp_f32_e32 v172, v162
	v_sub_f32_e32 v162, v173, v150
	v_exp_f32_e32 v173, v162
	v_sub_f32_e32 v162, v174, v150
	v_exp_f32_e32 v174, v162
	v_sub_f32_e32 v162, v175, v150
	v_exp_f32_e32 v175, v162
	v_sub_f32_e32 v162, v176, v150
	v_exp_f32_e32 v176, v162
	v_cvt_pk_bf16_f32 v178, v169, v170
	v_cvt_pk_bf16_f32 v179, v171, v172
	v_cvt_pk_bf16_f32 v180, v173, v174
	v_cvt_pk_bf16_f32 v181, v175, v176
	v_add_u32_e32 v162, 0x1804, v167
	ds_read2_b32 v[162:163], v162 offset1:1
	v_mfma_f32_16x16x32_bf16 v[100:103], v[116:119], v[178:181], v[100:103]
	v_mfma_f32_16x16x32_bf16 v[92:95], v[104:107], v[178:181], v[92:95]
	v_mfma_f32_16x16x32_bf16 v[88:91], v[108:111], v[178:181], v[88:91]
	v_mfma_f32_16x16x32_bf16 v[96:99], v[112:115], v[178:181], v[96:99]
	v_mfma_f32_16x16x32_bf16 v[178:181], v[36:39], v[8:11], 0
	v_mfma_f32_16x16x32_bf16 v[178:181], v[32:35], v[12:15], v[178:181]
	s_waitcnt lgkmcnt(0)
	s_nop 6
	v_fmamk_f32 v177, v178, 0x3e38aa3b, v162
	v_fmamk_f32 v178, v179, 0x3e38aa3b, v163
	v_add_u32_e32 v162, 0x180c, v167
	ds_read2_b32 v[162:163], v162 offset1:1
	v_max3_f32 v182, v177, s95, v178
	s_waitcnt lgkmcnt(0)
	v_fmamk_f32 v179, v180, 0x3e38aa3b, v162
	v_fmamk_f32 v180, v181, 0x3e38aa3b, v163
	v_max3_f32 v186, v182, v179, v180
	v_mfma_f32_16x16x32_bf16 v[182:185], v[28:31], v[8:11], 0
	v_add_u32_e32 v162, 0x1844, v167
	ds_read2_b32 v[162:163], v162 offset1:1
	v_mfma_f32_16x16x32_bf16 v[182:185], v[24:27], v[12:15], v[182:185]
	s_waitcnt lgkmcnt(0)
	s_nop 6
	v_fmamk_f32 v181, v182, 0x3e38aa3b, v162
	v_fmamk_f32 v182, v183, 0x3e38aa3b, v163
	v_add_u32_e32 v162, 0x184c, v167
	ds_read2_b32 v[162:163], v162 offset1:1
	v_max3_f32 v186, v186, v181, v182
	s_waitcnt lgkmcnt(0)
	v_fmamk_f32 v183, v184, 0x3e38aa3b, v162
	v_fmac_f32_e32 v163, 0x3e38aa3b, v185
	v_mov_b32_e32 v184, v163
	v_max3_f32 v185, v186, v183, v184
	v_sub_f32_e32 v162, v185, v143
	v_cmp_lt_f32_e32 vcc, s19, v162
	s_cbranch_vccz .LBB0_613
	ds_bpermute_b32 v162, v207, v185
	v_max_f32_e32 v163, v185, v185
	s_waitcnt lgkmcnt(0)
	v_max_f32_e32 v162, v162, v162
	v_max_f32_e32 v162, v163, v162
	ds_bpermute_b32 v163, v206, v162
	s_waitcnt lgkmcnt(0)
	v_max3_f32 v163, v143, v162, v163
	v_sub_f32_e32 v143, v143, v163
	v_exp_f32_e32 v162, v143
	v_mov_b32_e32 v143, v163
	v_mul_f32_e32 v154, v154, v162
	v_pk_mul_f32 v[78:79], v[78:79], v[162:163] op_sel_hi:[1,0]
	v_pk_mul_f32 v[76:77], v[76:77], v[162:163] op_sel_hi:[1,0]
	v_pk_mul_f32 v[74:75], v[74:75], v[162:163] op_sel_hi:[1,0]
	v_pk_mul_f32 v[72:73], v[72:73], v[162:163] op_sel_hi:[1,0]
	v_pk_mul_f32 v[82:83], v[82:83], v[162:163] op_sel_hi:[1,0]
	v_pk_mul_f32 v[80:81], v[80:81], v[162:163] op_sel_hi:[1,0]
	v_pk_mul_f32 v[86:87], v[86:87], v[162:163] op_sel_hi:[1,0]
	v_pk_mul_f32 v[84:85], v[84:85], v[162:163] op_sel_hi:[1,0]
.LBB0_613:
	v_sub_f32_e32 v162, v177, v143
	v_exp_f32_e32 v177, v162
	v_sub_f32_e32 v162, v178, v143
	v_exp_f32_e32 v178, v162
	v_sub_f32_e32 v162, v179, v143
	v_exp_f32_e32 v179, v162
	v_sub_f32_e32 v162, v180, v143
	v_exp_f32_e32 v180, v162
	v_sub_f32_e32 v162, v181, v143
	v_exp_f32_e32 v181, v162
	v_sub_f32_e32 v162, v182, v143
	v_mfma_f32_16x16x32_bf16 v[36:39], v[36:39], v[4:7], 0
	v_exp_f32_e32 v182, v162
	v_sub_f32_e32 v162, v183, v143
	v_exp_f32_e32 v183, v162
	v_sub_f32_e32 v162, v184, v143
	v_exp_f32_e32 v184, v162
	v_add_u32_e32 v162, 0x1c08, v167
	v_mfma_f32_16x16x32_bf16 v[32:35], v[32:35], v[0:3], v[36:39]
	v_cvt_pk_bf16_f32 v186, v177, v178
	v_cvt_pk_bf16_f32 v187, v179, v180
	v_cvt_pk_bf16_f32 v188, v181, v182
	ds_read2_b32 v[36:37], v162 offset1:1
	v_cvt_pk_bf16_f32 v189, v183, v184
	v_add_u32_e32 v38, 0x1c10, v167
	v_add_u32_e32 v39, 0x1c48, v167
	v_mfma_f32_16x16x32_bf16 v[76:79], v[116:119], v[186:189], v[76:79]
	s_waitcnt lgkmcnt(0)
	v_fmamk_f32 v33, v33, 0x3e38aa3b, v37
	v_add_u32_e32 v167, 0x1c50, v167
	v_fmamk_f32 v32, v32, 0x3e38aa3b, v36
	v_mfma_f32_16x16x32_bf16 v[72:75], v[104:107], v[186:189], v[72:75]
	v_mfma_f32_16x16x32_bf16 v[80:83], v[108:111], v[186:189], v[80:83]
	v_mfma_f32_16x16x32_bf16 v[84:87], v[112:115], v[186:189], v[84:87]
	ds_read2_b32 v[162:163], v38 offset1:1
	ds_read2_b32 v[186:187], v39 offset1:1
	ds_read2_b32 v[188:189], v167 offset1:1
	v_max3_f32 v167, v32, s95, v33
	s_waitcnt lgkmcnt(2)
	v_fmamk_f32 v34, v34, 0x3e38aa3b, v162
	v_mfma_f32_16x16x32_bf16 v[36:39], v[28:31], v[4:7], 0
	v_fmac_f32_e32 v163, 0x3e38aa3b, v35
	v_mov_b32_e32 v28, v163
	v_mfma_f32_16x16x32_bf16 v[24:27], v[24:27], v[0:3], v[36:39]
	v_max3_f32 v29, v167, v34, v28
	s_waitcnt lgkmcnt(1)
	s_nop 5
	v_fmamk_f32 v24, v24, 0x3e38aa3b, v186
	v_fmac_f32_e32 v187, 0x3e38aa3b, v25
	v_mov_b32_e32 v25, v187
	s_waitcnt lgkmcnt(0)
	v_fmamk_f32 v26, v26, 0x3e38aa3b, v188
	v_fmac_f32_e32 v189, 0x3e38aa3b, v27
	v_max3_f32 v29, v29, v24, v25
	v_mov_b32_e32 v27, v189
	v_max3_f32 v29, v29, v26, v27
	v_sub_f32_e32 v30, v29, v151
	v_cmp_lt_f32_e32 vcc, s19, v30
	s_cbranch_vccz .LBB0_615
	ds_bpermute_b32 v30, v207, v29
	v_max_f32_e32 v29, v29, v29
	s_waitcnt lgkmcnt(0)
	v_max_f32_e32 v30, v30, v30
	v_max_f32_e32 v29, v29, v30
	ds_bpermute_b32 v30, v206, v29
	s_waitcnt lgkmcnt(0)
	v_max3_f32 v29, v151, v29, v30
	v_sub_f32_e32 v30, v151, v29
	v_exp_f32_e32 v30, v30
	v_mov_b32_e32 v151, v29
	v_mul_f32_e32 v152, v152, v30
	v_pk_mul_f32 v[62:63], v[62:63], v[30:31] op_sel_hi:[1,0]
	v_pk_mul_f32 v[60:61], v[60:61], v[30:31] op_sel_hi:[1,0]
	v_pk_mul_f32 v[50:51], v[50:51], v[30:31] op_sel_hi:[1,0]
	v_pk_mul_f32 v[48:49], v[48:49], v[30:31] op_sel_hi:[1,0]
	v_pk_mul_f32 v[46:47], v[46:47], v[30:31] op_sel_hi:[1,0]
	v_pk_mul_f32 v[44:45], v[44:45], v[30:31] op_sel_hi:[1,0]
	v_pk_mul_f32 v[42:43], v[42:43], v[30:31] op_sel_hi:[1,0]
	v_pk_mul_f32 v[40:41], v[40:41], v[30:31] op_sel_hi:[1,0]

; #define PG8_STAGE(bufoff, gbase, voff) do { _Pragma("unroll") for (int _i = 0; _i < 2; ++_i) \
;         __builtin_amdgcn_global_load_lds((const unsigned*)((const char*)(gbase) + (voff)[_i]), (PG8_LAS unsigned*)(lds + (bufoff) + ldsw + _i * 8192), 16, 0, 0); } while (0)
; #define PG8_LDA(dst, b, h) do { _Pragma("unroll") for (int m = 0; m < 4; ++m) _Pragma("unroll") for (int k = 0; k < 2; ++k) dst[m][k] = *(const PG8_LAS bf16x8*)(lds + PG8_SA(b, h) + aoff + m * 2048 + k * 1024); } while (0)
; #define PG8_LDB(dst, b, h) do { _Pragma("unroll") for (int n = 0; n < 2; ++n) _Pragma("unroll") for (int k = 0; k < 2; ++k) dst[n][k] = *(const PG8_LAS bf16x8*)(lds + PG8_SB(b, h) + boff + n * 2048 + k * 1024); } while (0)
; #define PG8_MMA(ai, bj, At, Bt) do { __builtin_amdgcn_s_setprio(1); _Pragma("unroll") for (int m = 0; m < 4; ++m) _Pragma("unroll") for (int n = 0; n < 2; ++n) _Pragma("unroll") for (int k = 0; k < 2; ++k) \
;         acc[ai][bj][m][n] = __builtin_amdgcn_mfma_f32_16x16x32_bf16(Bt[n][k], At[m][k], acc[ai][bj][m][n], 0, 0, 0); __builtin_amdgcn_s_setprio(0); } while (0)
; #define PG8_WAIT_V(n) asm volatile("s_waitcnt vmcnt(" #n ")" ::: "memory")
; #define PG8_WAIT_L(n) asm volatile("s_waitcnt lgkmcnt(" #n ")" ::: "memory")
; #define PG8_BAR __builtin_amdgcn_s_barrier()
; #define PG8_SCHED __builtin_amdgcn_sched_barrier(0)
; template <class Epi, class Sched, bool ALIGN_EPI = false, bool SP2 = false>
; __device__ __forceinline__ void gemm_phase(PG8_LAS unsigned char* lds, const Gemm g, const Sched& S, const Epi& E, int tid_in) {
;     ...
;             PG8_LDB(B0, 0, 0); PG8_LDB(B1, 0, 1); PG8_SCHED; PG8_LDA(At, 0, 0); PG8_STAGE(PG8_SA(1, 1), a1 + hstep, voffA);
;             PG8_WAIT_V(8); PG8_WAIT_L(0); PG8_BAR; PG8_MMA(0, 0, At, B0); PG8_MMA(0, 1, At, B1); PG8_BAR; PG8_SCHED;
;             PG8_LDA(At, 0, 1); PG8_STAGE(PG8_SB(0, 0), b2, voffB); PG8_STAGE(PG8_SB(0, 1), b2 + hstep, voffB); PG8_STAGE(PG8_SA(0, 0), a2, voffA);
;             PG8_WAIT_V(8); PG8_WAIT_L(0); PG8_BAR; PG8_MMA(1, 0, At, B0); PG8_MMA(1, 1, At, B1); PG8_BAR; PG8_SCHED;
.Lpeel_enter_g2:
	s_add_u32 s0, s0, 0x80
	s_addc_u32 s1, s1, 0
	s_add_u32 s63, s22, 0x100
	s_addc_u32 vcc_lo, s23, 0
	s_mov_b32 s22, 0
	s_add_i32 s36, s22, 2
	s_add_u32 s2, s0, 0x80
	s_addc_u32 s3, s1, 0
	s_add_i32 s37, 0, 0x10000
	s_cmp_eq_u32 s90, s22
	s_cselect_b32 s23, s9, s3
	s_cselect_b32 s22, s8, s2
	s_cselect_b32 s3, s55, vcc_lo
	s_cselect_b32 s2, s54, s63
	s_add_i32 vcc_hi, 0, 0x14000
	v_add_u32_e32 v146, s37, v237
	v_add_u32_e32 v154, vcc_hi, v237
	ds_read_b128 v[134:137], v146
	ds_read_b128 v[138:141], v146 offset:1024
	ds_read_b128 v[142:145], v146 offset:2048
	ds_read_b128 v[146:149], v146 offset:3072
	ds_read_b128 v[150:153], v154
	ds_read_b128 v[166:169], v154 offset:1024
	ds_read_b128 v[170:173], v154 offset:2048
	ds_read_b128 v[174:177], v154 offset:3072
	v_lshl_add_u64 v[154:155], s[0:1], 0, v[130:131]
	s_add_i32 m0, s47, 0xc000
	ds_read_b128 v[178:181], v241
	ds_read_b128 v[182:185], v241 offset:1024
	ds_read_b128 v[186:189], v241 offset:2048
	ds_read_b128 v[190:193], v241 offset:3072
	ds_read_b128 v[194:197], v241 offset:4096
	ds_read_b128 v[198:201], v241 offset:5120
	ds_read_b128 v[202:205], v241 offset:6144
	ds_read_b128 v[206:209], v241 offset:7168
	global_load_lds_dwordx4 v[154:155], off
	v_lshl_add_u64 v[154:155], s[0:1], 0, v[132:133]
	s_add_i32 m0, s47, 0xe000
	s_nop 0
	global_load_lds_dwordx4 v[154:155], off
	s_waitcnt vmcnt(8)
	s_waitcnt lgkmcnt(0)
	s_barrier
	s_waitcnt lgkmcnt(0)
	v_mfma_f32_16x16x32_bf16 v[124:127], v[134:137], v[178:181], 0
	v_mfma_f32_16x16x32_bf16 v[120:123], v[142:145], v[178:181], 0
	v_mfma_f32_16x16x32_bf16 v[108:111], v[134:137], v[186:189], 0
	v_mfma_f32_16x16x32_bf16 v[104:107], v[142:145], v[186:189], 0
	v_mfma_f32_16x16x32_bf16 v[92:95], v[134:137], v[194:197], 0
	v_mfma_f32_16x16x32_bf16 v[88:91], v[142:145], v[194:197], 0
	v_mfma_f32_16x16x32_bf16 v[76:79], v[134:137], v[202:205], 0
	v_mfma_f32_16x16x32_bf16 v[72:75], v[142:145], v[202:205], 0
	v_mfma_f32_16x16x32_bf16 v[124:127], v[138:141], v[182:185], v[124:127]
	v_mfma_f32_16x16x32_bf16 v[120:123], v[146:149], v[182:185], v[120:123]
	v_mfma_f32_16x16x32_bf16 v[108:111], v[138:141], v[190:193], v[108:111]
	v_mfma_f32_16x16x32_bf16 v[104:107], v[146:149], v[190:193], v[104:107]
	v_mfma_f32_16x16x32_bf16 v[92:95], v[138:141], v[198:201], v[92:95]
	v_mfma_f32_16x16x32_bf16 v[88:91], v[146:149], v[198:201], v[88:91]
	v_mfma_f32_16x16x32_bf16 v[76:79], v[138:141], v[206:209], v[76:79]
	v_mfma_f32_16x16x32_bf16 v[72:75], v[146:149], v[206:209], v[72:75]
	v_mfma_f32_16x16x32_bf16 v[116:119], v[150:153], v[178:181], 0
	v_mfma_f32_16x16x32_bf16 v[112:115], v[170:173], v[178:181], 0
	v_mfma_f32_16x16x32_bf16 v[100:103], v[150:153], v[186:189], 0
	v_mfma_f32_16x16x32_bf16 v[96:99], v[170:173], v[186:189], 0
	v_mfma_f32_16x16x32_bf16 v[84:87], v[150:153], v[194:197], 0
	v_mfma_f32_16x16x32_bf16 v[80:83], v[170:173], v[194:197], 0
	v_mfma_f32_16x16x32_bf16 v[68:71], v[150:153], v[202:205], 0
	v_mfma_f32_16x16x32_bf16 v[64:67], v[170:173], v[202:205], 0
	v_mfma_f32_16x16x32_bf16 v[116:119], v[166:169], v[182:185], v[116:119]
	v_mfma_f32_16x16x32_bf16 v[112:115], v[174:177], v[182:185], v[112:115]
	v_mfma_f32_16x16x32_bf16 v[100:103], v[166:169], v[190:193], v[100:103]
	v_mfma_f32_16x16x32_bf16 v[96:99], v[174:177], v[190:193], v[96:99]
	v_mfma_f32_16x16x32_bf16 v[84:87], v[166:169], v[198:201], v[84:87]
	v_mfma_f32_16x16x32_bf16 v[80:83], v[174:177], v[198:201], v[80:83]
	v_mfma_f32_16x16x32_bf16 v[68:71], v[166:169], v[206:209], v[68:71]
	v_mfma_f32_16x16x32_bf16 v[64:67], v[174:177], v[206:209], v[64:67]
	s_barrier
	s_add_i32 s37, s37, s46
	v_lshl_add_u64 v[154:155], s[2:3], 0, v[156:157]
	s_mov_b32 m0, s37
	ds_read_b128 v[178:181], v241 offset:16384
	ds_read_b128 v[182:185], v241 offset:17408
	ds_read_b128 v[186:189], v241 offset:18432
	ds_read_b128 v[190:193], v241 offset:19456
	ds_read_b128 v[194:197], v241 offset:20480
	ds_read_b128 v[198:201], v241 offset:21504
	ds_read_b128 v[202:205], v241 offset:22528
	ds_read_b128 v[206:209], v241 offset:23552
	global_load_lds_dwordx4 v[154:155], off
	s_add_i32 m0, s37, 0x2000
	v_lshl_add_u64 v[162:163], s[2:3], 0, v[128:129]
	s_add_u32 s2, s2, s12
	s_addc_u32 s3, s3, s13
	s_add_i32 s37, vcc_hi, s46
	global_load_lds_dwordx4 v[162:163], off
	v_lshl_add_u64 v[210:211], s[2:3], 0, v[156:157]
	s_mov_b32 m0, s37
	v_lshl_add_u64 v[212:213], s[2:3], 0, v[128:129]
	global_load_lds_dwordx4 v[210:211], off
	s_add_i32 m0, s37, 0x2000
	v_lshl_add_u64 v[214:215], s[22:23], 0, v[156:157]
	global_load_lds_dwordx4 v[212:213], off
	s_mov_b32 m0, s47
	v_lshl_add_u64 v[216:217], s[22:23], 0, v[128:129]
	global_load_lds_dwordx4 v[214:215], off
	s_mov_b32 m0, s52
	s_nop 0
	global_load_lds_dwordx4 v[216:217], off
	s_waitcnt vmcnt(8)
	s_waitcnt lgkmcnt(0)
	s_barrier
; #define PG8_STAGE(bufoff, gbase, voff) do { _Pragma("unroll") for (int _i = 0; _i < 2; ++_i) \
;         __builtin_amdgcn_global_load_lds((const unsigned*)((const char*)(gbase) + (voff)[_i]), (PG8_LAS unsigned*)(lds + (bufoff) + ldsw + _i * 8192), 16, 0, 0); } while (0)
; #define PG8_LDA(dst, b, h) do { _Pragma("unroll") for (int m = 0; m < 4; ++m) _Pragma("unroll") for (int k = 0; k < 2; ++k) dst[m][k] = *(const PG8_LAS bf16x8*)(lds + PG8_SA(b, h) + aoff + m * 2048 + k * 1024); } while (0)
; #define PG8_LDB(dst, b, h) do { _Pragma("unroll") for (int n = 0; n < 2; ++n) _Pragma("unroll") for (int k = 0; k < 2; ++k) dst[n][k] = *(const PG8_LAS bf16x8*)(lds + PG8_SB(b, h) + boff + n * 2048 + k * 1024); } while (0)
; #define PG8_MMA(ai, bj, At, Bt) do { __builtin_amdgcn_s_setprio(1); _Pragma("unroll") for (int m = 0; m < 4; ++m) _Pragma("unroll") for (int n = 0; n < 2; ++n) _Pragma("unroll") for (int k = 0; k < 2; ++k) \
;         acc[ai][bj][m][n] = __builtin_amdgcn_mfma_f32_16x16x32_bf16(Bt[n][k], At[m][k], acc[ai][bj][m][n], 0, 0, 0); __builtin_amdgcn_s_setprio(0); } while (0)
; #define PG8_WAIT_V(n) asm volatile("s_waitcnt vmcnt(" #n ")" ::: "memory")
; #define PG8_WAIT_L(n) asm volatile("s_waitcnt lgkmcnt(" #n ")" ::: "memory")
; #define PG8_BAR __builtin_amdgcn_s_barrier()
; #define PG8_SCHED __builtin_amdgcn_sched_barrier(0)
; template <class Epi, class Sched, bool ALIGN_EPI = false, bool SP2 = false>
; __device__ __forceinline__ void gemm_phase(PG8_LAS unsigned char* lds, const Gemm g, const Sched& S, const Epi& E, int tid_in) {
;     ...
;             PG8_WAIT_V(8); PG8_WAIT_L(0); PG8_BAR; PG8_MMA(1, 0, At, B0); PG8_MMA(1, 1, At, B1); PG8_BAR; PG8_SCHED;
;             PG8_LDB(B0, 1, 0); PG8_LDB(B1, 1, 1); PG8_SCHED; PG8_LDA(At, 1, 0); PG8_STAGE(PG8_SA(0, 1), a2 + hstep, voffA);
;             PG8_WAIT_V(8); PG8_WAIT_L(0); PG8_BAR; PG8_MMA(0, 0, At, B0); PG8_MMA(0, 1, At, B1); PG8_BAR; PG8_SCHED;
;             PG8_LDA(At, 1, 1); PG8_STAGE(PG8_SB(1, 0), b3, voffB); PG8_STAGE(PG8_SB(1, 1), b3 + hstep, voffB); PG8_STAGE(PG8_SA(1, 0), a3, voffA);
;             PG8_WAIT_V(8); PG8_WAIT_L(0); PG8_BAR; PG8_MMA(1, 0, At, B0); PG8_MMA(1, 1, At, B1); PG8_BAR; PG8_SCHED;
	s_waitcnt lgkmcnt(0)
	v_mfma_f32_16x16x32_bf16 v[60:63], v[134:137], v[178:181], 0
	v_mfma_f32_16x16x32_bf16 v[56:59], v[142:145], v[178:181], 0
	v_mfma_f32_16x16x32_bf16 v[44:47], v[134:137], v[186:189], 0
	v_mfma_f32_16x16x32_bf16 v[40:43], v[142:145], v[186:189], 0
	v_mfma_f32_16x16x32_bf16 v[28:31], v[134:137], v[194:197], 0
	v_mfma_f32_16x16x32_bf16 v[24:27], v[142:145], v[194:197], 0
	v_mfma_f32_16x16x32_bf16 v[12:15], v[134:137], v[202:205], 0
	v_mfma_f32_16x16x32_bf16 v[8:11], v[142:145], v[202:205], 0
	v_mfma_f32_16x16x32_bf16 v[60:63], v[138:141], v[182:185], v[60:63]
	v_mfma_f32_16x16x32_bf16 v[56:59], v[146:149], v[182:185], v[56:59]
	v_mfma_f32_16x16x32_bf16 v[44:47], v[138:141], v[190:193], v[44:47]
	v_mfma_f32_16x16x32_bf16 v[40:43], v[146:149], v[190:193], v[40:43]
	v_mfma_f32_16x16x32_bf16 v[28:31], v[138:141], v[198:201], v[28:31]
	v_mfma_f32_16x16x32_bf16 v[24:27], v[146:149], v[198:201], v[24:27]
	v_mfma_f32_16x16x32_bf16 v[12:15], v[138:141], v[206:209], v[12:15]
	v_mfma_f32_16x16x32_bf16 v[8:11], v[146:149], v[206:209], v[8:11]
	v_mfma_f32_16x16x32_bf16 v[52:55], v[150:153], v[178:181], 0
	v_mfma_f32_16x16x32_bf16 v[48:51], v[170:173], v[178:181], 0
	v_mfma_f32_16x16x32_bf16 v[36:39], v[150:153], v[186:189], 0
	v_mfma_f32_16x16x32_bf16 v[32:35], v[170:173], v[186:189], 0
	v_mfma_f32_16x16x32_bf16 v[20:23], v[150:153], v[194:197], 0
	v_mfma_f32_16x16x32_bf16 v[16:19], v[170:173], v[194:197], 0
	v_mfma_f32_16x16x32_bf16 v[4:7], v[150:153], v[202:205], 0
	v_mfma_f32_16x16x32_bf16 v[0:3], v[170:173], v[202:205], 0
	v_mfma_f32_16x16x32_bf16 v[52:55], v[166:169], v[182:185], v[52:55]
	v_mfma_f32_16x16x32_bf16 v[48:51], v[174:177], v[182:185], v[48:51]
	v_mfma_f32_16x16x32_bf16 v[36:39], v[166:169], v[190:193], v[36:39]
	v_mfma_f32_16x16x32_bf16 v[32:35], v[174:177], v[190:193], v[32:35]
	v_mfma_f32_16x16x32_bf16 v[20:23], v[166:169], v[198:201], v[20:23]
	v_mfma_f32_16x16x32_bf16 v[16:19], v[174:177], v[198:201], v[16:19]
	v_mfma_f32_16x16x32_bf16 v[4:7], v[166:169], v[206:209], v[4:7]
	v_mfma_f32_16x16x32_bf16 v[0:3], v[174:177], v[206:209], v[0:3]
	s_barrier
	s_add_i32 s37, 0, 0x18000
	s_add_i32 vcc_hi, 0, 0x1c000
	v_add_u32_e32 v146, s37, v237
	v_add_u32_e32 v174, vcc_hi, v237
	ds_read_b128 v[134:137], v146
	ds_read_b128 v[138:141], v146 offset:1024
	ds_read_b128 v[142:145], v146 offset:2048
	ds_read_b128 v[146:149], v146 offset:3072
	ds_read_b128 v[150:153], v174
	ds_read_b128 v[166:169], v174 offset:1024
	ds_read_b128 v[170:173], v174 offset:2048
	ds_read_b128 v[174:177], v174 offset:3072
	s_add_u32 s2, s22, s12
	s_addc_u32 s3, s23, s13
	s_mov_b32 m0, s53
	v_lshl_add_u64 v[218:219], s[2:3], 0, v[156:157]
	ds_read_b128 v[178:181], v241 offset:32768
	ds_read_b128 v[182:185], v241 offset:33792
	ds_read_b128 v[186:189], v241 offset:34816
	ds_read_b128 v[190:193], v241 offset:35840
	ds_read_b128 v[194:197], v241 offset:36864
	ds_read_b128 v[198:201], v241 offset:37888
	ds_read_b128 v[202:205], v241 offset:38912
	ds_read_b128 v[206:209], v241 offset:39936
	global_load_lds_dwordx4 v[218:219], off
	v_lshl_add_u64 v[218:219], s[2:3], 0, v[128:129]
	s_mov_b32 m0, s56
	s_nop 0
	global_load_lds_dwordx4 v[218:219], off
	s_waitcnt vmcnt(8)
	s_waitcnt lgkmcnt(0)
	s_barrier
	s_waitcnt lgkmcnt(0)
	v_mfma_f32_16x16x32_bf16 v[124:127], v[134:137], v[178:181], v[124:127]
	v_mfma_f32_16x16x32_bf16 v[120:123], v[142:145], v[178:181], v[120:123]
	v_mfma_f32_16x16x32_bf16 v[108:111], v[134:137], v[186:189], v[108:111]
	v_mfma_f32_16x16x32_bf16 v[104:107], v[142:145], v[186:189], v[104:107]
	v_mfma_f32_16x16x32_bf16 v[92:95], v[134:137], v[194:197], v[92:95]
	v_mfma_f32_16x16x32_bf16 v[88:91], v[142:145], v[194:197], v[88:91]
	v_mfma_f32_16x16x32_bf16 v[76:79], v[134:137], v[202:205], v[76:79]
	v_mfma_f32_16x16x32_bf16 v[72:75], v[142:145], v[202:205], v[72:75]
	v_mfma_f32_16x16x32_bf16 v[124:127], v[138:141], v[182:185], v[124:127]
	v_mfma_f32_16x16x32_bf16 v[120:123], v[146:149], v[182:185], v[120:123]
	v_mfma_f32_16x16x32_bf16 v[108:111], v[138:141], v[190:193], v[108:111]
	v_mfma_f32_16x16x32_bf16 v[104:107], v[146:149], v[190:193], v[104:107]
	v_mfma_f32_16x16x32_bf16 v[92:95], v[138:141], v[198:201], v[92:95]
	v_mfma_f32_16x16x32_bf16 v[88:91], v[146:149], v[198:201], v[88:91]
	v_mfma_f32_16x16x32_bf16 v[76:79], v[138:141], v[206:209], v[76:79]
	v_mfma_f32_16x16x32_bf16 v[72:75], v[146:149], v[206:209], v[72:75]
	v_mfma_f32_16x16x32_bf16 v[116:119], v[150:153], v[178:181], v[116:119]
	v_mfma_f32_16x16x32_bf16 v[112:115], v[170:173], v[178:181], v[112:115]
	v_mfma_f32_16x16x32_bf16 v[100:103], v[150:153], v[186:189], v[100:103]
	v_mfma_f32_16x16x32_bf16 v[96:99], v[170:173], v[186:189], v[96:99]
	v_mfma_f32_16x16x32_bf16 v[84:87], v[150:153], v[194:197], v[84:87]
	v_mfma_f32_16x16x32_bf16 v[80:83], v[170:173], v[194:197], v[80:83]
	v_mfma_f32_16x16x32_bf16 v[68:71], v[150:153], v[202:205], v[68:71]
	v_mfma_f32_16x16x32_bf16 v[64:67], v[170:173], v[202:205], v[64:67]
	v_mfma_f32_16x16x32_bf16 v[116:119], v[166:169], v[182:185], v[116:119]
	v_mfma_f32_16x16x32_bf16 v[112:115], v[174:177], v[182:185], v[112:115]
	v_mfma_f32_16x16x32_bf16 v[100:103], v[166:169], v[190:193], v[100:103]
	v_mfma_f32_16x16x32_bf16 v[96:99], v[174:177], v[190:193], v[96:99]
	v_mfma_f32_16x16x32_bf16 v[84:87], v[166:169], v[198:201], v[84:87]
	v_mfma_f32_16x16x32_bf16 v[80:83], v[174:177], v[198:201], v[80:83]
	v_mfma_f32_16x16x32_bf16 v[68:71], v[166:169], v[206:209], v[68:71]
	v_mfma_f32_16x16x32_bf16 v[64:67], v[174:177], v[206:209], v[64:67]
	s_barrier
; #define PG8_STAGE(bufoff, gbase, voff) do { _Pragma("unroll") for (int _i = 0; _i < 2; ++_i) \
;         __builtin_amdgcn_global_load_lds((const unsigned*)((const char*)(gbase) + (voff)[_i]), (PG8_LAS unsigned*)(lds + (bufoff) + ldsw + _i * 8192), 16, 0, 0); } while (0)
; #define PG8_LDA(dst, b, h) do { _Pragma("unroll") for (int m = 0; m < 4; ++m) _Pragma("unroll") for (int k = 0; k < 2; ++k) dst[m][k] = *(const PG8_LAS bf16x8*)(lds + PG8_SA(b, h) + aoff + m * 2048 + k * 1024); } while (0)
; #define PG8_MMA(ai, bj, At, Bt) do { __builtin_amdgcn_s_setprio(1); _Pragma("unroll") for (int m = 0; m < 4; ++m) _Pragma("unroll") for (int n = 0; n < 2; ++n) _Pragma("unroll") for (int k = 0; k < 2; ++k) \
;         acc[ai][bj][m][n] = __builtin_amdgcn_mfma_f32_16x16x32_bf16(Bt[n][k], At[m][k], acc[ai][bj][m][n], 0, 0, 0); __builtin_amdgcn_s_setprio(0); } while (0)
; #define PG8_WAIT_V(n) asm volatile("s_waitcnt vmcnt(" #n ")" ::: "memory")
; #define PG8_WAIT_L(n) asm volatile("s_waitcnt lgkmcnt(" #n ")" ::: "memory")
; #define PG8_BAR __builtin_amdgcn_s_barrier()
; #define PG8_SCHED __builtin_amdgcn_sched_barrier(0)
; template <class Epi, class Sched, bool ALIGN_EPI = false, bool SP2 = false>
; __device__ __forceinline__ void gemm_phase(PG8_LAS unsigned char* lds, const Gemm g, const Sched& S, const Epi& E, int tid_in) {
;     ...
;         for (int t = 0; t < nt; t += 2) {
;     ...
;             PG8_WAIT_V(8); PG8_WAIT_L(0); PG8_BAR; PG8_MMA(0, 0, At, B0); PG8_MMA(0, 1, At, B1); PG8_BAR; PG8_SCHED;
;             PG8_LDA(At, 1, 1); PG8_STAGE(PG8_SB(1, 0), b3, voffB); PG8_STAGE(PG8_SB(1, 1), b3 + hstep, voffB); PG8_STAGE(PG8_SA(1, 0), a3, voffA);
;             PG8_WAIT_V(8); PG8_WAIT_L(0); PG8_BAR; PG8_MMA(1, 0, At, B0); PG8_MMA(1, 1, At, B1); PG8_BAR; PG8_SCHED;
	s_add_i32 s2, s37, s46
	v_lshl_add_u64 v[154:155], v[154:155], 0, s[64:65]
	s_mov_b32 m0, s2
	ds_read_b128 v[178:181], v241 offset:49152
	ds_read_b128 v[182:185], v241 offset:50176
	ds_read_b128 v[186:189], v241 offset:51200
	ds_read_b128 v[190:193], v241 offset:52224
	ds_read_b128 v[194:197], v241 offset:53248
	ds_read_b128 v[198:201], v241 offset:54272
	ds_read_b128 v[202:205], v241 offset:55296
	ds_read_b128 v[206:209], v241 offset:56320
	global_load_lds_dwordx4 v[154:155], off
	v_lshl_add_u64 v[154:155], v[162:163], 0, s[64:65]
	s_add_i32 m0, s2, 0x2000
	s_add_i32 s2, vcc_hi, s46
	global_load_lds_dwordx4 v[154:155], off
	v_lshl_add_u64 v[154:155], v[210:211], 0, s[64:65]
	s_mov_b32 m0, s2
	s_nop 0
	global_load_lds_dwordx4 v[154:155], off
	v_lshl_add_u64 v[154:155], v[212:213], 0, s[64:65]
	s_add_i32 m0, s2, 0x2000
	s_nop 0
	global_load_lds_dwordx4 v[154:155], off
	v_lshl_add_u64 v[154:155], v[214:215], 0, s[64:65]
	s_mov_b32 m0, s88
	s_nop 0
	global_load_lds_dwordx4 v[154:155], off
	v_lshl_add_u64 v[154:155], v[216:217], 0, s[64:65]
	s_mov_b32 m0, s89
	s_nop 0
	global_load_lds_dwordx4 v[154:155], off
	s_waitcnt vmcnt(8)
	s_waitcnt lgkmcnt(0)
	s_barrier
	s_waitcnt lgkmcnt(0)
	v_mfma_f32_16x16x32_bf16 v[60:63], v[134:137], v[178:181], v[60:63]
	v_mfma_f32_16x16x32_bf16 v[56:59], v[142:145], v[178:181], v[56:59]
	v_mfma_f32_16x16x32_bf16 v[44:47], v[134:137], v[186:189], v[44:47]
	v_mfma_f32_16x16x32_bf16 v[40:43], v[142:145], v[186:189], v[40:43]
	v_mfma_f32_16x16x32_bf16 v[28:31], v[134:137], v[194:197], v[28:31]
	v_mfma_f32_16x16x32_bf16 v[24:27], v[142:145], v[194:197], v[24:27]
	v_mfma_f32_16x16x32_bf16 v[12:15], v[134:137], v[202:205], v[12:15]
	v_mfma_f32_16x16x32_bf16 v[8:11], v[142:145], v[202:205], v[8:11]
	v_mfma_f32_16x16x32_bf16 v[60:63], v[138:141], v[182:185], v[60:63]
	v_mfma_f32_16x16x32_bf16 v[56:59], v[146:149], v[182:185], v[56:59]
	v_mfma_f32_16x16x32_bf16 v[44:47], v[138:141], v[190:193], v[44:47]
	v_mfma_f32_16x16x32_bf16 v[40:43], v[146:149], v[190:193], v[40:43]
	v_mfma_f32_16x16x32_bf16 v[28:31], v[138:141], v[198:201], v[28:31]
	v_mfma_f32_16x16x32_bf16 v[24:27], v[146:149], v[198:201], v[24:27]
	v_mfma_f32_16x16x32_bf16 v[12:15], v[138:141], v[206:209], v[12:15]
	v_mfma_f32_16x16x32_bf16 v[8:11], v[146:149], v[206:209], v[8:11]
	v_mfma_f32_16x16x32_bf16 v[52:55], v[150:153], v[178:181], v[52:55]
	v_mfma_f32_16x16x32_bf16 v[48:51], v[170:173], v[178:181], v[48:51]
	v_mfma_f32_16x16x32_bf16 v[36:39], v[150:153], v[186:189], v[36:39]
	v_mfma_f32_16x16x32_bf16 v[32:35], v[170:173], v[186:189], v[32:35]
	v_mfma_f32_16x16x32_bf16 v[20:23], v[150:153], v[194:197], v[20:23]
	v_mfma_f32_16x16x32_bf16 v[16:19], v[170:173], v[194:197], v[16:19]
	v_mfma_f32_16x16x32_bf16 v[4:7], v[150:153], v[202:205], v[4:7]
	v_mfma_f32_16x16x32_bf16 v[0:3], v[170:173], v[202:205], v[0:3]
	v_mfma_f32_16x16x32_bf16 v[52:55], v[166:169], v[182:185], v[52:55]
	v_mfma_f32_16x16x32_bf16 v[48:51], v[174:177], v[182:185], v[48:51]
	s_add_u32 s0, s0, 0x100
	v_mfma_f32_16x16x32_bf16 v[36:39], v[166:169], v[190:193], v[36:39]
	s_addc_u32 s1, s1, 0
	v_mfma_f32_16x16x32_bf16 v[32:35], v[174:177], v[190:193], v[32:35]
	s_add_u32 s63, s63, 0x100
	v_mfma_f32_16x16x32_bf16 v[20:23], v[166:169], v[198:201], v[20:23]
	s_addc_u32 vcc_lo, vcc_lo, 0
	v_mfma_f32_16x16x32_bf16 v[16:19], v[174:177], v[198:201], v[16:19]
	s_cmp_ge_i32 s36, s67
	v_mfma_f32_16x16x32_bf16 v[4:7], v[166:169], v[206:209], v[4:7]
	s_mov_b32 s22, s36
	v_mfma_f32_16x16x32_bf16 v[0:3], v[174:177], v[206:209], v[0:3]
	s_barrier
	s_cbranch_scc0 .LBB0_820
	s_branch .Lpeel_exit_g2
.LBB0_820:
	s_add_i32 s36, s22, 2
	s_add_u32 s2, s0, 0x80
	s_addc_u32 s3, s1, 0
	s_add_i32 s37, 0, 0x10000
	s_cmp_eq_u32 s90, s22
	s_cselect_b32 s23, s9, s3
	s_cselect_b32 s22, s8, s2
	s_cselect_b32 s3, s55, vcc_lo
	s_cselect_b32 s2, s54, s63
	s_add_i32 vcc_hi, 0, 0x14000
	v_add_u32_e32 v146, s37, v237
	v_add_u32_e32 v154, vcc_hi, v237
	ds_read_b128 v[134:137], v146
	ds_read_b128 v[138:141], v146 offset:1024
	ds_read_b128 v[142:145], v146 offset:2048
	ds_read_b128 v[146:149], v146 offset:3072
	ds_read_b128 v[150:153], v154
	ds_read_b128 v[166:169], v154 offset:1024
	ds_read_b128 v[170:173], v154 offset:2048
	ds_read_b128 v[174:177], v154 offset:3072
	v_lshl_add_u64 v[154:155], s[0:1], 0, v[130:131]
	s_add_i32 m0, s47, 0xc000
	ds_read_b128 v[178:181], v241
	ds_read_b128 v[182:185], v241 offset:1024
	ds_read_b128 v[186:189], v241 offset:2048
	ds_read_b128 v[190:193], v241 offset:3072
	ds_read_b128 v[194:197], v241 offset:4096
	ds_read_b128 v[198:201], v241 offset:5120
	ds_read_b128 v[202:205], v241 offset:6144
	ds_read_b128 v[206:209], v241 offset:7168
	global_load_lds_dwordx4 v[154:155], off
	v_lshl_add_u64 v[154:155], s[0:1], 0, v[132:133]
	s_add_i32 m0, s47, 0xe000
	s_nop 0
	global_load_lds_dwordx4 v[154:155], off
	s_waitcnt vmcnt(8)
	s_waitcnt lgkmcnt(0)
	s_barrier
; #define PG8_STAGE(bufoff, gbase, voff) do { _Pragma("unroll") for (int _i = 0; _i < 2; ++_i) \
;         __builtin_amdgcn_global_load_lds((const unsigned*)((const char*)(gbase) + (voff)[_i]), (PG8_LAS unsigned*)(lds + (bufoff) + ldsw + _i * 8192), 16, 0, 0); } while (0)
; #define PG8_LDA(dst, b, h) do { _Pragma("unroll") for (int m = 0; m < 4; ++m) _Pragma("unroll") for (int k = 0; k < 2; ++k) dst[m][k] = *(const PG8_LAS bf16x8*)(lds + PG8_SA(b, h) + aoff + m * 2048 + k * 1024); } while (0)
; #define PG8_MMA(ai, bj, At, Bt) do { __builtin_amdgcn_s_setprio(1); _Pragma("unroll") for (int m = 0; m < 4; ++m) _Pragma("unroll") for (int n = 0; n < 2; ++n) _Pragma("unroll") for (int k = 0; k < 2; ++k) \
;         acc[ai][bj][m][n] = __builtin_amdgcn_mfma_f32_16x16x32_bf16(Bt[n][k], At[m][k], acc[ai][bj][m][n], 0, 0, 0); __builtin_amdgcn_s_setprio(0); } while (0)
; #define PG8_WAIT_V(n) asm volatile("s_waitcnt vmcnt(" #n ")" ::: "memory")
; #define PG8_WAIT_L(n) asm volatile("s_waitcnt lgkmcnt(" #n ")" ::: "memory")
; #define PG8_BAR __builtin_amdgcn_s_barrier()
; #define PG8_SCHED __builtin_amdgcn_sched_barrier(0)
; template <class Epi, class Sched, bool ALIGN_EPI = false, bool SP2 = false>
; __device__ __forceinline__ void gemm_phase(PG8_LAS unsigned char* lds, const Gemm g, const Sched& S, const Epi& E, int tid_in) {
;     ...
;             PG8_WAIT_V(8); PG8_WAIT_L(0); PG8_BAR; PG8_MMA(0, 0, At, B0); PG8_MMA(0, 1, At, B1); PG8_BAR; PG8_SCHED;
;             PG8_LDA(At, 0, 1); PG8_STAGE(PG8_SB(0, 0), b2, voffB); PG8_STAGE(PG8_SB(0, 1), b2 + hstep, voffB); PG8_STAGE(PG8_SA(0, 0), a2, voffA);
;             PG8_WAIT_V(8); PG8_WAIT_L(0); PG8_BAR; PG8_MMA(1, 0, At, B0); PG8_MMA(1, 1, At, B1); PG8_BAR; PG8_SCHED;
	s_waitcnt lgkmcnt(0)
	v_mfma_f32_16x16x32_bf16 v[124:127], v[134:137], v[178:181], v[124:127]
	v_mfma_f32_16x16x32_bf16 v[120:123], v[142:145], v[178:181], v[120:123]
	v_mfma_f32_16x16x32_bf16 v[108:111], v[134:137], v[186:189], v[108:111]
	v_mfma_f32_16x16x32_bf16 v[104:107], v[142:145], v[186:189], v[104:107]
	v_mfma_f32_16x16x32_bf16 v[92:95], v[134:137], v[194:197], v[92:95]
	v_mfma_f32_16x16x32_bf16 v[88:91], v[142:145], v[194:197], v[88:91]
	v_mfma_f32_16x16x32_bf16 v[76:79], v[134:137], v[202:205], v[76:79]
	v_mfma_f32_16x16x32_bf16 v[72:75], v[142:145], v[202:205], v[72:75]
	v_mfma_f32_16x16x32_bf16 v[124:127], v[138:141], v[182:185], v[124:127]
	v_mfma_f32_16x16x32_bf16 v[120:123], v[146:149], v[182:185], v[120:123]
	v_mfma_f32_16x16x32_bf16 v[108:111], v[138:141], v[190:193], v[108:111]
	v_mfma_f32_16x16x32_bf16 v[104:107], v[146:149], v[190:193], v[104:107]
	v_mfma_f32_16x16x32_bf16 v[92:95], v[138:141], v[198:201], v[92:95]
	v_mfma_f32_16x16x32_bf16 v[88:91], v[146:149], v[198:201], v[88:91]
	v_mfma_f32_16x16x32_bf16 v[76:79], v[138:141], v[206:209], v[76:79]
	v_mfma_f32_16x16x32_bf16 v[72:75], v[146:149], v[206:209], v[72:75]
	v_mfma_f32_16x16x32_bf16 v[116:119], v[150:153], v[178:181], v[116:119]
	v_mfma_f32_16x16x32_bf16 v[112:115], v[170:173], v[178:181], v[112:115]
	v_mfma_f32_16x16x32_bf16 v[100:103], v[150:153], v[186:189], v[100:103]
	v_mfma_f32_16x16x32_bf16 v[96:99], v[170:173], v[186:189], v[96:99]
	v_mfma_f32_16x16x32_bf16 v[84:87], v[150:153], v[194:197], v[84:87]
	v_mfma_f32_16x16x32_bf16 v[80:83], v[170:173], v[194:197], v[80:83]
	v_mfma_f32_16x16x32_bf16 v[68:71], v[150:153], v[202:205], v[68:71]
	v_mfma_f32_16x16x32_bf16 v[64:67], v[170:173], v[202:205], v[64:67]
	v_mfma_f32_16x16x32_bf16 v[116:119], v[166:169], v[182:185], v[116:119]
	v_mfma_f32_16x16x32_bf16 v[112:115], v[174:177], v[182:185], v[112:115]
	v_mfma_f32_16x16x32_bf16 v[100:103], v[166:169], v[190:193], v[100:103]
	v_mfma_f32_16x16x32_bf16 v[96:99], v[174:177], v[190:193], v[96:99]
	v_mfma_f32_16x16x32_bf16 v[84:87], v[166:169], v[198:201], v[84:87]
	v_mfma_f32_16x16x32_bf16 v[80:83], v[174:177], v[198:201], v[80:83]
	v_mfma_f32_16x16x32_bf16 v[68:71], v[166:169], v[206:209], v[68:71]
	v_mfma_f32_16x16x32_bf16 v[64:67], v[174:177], v[206:209], v[64:67]
	s_barrier
	s_add_i32 s37, s37, s46
	v_lshl_add_u64 v[154:155], s[2:3], 0, v[156:157]
	s_mov_b32 m0, s37
	ds_read_b128 v[178:181], v241 offset:16384
	ds_read_b128 v[182:185], v241 offset:17408
	ds_read_b128 v[186:189], v241 offset:18432
	ds_read_b128 v[190:193], v241 offset:19456
	ds_read_b128 v[194:197], v241 offset:20480
	ds_read_b128 v[198:201], v241 offset:21504
	ds_read_b128 v[202:205], v241 offset:22528
	ds_read_b128 v[206:209], v241 offset:23552
	global_load_lds_dwordx4 v[154:155], off
	s_add_i32 m0, s37, 0x2000
	v_lshl_add_u64 v[162:163], s[2:3], 0, v[128:129]
	s_add_u32 s2, s2, s12
	s_addc_u32 s3, s3, s13
	s_add_i32 s37, vcc_hi, s46
	global_load_lds_dwordx4 v[162:163], off
	v_lshl_add_u64 v[210:211], s[2:3], 0, v[156:157]
	s_mov_b32 m0, s37
	v_lshl_add_u64 v[212:213], s[2:3], 0, v[128:129]
	global_load_lds_dwordx4 v[210:211], off
	s_add_i32 m0, s37, 0x2000
	v_lshl_add_u64 v[214:215], s[22:23], 0, v[156:157]
	global_load_lds_dwordx4 v[212:213], off
	s_mov_b32 m0, s47
	v_lshl_add_u64 v[216:217], s[22:23], 0, v[128:129]
	global_load_lds_dwordx4 v[214:215], off
	s_mov_b32 m0, s52
	s_nop 0
	global_load_lds_dwordx4 v[216:217], off
	s_waitcnt vmcnt(8)
	s_waitcnt lgkmcnt(0)
	s_barrier
	s_waitcnt lgkmcnt(0)
	v_mfma_f32_16x16x32_bf16 v[60:63], v[134:137], v[178:181], v[60:63]
	v_mfma_f32_16x16x32_bf16 v[56:59], v[142:145], v[178:181], v[56:59]
	v_mfma_f32_16x16x32_bf16 v[44:47], v[134:137], v[186:189], v[44:47]
	v_mfma_f32_16x16x32_bf16 v[40:43], v[142:145], v[186:189], v[40:43]
	v_mfma_f32_16x16x32_bf16 v[28:31], v[134:137], v[194:197], v[28:31]
	v_mfma_f32_16x16x32_bf16 v[24:27], v[142:145], v[194:197], v[24:27]
	v_mfma_f32_16x16x32_bf16 v[12:15], v[134:137], v[202:205], v[12:15]
	v_mfma_f32_16x16x32_bf16 v[8:11], v[142:145], v[202:205], v[8:11]
	v_mfma_f32_16x16x32_bf16 v[60:63], v[138:141], v[182:185], v[60:63]
	v_mfma_f32_16x16x32_bf16 v[56:59], v[146:149], v[182:185], v[56:59]
	v_mfma_f32_16x16x32_bf16 v[44:47], v[138:141], v[190:193], v[44:47]
	v_mfma_f32_16x16x32_bf16 v[40:43], v[146:149], v[190:193], v[40:43]
	v_mfma_f32_16x16x32_bf16 v[28:31], v[138:141], v[198:201], v[28:31]
	v_mfma_f32_16x16x32_bf16 v[24:27], v[146:149], v[198:201], v[24:27]
	v_mfma_f32_16x16x32_bf16 v[12:15], v[138:141], v[206:209], v[12:15]
	v_mfma_f32_16x16x32_bf16 v[8:11], v[146:149], v[206:209], v[8:11]
	v_mfma_f32_16x16x32_bf16 v[52:55], v[150:153], v[178:181], v[52:55]
	v_mfma_f32_16x16x32_bf16 v[48:51], v[170:173], v[178:181], v[48:51]
	v_mfma_f32_16x16x32_bf16 v[36:39], v[150:153], v[186:189], v[36:39]
	v_mfma_f32_16x16x32_bf16 v[32:35], v[170:173], v[186:189], v[32:35]
	v_mfma_f32_16x16x32_bf16 v[20:23], v[150:153], v[194:197], v[20:23]
	v_mfma_f32_16x16x32_bf16 v[16:19], v[170:173], v[194:197], v[16:19]
	v_mfma_f32_16x16x32_bf16 v[4:7], v[150:153], v[202:205], v[4:7]
	v_mfma_f32_16x16x32_bf16 v[0:3], v[170:173], v[202:205], v[0:3]
	v_mfma_f32_16x16x32_bf16 v[52:55], v[166:169], v[182:185], v[52:55]
	v_mfma_f32_16x16x32_bf16 v[48:51], v[174:177], v[182:185], v[48:51]
	v_mfma_f32_16x16x32_bf16 v[36:39], v[166:169], v[190:193], v[36:39]
	v_mfma_f32_16x16x32_bf16 v[32:35], v[174:177], v[190:193], v[32:35]
	v_mfma_f32_16x16x32_bf16 v[20:23], v[166:169], v[198:201], v[20:23]
	v_mfma_f32_16x16x32_bf16 v[16:19], v[174:177], v[198:201], v[16:19]
	v_mfma_f32_16x16x32_bf16 v[4:7], v[166:169], v[206:209], v[4:7]
	v_mfma_f32_16x16x32_bf16 v[0:3], v[174:177], v[206:209], v[0:3]
	s_barrier
; #define PG8_STAGE(bufoff, gbase, voff) do { _Pragma("unroll") for (int _i = 0; _i < 2; ++_i) \
;         __builtin_amdgcn_global_load_lds((const unsigned*)((const char*)(gbase) + (voff)[_i]), (PG8_LAS unsigned*)(lds + (bufoff) + ldsw + _i * 8192), 16, 0, 0); } while (0)
; #define PG8_LDA(dst, b, h) do { _Pragma("unroll") for (int m = 0; m < 4; ++m) _Pragma("unroll") for (int k = 0; k < 2; ++k) dst[m][k] = *(const PG8_LAS bf16x8*)(lds + PG8_SA(b, h) + aoff + m * 2048 + k * 1024); } while (0)
; #define PG8_LDB(dst, b, h) do { _Pragma("unroll") for (int n = 0; n < 2; ++n) _Pragma("unroll") for (int k = 0; k < 2; ++k) dst[n][k] = *(const PG8_LAS bf16x8*)(lds + PG8_SB(b, h) + boff + n * 2048 + k * 1024); } while (0)
; #define PG8_MMA(ai, bj, At, Bt) do { __builtin_amdgcn_s_setprio(1); _Pragma("unroll") for (int m = 0; m < 4; ++m) _Pragma("unroll") for (int n = 0; n < 2; ++n) _Pragma("unroll") for (int k = 0; k < 2; ++k) \
;         acc[ai][bj][m][n] = __builtin_amdgcn_mfma_f32_16x16x32_bf16(Bt[n][k], At[m][k], acc[ai][bj][m][n], 0, 0, 0); __builtin_amdgcn_s_setprio(0); } while (0)
; #define PG8_WAIT_V(n) asm volatile("s_waitcnt vmcnt(" #n ")" ::: "memory")
; #define PG8_WAIT_L(n) asm volatile("s_waitcnt lgkmcnt(" #n ")" ::: "memory")
; #define PG8_BAR __builtin_amdgcn_s_barrier()
; #define PG8_SCHED __builtin_amdgcn_sched_barrier(0)
; template <class Epi, class Sched, bool ALIGN_EPI = false, bool SP2 = false>
; __device__ __forceinline__ void gemm_phase(PG8_LAS unsigned char* lds, const Gemm g, const Sched& S, const Epi& E, int tid_in) {
;     ...
;             PG8_LDB(B0, 1, 0); PG8_LDB(B1, 1, 1); PG8_SCHED; PG8_LDA(At, 1, 0); PG8_STAGE(PG8_SA(0, 1), a2 + hstep, voffA);
;             PG8_WAIT_V(8); PG8_WAIT_L(0); PG8_BAR; PG8_MMA(0, 0, At, B0); PG8_MMA(0, 1, At, B1); PG8_BAR; PG8_SCHED;
;             PG8_LDA(At, 1, 1); PG8_STAGE(PG8_SB(1, 0), b3, voffB); PG8_STAGE(PG8_SB(1, 1), b3 + hstep, voffB); PG8_STAGE(PG8_SA(1, 0), a3, voffA);
;             PG8_WAIT_V(8); PG8_WAIT_L(0); PG8_BAR; PG8_MMA(1, 0, At, B0); PG8_MMA(1, 1, At, B1); PG8_BAR; PG8_SCHED;
	s_add_i32 s37, 0, 0x18000
	s_add_i32 vcc_hi, 0, 0x1c000
	v_add_u32_e32 v146, s37, v237
	v_add_u32_e32 v174, vcc_hi, v237
	ds_read_b128 v[134:137], v146
	ds_read_b128 v[138:141], v146 offset:1024
	ds_read_b128 v[142:145], v146 offset:2048
	ds_read_b128 v[146:149], v146 offset:3072
	ds_read_b128 v[150:153], v174
	ds_read_b128 v[166:169], v174 offset:1024
	ds_read_b128 v[170:173], v174 offset:2048
	ds_read_b128 v[174:177], v174 offset:3072
	s_add_u32 s2, s22, s12
	s_addc_u32 s3, s23, s13
	s_mov_b32 m0, s53
	v_lshl_add_u64 v[218:219], s[2:3], 0, v[156:157]
	ds_read_b128 v[178:181], v241 offset:32768
	ds_read_b128 v[182:185], v241 offset:33792
	ds_read_b128 v[186:189], v241 offset:34816
	ds_read_b128 v[190:193], v241 offset:35840
	ds_read_b128 v[194:197], v241 offset:36864
	ds_read_b128 v[198:201], v241 offset:37888
	ds_read_b128 v[202:205], v241 offset:38912
	ds_read_b128 v[206:209], v241 offset:39936
	global_load_lds_dwordx4 v[218:219], off
	v_lshl_add_u64 v[218:219], s[2:3], 0, v[128:129]
	s_mov_b32 m0, s56
	s_nop 0
	global_load_lds_dwordx4 v[218:219], off
	s_waitcnt vmcnt(8)
	s_waitcnt lgkmcnt(0)
	s_barrier
	s_waitcnt lgkmcnt(0)
	v_mfma_f32_16x16x32_bf16 v[124:127], v[134:137], v[178:181], v[124:127]
	v_mfma_f32_16x16x32_bf16 v[120:123], v[142:145], v[178:181], v[120:123]
	v_mfma_f32_16x16x32_bf16 v[108:111], v[134:137], v[186:189], v[108:111]
	v_mfma_f32_16x16x32_bf16 v[104:107], v[142:145], v[186:189], v[104:107]
	v_mfma_f32_16x16x32_bf16 v[92:95], v[134:137], v[194:197], v[92:95]
	v_mfma_f32_16x16x32_bf16 v[88:91], v[142:145], v[194:197], v[88:91]
	v_mfma_f32_16x16x32_bf16 v[76:79], v[134:137], v[202:205], v[76:79]
	v_mfma_f32_16x16x32_bf16 v[72:75], v[142:145], v[202:205], v[72:75]
	v_mfma_f32_16x16x32_bf16 v[124:127], v[138:141], v[182:185], v[124:127]
	v_mfma_f32_16x16x32_bf16 v[120:123], v[146:149], v[182:185], v[120:123]
	v_mfma_f32_16x16x32_bf16 v[108:111], v[138:141], v[190:193], v[108:111]
	v_mfma_f32_16x16x32_bf16 v[104:107], v[146:149], v[190:193], v[104:107]
	v_mfma_f32_16x16x32_bf16 v[92:95], v[138:141], v[198:201], v[92:95]
	v_mfma_f32_16x16x32_bf16 v[88:91], v[146:149], v[198:201], v[88:91]
	v_mfma_f32_16x16x32_bf16 v[76:79], v[138:141], v[206:209], v[76:79]
	v_mfma_f32_16x16x32_bf16 v[72:75], v[146:149], v[206:209], v[72:75]
	v_mfma_f32_16x16x32_bf16 v[116:119], v[150:153], v[178:181], v[116:119]
	v_mfma_f32_16x16x32_bf16 v[112:115], v[170:173], v[178:181], v[112:115]
	v_mfma_f32_16x16x32_bf16 v[100:103], v[150:153], v[186:189], v[100:103]
	v_mfma_f32_16x16x32_bf16 v[96:99], v[170:173], v[186:189], v[96:99]
	v_mfma_f32_16x16x32_bf16 v[84:87], v[150:153], v[194:197], v[84:87]
	v_mfma_f32_16x16x32_bf16 v[80:83], v[170:173], v[194:197], v[80:83]
	v_mfma_f32_16x16x32_bf16 v[68:71], v[150:153], v[202:205], v[68:71]
	v_mfma_f32_16x16x32_bf16 v[64:67], v[170:173], v[202:205], v[64:67]
	v_mfma_f32_16x16x32_bf16 v[116:119], v[166:169], v[182:185], v[116:119]
	v_mfma_f32_16x16x32_bf16 v[112:115], v[174:177], v[182:185], v[112:115]
	v_mfma_f32_16x16x32_bf16 v[100:103], v[166:169], v[190:193], v[100:103]
	v_mfma_f32_16x16x32_bf16 v[96:99], v[174:177], v[190:193], v[96:99]
	v_mfma_f32_16x16x32_bf16 v[84:87], v[166:169], v[198:201], v[84:87]
	v_mfma_f32_16x16x32_bf16 v[80:83], v[174:177], v[198:201], v[80:83]
	v_mfma_f32_16x16x32_bf16 v[68:71], v[166:169], v[206:209], v[68:71]
	v_mfma_f32_16x16x32_bf16 v[64:67], v[174:177], v[206:209], v[64:67]
	s_barrier
	s_add_i32 s2, s37, s46
	v_lshl_add_u64 v[154:155], v[154:155], 0, s[64:65]
	s_mov_b32 m0, s2
	ds_read_b128 v[178:181], v241 offset:49152
	ds_read_b128 v[182:185], v241 offset:50176
	ds_read_b128 v[186:189], v241 offset:51200
	ds_read_b128 v[190:193], v241 offset:52224
	ds_read_b128 v[194:197], v241 offset:53248
	ds_read_b128 v[198:201], v241 offset:54272
	ds_read_b128 v[202:205], v241 offset:55296
	ds_read_b128 v[206:209], v241 offset:56320
	global_load_lds_dwordx4 v[154:155], off
	v_lshl_add_u64 v[154:155], v[162:163], 0, s[64:65]
	s_add_i32 m0, s2, 0x2000
	s_add_i32 s2, vcc_hi, s46
	global_load_lds_dwordx4 v[154:155], off
	v_lshl_add_u64 v[154:155], v[210:211], 0, s[64:65]
	s_mov_b32 m0, s2
	s_nop 0
	global_load_lds_dwordx4 v[154:155], off
	v_lshl_add_u64 v[154:155], v[212:213], 0, s[64:65]
	s_add_i32 m0, s2, 0x2000
	s_nop 0
	global_load_lds_dwordx4 v[154:155], off
	v_lshl_add_u64 v[154:155], v[214:215], 0, s[64:65]
	s_mov_b32 m0, s88
	s_nop 0
	global_load_lds_dwordx4 v[154:155], off
	v_lshl_add_u64 v[154:155], v[216:217], 0, s[64:65]
	s_mov_b32 m0, s89
	s_nop 0
	global_load_lds_dwordx4 v[154:155], off
	s_waitcnt vmcnt(8)
	s_waitcnt lgkmcnt(0)
	s_barrier
	s_waitcnt lgkmcnt(0)
	v_mfma_f32_16x16x32_bf16 v[60:63], v[134:137], v[178:181], v[60:63]
	v_mfma_f32_16x16x32_bf16 v[56:59], v[142:145], v[178:181], v[56:59]
	v_mfma_f32_16x16x32_bf16 v[44:47], v[134:137], v[186:189], v[44:47]
	v_mfma_f32_16x16x32_bf16 v[40:43], v[142:145], v[186:189], v[40:43]
	v_mfma_f32_16x16x32_bf16 v[28:31], v[134:137], v[194:197], v[28:31]
	v_mfma_f32_16x16x32_bf16 v[24:27], v[142:145], v[194:197], v[24:27]
	v_mfma_f32_16x16x32_bf16 v[12:15], v[134:137], v[202:205], v[12:15]
	v_mfma_f32_16x16x32_bf16 v[8:11], v[142:145], v[202:205], v[8:11]
	v_mfma_f32_16x16x32_bf16 v[60:63], v[138:141], v[182:185], v[60:63]
	v_mfma_f32_16x16x32_bf16 v[56:59], v[146:149], v[182:185], v[56:59]
	v_mfma_f32_16x16x32_bf16 v[44:47], v[138:141], v[190:193], v[44:47]
	v_mfma_f32_16x16x32_bf16 v[40:43], v[146:149], v[190:193], v[40:43]
	v_mfma_f32_16x16x32_bf16 v[28:31], v[138:141], v[198:201], v[28:31]
	v_mfma_f32_16x16x32_bf16 v[24:27], v[146:149], v[198:201], v[24:27]
	v_mfma_f32_16x16x32_bf16 v[12:15], v[138:141], v[206:209], v[12:15]
	v_mfma_f32_16x16x32_bf16 v[8:11], v[146:149], v[206:209], v[8:11]
	v_mfma_f32_16x16x32_bf16 v[52:55], v[150:153], v[178:181], v[52:55]
	v_mfma_f32_16x16x32_bf16 v[48:51], v[170:173], v[178:181], v[48:51]
	v_mfma_f32_16x16x32_bf16 v[36:39], v[150:153], v[186:189], v[36:39]
	v_mfma_f32_16x16x32_bf16 v[32:35], v[170:173], v[186:189], v[32:35]
	v_mfma_f32_16x16x32_bf16 v[20:23], v[150:153], v[194:197], v[20:23]
	v_mfma_f32_16x16x32_bf16 v[16:19], v[170:173], v[194:197], v[16:19]
	v_mfma_f32_16x16x32_bf16 v[4:7], v[150:153], v[202:205], v[4:7]
	v_mfma_f32_16x16x32_bf16 v[0:3], v[170:173], v[202:205], v[0:3]
	v_mfma_f32_16x16x32_bf16 v[52:55], v[166:169], v[182:185], v[52:55]
	v_mfma_f32_16x16x32_bf16 v[48:51], v[174:177], v[182:185], v[48:51]
	s_add_u32 s0, s0, 0x100
	v_mfma_f32_16x16x32_bf16 v[36:39], v[166:169], v[190:193], v[36:39]
	s_addc_u32 s1, s1, 0
	v_mfma_f32_16x16x32_bf16 v[32:35], v[174:177], v[190:193], v[32:35]
	s_add_u32 s63, s63, 0x100
	v_mfma_f32_16x16x32_bf16 v[20:23], v[166:169], v[198:201], v[20:23]
	s_addc_u32 vcc_lo, vcc_lo, 0
	v_mfma_f32_16x16x32_bf16 v[16:19], v[174:177], v[198:201], v[16:19]
	s_cmp_ge_i32 s36, s67
	v_mfma_f32_16x16x32_bf16 v[4:7], v[166:169], v[206:209], v[4:7]
	s_mov_b32 s22, s36
	v_mfma_f32_16x16x32_bf16 v[0:3], v[174:177], v[206:209], v[0:3]
	s_barrier
	s_cbranch_scc0 .LBB0_820

; #define PG8_STAGE(bufoff, gbase, voff) do { _Pragma("unroll") for (int _i = 0; _i < 2; ++_i) \
;         __builtin_amdgcn_global_load_lds((const unsigned*)((const char*)(gbase) + (voff)[_i]), (PG8_LAS unsigned*)(lds + (bufoff) + ldsw + _i * 8192), 16, 0, 0); } while (0)
; #define PG8_LDA(dst, b, h) do { _Pragma("unroll") for (int m = 0; m < 4; ++m) _Pragma("unroll") for (int k = 0; k < 2; ++k) dst[m][k] = *(const PG8_LAS bf16x8*)(lds + PG8_SA(b, h) + aoff + m * 2048 + k * 1024); } while (0)
; #define PG8_LDB(dst, b, h) do { _Pragma("unroll") for (int n = 0; n < 2; ++n) _Pragma("unroll") for (int k = 0; k < 2; ++k) dst[n][k] = *(const PG8_LAS bf16x8*)(lds + PG8_SB(b, h) + boff + n * 2048 + k * 1024); } while (0)
; #define PG8_MMA(ai, bj, At, Bt) do { __builtin_amdgcn_s_setprio(1); _Pragma("unroll") for (int m = 0; m < 4; ++m) _Pragma("unroll") for (int n = 0; n < 2; ++n) _Pragma("unroll") for (int k = 0; k < 2; ++k) \
;         acc[ai][bj][m][n] = __builtin_amdgcn_mfma_f32_16x16x32_bf16(Bt[n][k], At[m][k], acc[ai][bj][m][n], 0, 0, 0); __builtin_amdgcn_s_setprio(0); } while (0)
; #define PG8_WAIT_V(n) asm volatile("s_waitcnt vmcnt(" #n ")" ::: "memory")
; #define PG8_WAIT_L(n) asm volatile("s_waitcnt lgkmcnt(" #n ")" ::: "memory")
; #define PG8_BAR __builtin_amdgcn_s_barrier()
; #define PG8_SCHED __builtin_amdgcn_sched_barrier(0)
; template <class Epi, class Sched, bool ALIGN_EPI = false, bool SP2 = false>
; __device__ __forceinline__ void gemm_phase(PG8_LAS unsigned char* lds, const Gemm g, const Sched& S, const Epi& E, int tid_in) {
;     ...
;                 for (int n = 0; n < 2; ++n) acc[a][b][m][n] = (f32x4){0.f, 0.f, 0.f, 0.f};
;     ...
;             PG8_LDB(B0, 0, 0); PG8_LDB(B1, 0, 1); PG8_SCHED; PG8_LDA(At, 0, 0); PG8_STAGE(PG8_SA(1, 1), a1 + hstep, voffA);
;             PG8_WAIT_V(8); PG8_WAIT_L(0); PG8_BAR; PG8_MMA(0, 0, At, B0); PG8_MMA(0, 1, At, B1); PG8_BAR; PG8_SCHED;
;             PG8_LDA(At, 0, 1); PG8_STAGE(PG8_SB(0, 0), b2, voffB); PG8_STAGE(PG8_SB(0, 1), b2 + hstep, voffB); PG8_STAGE(PG8_SA(0, 0), a2, voffA);
;             PG8_WAIT_V(8); PG8_WAIT_L(0); PG8_BAR; PG8_MMA(1, 0, At, B0); PG8_MMA(1, 1, At, B1); PG8_BAR; PG8_SCHED;
.Lpeel_enter_g3:
	s_add_u32 s0, s0, 0x80
	s_addc_u32 s1, s1, 0
	s_add_u32 s22, s22, 0x100
	s_addc_u32 s23, s23, 0
	s_mov_b32 s6, 0
	s_add_i32 s36, s6, 2
	s_add_u32 s2, s0, 0x80
	s_addc_u32 s3, s1, 0
	s_add_i32 s37, 0, 0x10000
	s_cmp_eq_u32 s60, s6
	s_cselect_b32 s7, s63, s3
	s_cselect_b32 s6, s62, s2
	v_add_u32_e32 v144, s37, v151
	s_cselect_b32 s3, s67, s23
	s_cselect_b32 s2, s66, s22
	s_add_i32 s91, 0, 0x14000
	ds_read_b128 v[140:143], v144
	ds_read_b128 v[168:171], v144 offset:1024
	ds_read_b128 v[172:175], v144 offset:2048
	ds_read_b128 v[176:179], v144 offset:3072
	v_add_u32_e32 v144, s91, v151
	ds_read_b128 v[180:183], v144
	ds_read_b128 v[184:187], v144 offset:1024
	ds_read_b128 v[188:191], v144 offset:2048
	ds_read_b128 v[192:195], v144 offset:3072
	v_lshl_add_u64 v[146:147], s[0:1], 0, v[136:137]
	s_add_i32 m0, s43, 0xc000
	ds_read_b128 v[196:199], v167
	ds_read_b128 v[200:203], v167 offset:1024
	ds_read_b128 v[204:207], v167 offset:2048
	ds_read_b128 v[208:211], v167 offset:3072
	ds_read_b128 v[212:215], v167 offset:4096
	ds_read_b128 v[216:219], v167 offset:5120
	ds_read_b128 v[220:223], v167 offset:6144
	ds_read_b128 v[224:227], v167 offset:7168
	global_load_lds_dwordx4 v[146:147], off
	v_lshl_add_u64 v[146:147], s[0:1], 0, v[138:139]
	s_add_i32 m0, s43, 0xe000
	s_nop 0
	global_load_lds_dwordx4 v[146:147], off
	s_waitcnt vmcnt(8)
	s_waitcnt lgkmcnt(0)
	s_barrier
	s_waitcnt lgkmcnt(0)
	v_mfma_f32_16x16x32_bf16 v[124:127], v[140:143], v[196:199], 0
	v_mfma_f32_16x16x32_bf16 v[120:123], v[172:175], v[196:199], 0
	v_mfma_f32_16x16x32_bf16 v[108:111], v[140:143], v[204:207], 0
	v_mfma_f32_16x16x32_bf16 v[104:107], v[172:175], v[204:207], 0
	v_mfma_f32_16x16x32_bf16 v[92:95], v[140:143], v[212:215], 0
	v_mfma_f32_16x16x32_bf16 v[88:91], v[172:175], v[212:215], 0
	v_mfma_f32_16x16x32_bf16 v[76:79], v[140:143], v[220:223], 0
	v_mfma_f32_16x16x32_bf16 v[72:75], v[172:175], v[220:223], 0
	v_mfma_f32_16x16x32_bf16 v[124:127], v[168:171], v[200:203], v[124:127]
	v_mfma_f32_16x16x32_bf16 v[120:123], v[176:179], v[200:203], v[120:123]
	v_mfma_f32_16x16x32_bf16 v[108:111], v[168:171], v[208:211], v[108:111]
	v_mfma_f32_16x16x32_bf16 v[104:107], v[176:179], v[208:211], v[104:107]
	v_mfma_f32_16x16x32_bf16 v[92:95], v[168:171], v[216:219], v[92:95]
	v_mfma_f32_16x16x32_bf16 v[88:91], v[176:179], v[216:219], v[88:91]
	v_mfma_f32_16x16x32_bf16 v[76:79], v[168:171], v[224:227], v[76:79]
	v_mfma_f32_16x16x32_bf16 v[72:75], v[176:179], v[224:227], v[72:75]
	v_mfma_f32_16x16x32_bf16 v[116:119], v[180:183], v[196:199], 0
	v_mfma_f32_16x16x32_bf16 v[112:115], v[188:191], v[196:199], 0
	v_mfma_f32_16x16x32_bf16 v[100:103], v[180:183], v[204:207], 0
	v_mfma_f32_16x16x32_bf16 v[96:99], v[188:191], v[204:207], 0
	v_mfma_f32_16x16x32_bf16 v[84:87], v[180:183], v[212:215], 0
	v_mfma_f32_16x16x32_bf16 v[80:83], v[188:191], v[212:215], 0
	v_mfma_f32_16x16x32_bf16 v[68:71], v[180:183], v[220:223], 0
	v_mfma_f32_16x16x32_bf16 v[64:67], v[188:191], v[220:223], 0
	v_mfma_f32_16x16x32_bf16 v[116:119], v[184:187], v[200:203], v[116:119]
	v_mfma_f32_16x16x32_bf16 v[112:115], v[192:195], v[200:203], v[112:115]
	v_mfma_f32_16x16x32_bf16 v[100:103], v[184:187], v[208:211], v[100:103]
	v_mfma_f32_16x16x32_bf16 v[96:99], v[192:195], v[208:211], v[96:99]
	v_mfma_f32_16x16x32_bf16 v[84:87], v[184:187], v[216:219], v[84:87]
	v_mfma_f32_16x16x32_bf16 v[80:83], v[192:195], v[216:219], v[80:83]
	v_mfma_f32_16x16x32_bf16 v[68:71], v[184:187], v[224:227], v[68:71]
	v_mfma_f32_16x16x32_bf16 v[64:67], v[192:195], v[224:227], v[64:67]
	s_barrier
	s_add_i32 s37, s37, s42
	v_lshl_add_u64 v[146:147], s[2:3], 0, v[156:157]
	s_mov_b32 m0, s37
	ds_read_b128 v[196:199], v167 offset:16384
	ds_read_b128 v[200:203], v167 offset:17408
	ds_read_b128 v[204:207], v167 offset:18432
	ds_read_b128 v[208:211], v167 offset:19456
	ds_read_b128 v[212:215], v167 offset:20480
	ds_read_b128 v[216:219], v167 offset:21504
	ds_read_b128 v[220:223], v167 offset:22528
	ds_read_b128 v[224:227], v167 offset:23552
	global_load_lds_dwordx4 v[146:147], off
	s_add_i32 m0, s37, 0x2000
	v_lshl_add_u64 v[162:163], s[2:3], 0, v[128:129]
	s_add_u32 s2, s2, s10
	s_addc_u32 s3, s3, s11
	s_add_i32 s37, s91, s42
	global_load_lds_dwordx4 v[162:163], off
	v_lshl_add_u64 v[228:229], s[2:3], 0, v[156:157]
	s_mov_b32 m0, s37
	v_lshl_add_u64 v[230:231], s[2:3], 0, v[128:129]
	global_load_lds_dwordx4 v[228:229], off
	s_add_i32 m0, s37, 0x2000
	v_lshl_add_u64 v[238:239], s[6:7], 0, v[132:133]
	global_load_lds_dwordx4 v[230:231], off
	s_mov_b32 m0, s43
	v_lshl_add_u64 v[240:241], s[6:7], 0, v[130:131]
	global_load_lds_dwordx4 v[238:239], off
	s_mov_b32 m0, s44
	s_nop 0
	global_load_lds_dwordx4 v[240:241], off
	s_waitcnt vmcnt(8)
	s_waitcnt lgkmcnt(0)
	s_barrier
; #define PG8_STAGE(bufoff, gbase, voff) do { _Pragma("unroll") for (int _i = 0; _i < 2; ++_i) \
;         __builtin_amdgcn_global_load_lds((const unsigned*)((const char*)(gbase) + (voff)[_i]), (PG8_LAS unsigned*)(lds + (bufoff) + ldsw + _i * 8192), 16, 0, 0); } while (0)
; #define PG8_LDA(dst, b, h) do { _Pragma("unroll") for (int m = 0; m < 4; ++m) _Pragma("unroll") for (int k = 0; k < 2; ++k) dst[m][k] = *(const PG8_LAS bf16x8*)(lds + PG8_SA(b, h) + aoff + m * 2048 + k * 1024); } while (0)
; #define PG8_LDB(dst, b, h) do { _Pragma("unroll") for (int n = 0; n < 2; ++n) _Pragma("unroll") for (int k = 0; k < 2; ++k) dst[n][k] = *(const PG8_LAS bf16x8*)(lds + PG8_SB(b, h) + boff + n * 2048 + k * 1024); } while (0)
; #define PG8_MMA(ai, bj, At, Bt) do { __builtin_amdgcn_s_setprio(1); _Pragma("unroll") for (int m = 0; m < 4; ++m) _Pragma("unroll") for (int n = 0; n < 2; ++n) _Pragma("unroll") for (int k = 0; k < 2; ++k) \
;         acc[ai][bj][m][n] = __builtin_amdgcn_mfma_f32_16x16x32_bf16(Bt[n][k], At[m][k], acc[ai][bj][m][n], 0, 0, 0); __builtin_amdgcn_s_setprio(0); } while (0)
; #define PG8_WAIT_V(n) asm volatile("s_waitcnt vmcnt(" #n ")" ::: "memory")
; #define PG8_WAIT_L(n) asm volatile("s_waitcnt lgkmcnt(" #n ")" ::: "memory")
; #define PG8_BAR __builtin_amdgcn_s_barrier()
; #define PG8_SCHED __builtin_amdgcn_sched_barrier(0)
; template <class Epi, class Sched, bool ALIGN_EPI = false, bool SP2 = false>
; __device__ __forceinline__ void gemm_phase(PG8_LAS unsigned char* lds, const Gemm g, const Sched& S, const Epi& E, int tid_in) {
;     ...
;             PG8_WAIT_V(8); PG8_WAIT_L(0); PG8_BAR; PG8_MMA(1, 0, At, B0); PG8_MMA(1, 1, At, B1); PG8_BAR; PG8_SCHED;
;             PG8_LDB(B0, 1, 0); PG8_LDB(B1, 1, 1); PG8_SCHED; PG8_LDA(At, 1, 0); PG8_STAGE(PG8_SA(0, 1), a2 + hstep, voffA);
;             PG8_WAIT_V(8); PG8_WAIT_L(0); PG8_BAR; PG8_MMA(0, 0, At, B0); PG8_MMA(0, 1, At, B1); PG8_BAR; PG8_SCHED;
	s_waitcnt lgkmcnt(0)
	v_mfma_f32_16x16x32_bf16 v[60:63], v[140:143], v[196:199], 0
	v_mfma_f32_16x16x32_bf16 v[56:59], v[172:175], v[196:199], 0
	v_mfma_f32_16x16x32_bf16 v[44:47], v[140:143], v[204:207], 0
	v_mfma_f32_16x16x32_bf16 v[40:43], v[172:175], v[204:207], 0
	v_mfma_f32_16x16x32_bf16 v[28:31], v[140:143], v[212:215], 0
	v_mfma_f32_16x16x32_bf16 v[24:27], v[172:175], v[212:215], 0
	v_mfma_f32_16x16x32_bf16 v[12:15], v[140:143], v[220:223], 0
	v_mfma_f32_16x16x32_bf16 v[8:11], v[172:175], v[220:223], 0
	v_mfma_f32_16x16x32_bf16 v[60:63], v[168:171], v[200:203], v[60:63]
	v_mfma_f32_16x16x32_bf16 v[56:59], v[176:179], v[200:203], v[56:59]
	v_mfma_f32_16x16x32_bf16 v[44:47], v[168:171], v[208:211], v[44:47]
	v_mfma_f32_16x16x32_bf16 v[40:43], v[176:179], v[208:211], v[40:43]
	v_mfma_f32_16x16x32_bf16 v[28:31], v[168:171], v[216:219], v[28:31]
	v_mfma_f32_16x16x32_bf16 v[24:27], v[176:179], v[216:219], v[24:27]
	v_mfma_f32_16x16x32_bf16 v[12:15], v[168:171], v[224:227], v[12:15]
	v_mfma_f32_16x16x32_bf16 v[8:11], v[176:179], v[224:227], v[8:11]
	v_mfma_f32_16x16x32_bf16 v[52:55], v[180:183], v[196:199], 0
	v_mfma_f32_16x16x32_bf16 v[48:51], v[188:191], v[196:199], 0
	v_mfma_f32_16x16x32_bf16 v[36:39], v[180:183], v[204:207], 0
	v_mfma_f32_16x16x32_bf16 v[32:35], v[188:191], v[204:207], 0
	v_mfma_f32_16x16x32_bf16 v[20:23], v[180:183], v[212:215], 0
	v_mfma_f32_16x16x32_bf16 v[16:19], v[188:191], v[212:215], 0
	v_mfma_f32_16x16x32_bf16 v[4:7], v[180:183], v[220:223], 0
	v_mfma_f32_16x16x32_bf16 v[0:3], v[188:191], v[220:223], 0
	v_mfma_f32_16x16x32_bf16 v[52:55], v[184:187], v[200:203], v[52:55]
	v_mfma_f32_16x16x32_bf16 v[48:51], v[192:195], v[200:203], v[48:51]
	v_mfma_f32_16x16x32_bf16 v[36:39], v[184:187], v[208:211], v[36:39]
	v_mfma_f32_16x16x32_bf16 v[32:35], v[192:195], v[208:211], v[32:35]
	v_mfma_f32_16x16x32_bf16 v[20:23], v[184:187], v[216:219], v[20:23]
	v_mfma_f32_16x16x32_bf16 v[16:19], v[192:195], v[216:219], v[16:19]
	v_mfma_f32_16x16x32_bf16 v[4:7], v[184:187], v[224:227], v[4:7]
	v_mfma_f32_16x16x32_bf16 v[0:3], v[192:195], v[224:227], v[0:3]
	s_barrier
	s_add_i32 s37, 0, 0x18000
	v_add_u32_e32 v144, s37, v151
	s_add_i32 s91, 0, 0x1c000
	ds_read_b128 v[140:143], v144
	ds_read_b128 v[168:171], v144 offset:1024
	ds_read_b128 v[172:175], v144 offset:2048
	ds_read_b128 v[176:179], v144 offset:3072
	v_add_u32_e32 v144, s91, v151
	ds_read_b128 v[180:183], v144
	ds_read_b128 v[184:187], v144 offset:1024
	ds_read_b128 v[188:191], v144 offset:2048
	ds_read_b128 v[192:195], v144 offset:3072
	s_add_u32 s2, s6, s10
	s_addc_u32 s3, s7, s11
	s_mov_b32 m0, s45
	v_lshl_add_u64 v[242:243], s[2:3], 0, v[132:133]
	ds_read_b128 v[196:199], v167 offset:32768
	ds_read_b128 v[200:203], v167 offset:33792
	ds_read_b128 v[204:207], v167 offset:34816
	ds_read_b128 v[208:211], v167 offset:35840
	ds_read_b128 v[212:215], v167 offset:36864
	ds_read_b128 v[216:219], v167 offset:37888
	ds_read_b128 v[220:223], v167 offset:38912
	ds_read_b128 v[224:227], v167 offset:39936
	global_load_lds_dwordx4 v[242:243], off
	v_lshl_add_u64 v[242:243], s[2:3], 0, v[130:131]
	s_mov_b32 m0, s46
	s_nop 0
	global_load_lds_dwordx4 v[242:243], off
	s_waitcnt vmcnt(8)
	s_waitcnt lgkmcnt(0)
	s_barrier
	s_waitcnt lgkmcnt(0)
	v_mfma_f32_16x16x32_bf16 v[124:127], v[140:143], v[196:199], v[124:127]
	v_mfma_f32_16x16x32_bf16 v[120:123], v[172:175], v[196:199], v[120:123]
	v_mfma_f32_16x16x32_bf16 v[108:111], v[140:143], v[204:207], v[108:111]
	v_mfma_f32_16x16x32_bf16 v[104:107], v[172:175], v[204:207], v[104:107]
	v_mfma_f32_16x16x32_bf16 v[92:95], v[140:143], v[212:215], v[92:95]
	v_mfma_f32_16x16x32_bf16 v[88:91], v[172:175], v[212:215], v[88:91]
	v_mfma_f32_16x16x32_bf16 v[76:79], v[140:143], v[220:223], v[76:79]
	v_mfma_f32_16x16x32_bf16 v[72:75], v[172:175], v[220:223], v[72:75]
	v_mfma_f32_16x16x32_bf16 v[124:127], v[168:171], v[200:203], v[124:127]
	v_mfma_f32_16x16x32_bf16 v[120:123], v[176:179], v[200:203], v[120:123]
	v_mfma_f32_16x16x32_bf16 v[108:111], v[168:171], v[208:211], v[108:111]
	v_mfma_f32_16x16x32_bf16 v[104:107], v[176:179], v[208:211], v[104:107]
	v_mfma_f32_16x16x32_bf16 v[92:95], v[168:171], v[216:219], v[92:95]
	v_mfma_f32_16x16x32_bf16 v[88:91], v[176:179], v[216:219], v[88:91]
	v_mfma_f32_16x16x32_bf16 v[76:79], v[168:171], v[224:227], v[76:79]
	v_mfma_f32_16x16x32_bf16 v[72:75], v[176:179], v[224:227], v[72:75]
	v_mfma_f32_16x16x32_bf16 v[116:119], v[180:183], v[196:199], v[116:119]
	v_mfma_f32_16x16x32_bf16 v[112:115], v[188:191], v[196:199], v[112:115]
	v_mfma_f32_16x16x32_bf16 v[100:103], v[180:183], v[204:207], v[100:103]
	v_mfma_f32_16x16x32_bf16 v[96:99], v[188:191], v[204:207], v[96:99]
	v_mfma_f32_16x16x32_bf16 v[84:87], v[180:183], v[212:215], v[84:87]
	v_mfma_f32_16x16x32_bf16 v[80:83], v[188:191], v[212:215], v[80:83]
	v_mfma_f32_16x16x32_bf16 v[68:71], v[180:183], v[220:223], v[68:71]
	v_mfma_f32_16x16x32_bf16 v[64:67], v[188:191], v[220:223], v[64:67]
	v_mfma_f32_16x16x32_bf16 v[116:119], v[184:187], v[200:203], v[116:119]
	v_mfma_f32_16x16x32_bf16 v[112:115], v[192:195], v[200:203], v[112:115]
	v_mfma_f32_16x16x32_bf16 v[100:103], v[184:187], v[208:211], v[100:103]
	v_mfma_f32_16x16x32_bf16 v[96:99], v[192:195], v[208:211], v[96:99]
	v_mfma_f32_16x16x32_bf16 v[84:87], v[184:187], v[216:219], v[84:87]
	v_mfma_f32_16x16x32_bf16 v[80:83], v[192:195], v[216:219], v[80:83]
	v_mfma_f32_16x16x32_bf16 v[68:71], v[184:187], v[224:227], v[68:71]
	v_mfma_f32_16x16x32_bf16 v[64:67], v[192:195], v[224:227], v[64:67]
	s_barrier
; #define PG8_STAGE(bufoff, gbase, voff) do { _Pragma("unroll") for (int _i = 0; _i < 2; ++_i) \
;         __builtin_amdgcn_global_load_lds((const unsigned*)((const char*)(gbase) + (voff)[_i]), (PG8_LAS unsigned*)(lds + (bufoff) + ldsw + _i * 8192), 16, 0, 0); } while (0)
; #define PG8_LDA(dst, b, h) do { _Pragma("unroll") for (int m = 0; m < 4; ++m) _Pragma("unroll") for (int k = 0; k < 2; ++k) dst[m][k] = *(const PG8_LAS bf16x8*)(lds + PG8_SA(b, h) + aoff + m * 2048 + k * 1024); } while (0)
; #define PG8_LDB(dst, b, h) do { _Pragma("unroll") for (int n = 0; n < 2; ++n) _Pragma("unroll") for (int k = 0; k < 2; ++k) dst[n][k] = *(const PG8_LAS bf16x8*)(lds + PG8_SB(b, h) + boff + n * 2048 + k * 1024); } while (0)
; #define PG8_MMA(ai, bj, At, Bt) do { __builtin_amdgcn_s_setprio(1); _Pragma("unroll") for (int m = 0; m < 4; ++m) _Pragma("unroll") for (int n = 0; n < 2; ++n) _Pragma("unroll") for (int k = 0; k < 2; ++k) \
;         acc[ai][bj][m][n] = __builtin_amdgcn_mfma_f32_16x16x32_bf16(Bt[n][k], At[m][k], acc[ai][bj][m][n], 0, 0, 0); __builtin_amdgcn_s_setprio(0); } while (0)
; #define PG8_WAIT_V(n) asm volatile("s_waitcnt vmcnt(" #n ")" ::: "memory")
; #define PG8_WAIT_L(n) asm volatile("s_waitcnt lgkmcnt(" #n ")" ::: "memory")
; #define PG8_BAR __builtin_amdgcn_s_barrier()
; #define PG8_SCHED __builtin_amdgcn_sched_barrier(0)
; template <class Epi, class Sched, bool ALIGN_EPI = false, bool SP2 = false>
; __device__ __forceinline__ void gemm_phase(PG8_LAS unsigned char* lds, const Gemm g, const Sched& S, const Epi& E, int tid_in) {
;     ...
;             PG8_LDB(B0, 0, 0); PG8_LDB(B1, 0, 1); PG8_SCHED; PG8_LDA(At, 0, 0); PG8_STAGE(PG8_SA(1, 1), a1 + hstep, voffA);
;             PG8_WAIT_V(8); PG8_WAIT_L(0); PG8_BAR; PG8_MMA(0, 0, At, B0); PG8_MMA(0, 1, At, B1); PG8_BAR; PG8_SCHED;
;     ...
;             PG8_LDA(At, 1, 1); PG8_STAGE(PG8_SB(1, 0), b3, voffB); PG8_STAGE(PG8_SB(1, 1), b3 + hstep, voffB); PG8_STAGE(PG8_SA(1, 0), a3, voffA);
;             PG8_WAIT_V(8); PG8_WAIT_L(0); PG8_BAR; PG8_MMA(1, 0, At, B0); PG8_MMA(1, 1, At, B1); PG8_BAR; PG8_SCHED;
	s_add_i32 s2, s37, s42
	v_lshl_add_u64 v[146:147], v[146:147], 0, s[64:65]
	s_mov_b32 m0, s2
	ds_read_b128 v[196:199], v167 offset:49152
	ds_read_b128 v[200:203], v167 offset:50176
	ds_read_b128 v[204:207], v167 offset:51200
	ds_read_b128 v[208:211], v167 offset:52224
	ds_read_b128 v[212:215], v167 offset:53248
	ds_read_b128 v[216:219], v167 offset:54272
	ds_read_b128 v[220:223], v167 offset:55296
	ds_read_b128 v[224:227], v167 offset:56320
	global_load_lds_dwordx4 v[146:147], off
	v_lshl_add_u64 v[146:147], v[162:163], 0, s[64:65]
	s_add_i32 m0, s2, 0x2000
	s_add_i32 s2, s91, s42
	global_load_lds_dwordx4 v[146:147], off
	v_lshl_add_u64 v[146:147], v[228:229], 0, s[64:65]
	s_mov_b32 m0, s2
	s_nop 0
	global_load_lds_dwordx4 v[146:147], off
	v_lshl_add_u64 v[146:147], v[230:231], 0, s[64:65]
	s_add_i32 m0, s2, 0x2000
	s_nop 0
	global_load_lds_dwordx4 v[146:147], off
	v_lshl_add_u64 v[146:147], v[238:239], 0, s[64:65]
	s_mov_b32 m0, s56
	s_nop 0
	global_load_lds_dwordx4 v[146:147], off
	v_lshl_add_u64 v[146:147], v[240:241], 0, s[64:65]
	s_mov_b32 m0, s57
	s_nop 0
	global_load_lds_dwordx4 v[146:147], off
	s_waitcnt vmcnt(8)
	s_waitcnt lgkmcnt(0)
	s_barrier
	s_waitcnt lgkmcnt(0)
	v_mfma_f32_16x16x32_bf16 v[60:63], v[140:143], v[196:199], v[60:63]
	v_mfma_f32_16x16x32_bf16 v[56:59], v[172:175], v[196:199], v[56:59]
	v_mfma_f32_16x16x32_bf16 v[44:47], v[140:143], v[204:207], v[44:47]
	v_mfma_f32_16x16x32_bf16 v[40:43], v[172:175], v[204:207], v[40:43]
	v_mfma_f32_16x16x32_bf16 v[28:31], v[140:143], v[212:215], v[28:31]
	v_mfma_f32_16x16x32_bf16 v[24:27], v[172:175], v[212:215], v[24:27]
	v_mfma_f32_16x16x32_bf16 v[12:15], v[140:143], v[220:223], v[12:15]
	v_mfma_f32_16x16x32_bf16 v[8:11], v[172:175], v[220:223], v[8:11]
	v_mfma_f32_16x16x32_bf16 v[60:63], v[168:171], v[200:203], v[60:63]
	v_mfma_f32_16x16x32_bf16 v[56:59], v[176:179], v[200:203], v[56:59]
	v_mfma_f32_16x16x32_bf16 v[44:47], v[168:171], v[208:211], v[44:47]
	v_mfma_f32_16x16x32_bf16 v[40:43], v[176:179], v[208:211], v[40:43]
	v_mfma_f32_16x16x32_bf16 v[28:31], v[168:171], v[216:219], v[28:31]
	v_mfma_f32_16x16x32_bf16 v[24:27], v[176:179], v[216:219], v[24:27]
	v_mfma_f32_16x16x32_bf16 v[12:15], v[168:171], v[224:227], v[12:15]
	v_mfma_f32_16x16x32_bf16 v[8:11], v[176:179], v[224:227], v[8:11]
	v_mfma_f32_16x16x32_bf16 v[52:55], v[180:183], v[196:199], v[52:55]
	v_mfma_f32_16x16x32_bf16 v[48:51], v[188:191], v[196:199], v[48:51]
	v_mfma_f32_16x16x32_bf16 v[36:39], v[180:183], v[204:207], v[36:39]
	v_mfma_f32_16x16x32_bf16 v[32:35], v[188:191], v[204:207], v[32:35]
	v_mfma_f32_16x16x32_bf16 v[20:23], v[180:183], v[212:215], v[20:23]
	v_mfma_f32_16x16x32_bf16 v[16:19], v[188:191], v[212:215], v[16:19]
	v_mfma_f32_16x16x32_bf16 v[4:7], v[180:183], v[220:223], v[4:7]
	v_mfma_f32_16x16x32_bf16 v[0:3], v[188:191], v[220:223], v[0:3]
	v_mfma_f32_16x16x32_bf16 v[52:55], v[184:187], v[200:203], v[52:55]
	v_mfma_f32_16x16x32_bf16 v[48:51], v[192:195], v[200:203], v[48:51]
	s_add_u32 s0, s0, 0x100
	v_mfma_f32_16x16x32_bf16 v[36:39], v[184:187], v[208:211], v[36:39]
	s_addc_u32 s1, s1, 0
	v_mfma_f32_16x16x32_bf16 v[32:35], v[192:195], v[208:211], v[32:35]
	s_add_u32 s22, s22, 0x100
	v_mfma_f32_16x16x32_bf16 v[20:23], v[184:187], v[216:219], v[20:23]
	s_addc_u32 s23, s23, 0
	v_mfma_f32_16x16x32_bf16 v[16:19], v[192:195], v[216:219], v[16:19]
	s_cmp_ge_i32 s36, s52
	v_mfma_f32_16x16x32_bf16 v[4:7], v[184:187], v[224:227], v[4:7]
	s_mov_b32 s6, s36
	v_mfma_f32_16x16x32_bf16 v[0:3], v[192:195], v[224:227], v[0:3]
	s_barrier
	s_cbranch_scc0 .LBB0_928
	s_branch .Lpeel_exit_g3
.LBB0_928:
	s_add_i32 s36, s6, 2
	s_add_u32 s2, s0, 0x80
	s_addc_u32 s3, s1, 0
	s_add_i32 s37, 0, 0x10000
	s_cmp_eq_u32 s60, s6
	s_cselect_b32 s7, s63, s3
	s_cselect_b32 s6, s62, s2
	v_add_u32_e32 v144, s37, v151
	s_cselect_b32 s3, s67, s23
	s_cselect_b32 s2, s66, s22
	s_add_i32 s91, 0, 0x14000
	ds_read_b128 v[140:143], v144
	ds_read_b128 v[168:171], v144 offset:1024
	ds_read_b128 v[172:175], v144 offset:2048
	ds_read_b128 v[176:179], v144 offset:3072
	v_add_u32_e32 v144, s91, v151
	ds_read_b128 v[180:183], v144
	ds_read_b128 v[184:187], v144 offset:1024
	ds_read_b128 v[188:191], v144 offset:2048
	ds_read_b128 v[192:195], v144 offset:3072
	v_lshl_add_u64 v[146:147], s[0:1], 0, v[136:137]
	s_add_i32 m0, s43, 0xc000
	ds_read_b128 v[196:199], v167
	ds_read_b128 v[200:203], v167 offset:1024
	ds_read_b128 v[204:207], v167 offset:2048
	ds_read_b128 v[208:211], v167 offset:3072
	ds_read_b128 v[212:215], v167 offset:4096
	ds_read_b128 v[216:219], v167 offset:5120
	ds_read_b128 v[220:223], v167 offset:6144
	ds_read_b128 v[224:227], v167 offset:7168
	global_load_lds_dwordx4 v[146:147], off
	v_lshl_add_u64 v[146:147], s[0:1], 0, v[138:139]
	s_add_i32 m0, s43, 0xe000
	s_nop 0
	global_load_lds_dwordx4 v[146:147], off
	s_waitcnt vmcnt(8)
	s_waitcnt lgkmcnt(0)
	s_barrier
; #define PG8_STAGE(bufoff, gbase, voff) do { _Pragma("unroll") for (int _i = 0; _i < 2; ++_i) \
;         __builtin_amdgcn_global_load_lds((const unsigned*)((const char*)(gbase) + (voff)[_i]), (PG8_LAS unsigned*)(lds + (bufoff) + ldsw + _i * 8192), 16, 0, 0); } while (0)
; #define PG8_LDA(dst, b, h) do { _Pragma("unroll") for (int m = 0; m < 4; ++m) _Pragma("unroll") for (int k = 0; k < 2; ++k) dst[m][k] = *(const PG8_LAS bf16x8*)(lds + PG8_SA(b, h) + aoff + m * 2048 + k * 1024); } while (0)
; #define PG8_LDB(dst, b, h) do { _Pragma("unroll") for (int n = 0; n < 2; ++n) _Pragma("unroll") for (int k = 0; k < 2; ++k) dst[n][k] = *(const PG8_LAS bf16x8*)(lds + PG8_SB(b, h) + boff + n * 2048 + k * 1024); } while (0)
; #define PG8_MMA(ai, bj, At, Bt) do { __builtin_amdgcn_s_setprio(1); _Pragma("unroll") for (int m = 0; m < 4; ++m) _Pragma("unroll") for (int n = 0; n < 2; ++n) _Pragma("unroll") for (int k = 0; k < 2; ++k) \
;         acc[ai][bj][m][n] = __builtin_amdgcn_mfma_f32_16x16x32_bf16(Bt[n][k], At[m][k], acc[ai][bj][m][n], 0, 0, 0); __builtin_amdgcn_s_setprio(0); } while (0)
; #define PG8_WAIT_V(n) asm volatile("s_waitcnt vmcnt(" #n ")" ::: "memory")
; #define PG8_WAIT_L(n) asm volatile("s_waitcnt lgkmcnt(" #n ")" ::: "memory")
; #define PG8_BAR __builtin_amdgcn_s_barrier()
; #define PG8_SCHED __builtin_amdgcn_sched_barrier(0)
; template <class Epi, class Sched, bool ALIGN_EPI = false, bool SP2 = false>
; __device__ __forceinline__ void gemm_phase(PG8_LAS unsigned char* lds, const Gemm g, const Sched& S, const Epi& E, int tid_in) {
;     ...
;             PG8_WAIT_V(8); PG8_WAIT_L(0); PG8_BAR; PG8_MMA(0, 0, At, B0); PG8_MMA(0, 1, At, B1); PG8_BAR; PG8_SCHED;
;             PG8_LDA(At, 0, 1); PG8_STAGE(PG8_SB(0, 0), b2, voffB); PG8_STAGE(PG8_SB(0, 1), b2 + hstep, voffB); PG8_STAGE(PG8_SA(0, 0), a2, voffA);
;             PG8_WAIT_V(8); PG8_WAIT_L(0); PG8_BAR; PG8_MMA(1, 0, At, B0); PG8_MMA(1, 1, At, B1); PG8_BAR; PG8_SCHED;
;             PG8_LDB(B0, 1, 0); PG8_LDB(B1, 1, 1); PG8_SCHED; PG8_LDA(At, 1, 0); PG8_STAGE(PG8_SA(0, 1), a2 + hstep, voffA);
;             PG8_WAIT_V(8); PG8_WAIT_L(0); PG8_BAR; PG8_MMA(0, 0, At, B0); PG8_MMA(0, 1, At, B1); PG8_BAR; PG8_SCHED;
	s_waitcnt lgkmcnt(0)
	v_mfma_f32_16x16x32_bf16 v[124:127], v[140:143], v[196:199], v[124:127]
	v_mfma_f32_16x16x32_bf16 v[120:123], v[172:175], v[196:199], v[120:123]
	v_mfma_f32_16x16x32_bf16 v[108:111], v[140:143], v[204:207], v[108:111]
	v_mfma_f32_16x16x32_bf16 v[104:107], v[172:175], v[204:207], v[104:107]
	v_mfma_f32_16x16x32_bf16 v[92:95], v[140:143], v[212:215], v[92:95]
	v_mfma_f32_16x16x32_bf16 v[88:91], v[172:175], v[212:215], v[88:91]
	v_mfma_f32_16x16x32_bf16 v[76:79], v[140:143], v[220:223], v[76:79]
	v_mfma_f32_16x16x32_bf16 v[72:75], v[172:175], v[220:223], v[72:75]
	v_mfma_f32_16x16x32_bf16 v[124:127], v[168:171], v[200:203], v[124:127]
	v_mfma_f32_16x16x32_bf16 v[120:123], v[176:179], v[200:203], v[120:123]
	v_mfma_f32_16x16x32_bf16 v[108:111], v[168:171], v[208:211], v[108:111]
	v_mfma_f32_16x16x32_bf16 v[104:107], v[176:179], v[208:211], v[104:107]
	v_mfma_f32_16x16x32_bf16 v[92:95], v[168:171], v[216:219], v[92:95]
	v_mfma_f32_16x16x32_bf16 v[88:91], v[176:179], v[216:219], v[88:91]
	v_mfma_f32_16x16x32_bf16 v[76:79], v[168:171], v[224:227], v[76:79]
	v_mfma_f32_16x16x32_bf16 v[72:75], v[176:179], v[224:227], v[72:75]
	v_mfma_f32_16x16x32_bf16 v[116:119], v[180:183], v[196:199], v[116:119]
	v_mfma_f32_16x16x32_bf16 v[112:115], v[188:191], v[196:199], v[112:115]
	v_mfma_f32_16x16x32_bf16 v[100:103], v[180:183], v[204:207], v[100:103]
	v_mfma_f32_16x16x32_bf16 v[96:99], v[188:191], v[204:207], v[96:99]
	v_mfma_f32_16x16x32_bf16 v[84:87], v[180:183], v[212:215], v[84:87]
	v_mfma_f32_16x16x32_bf16 v[80:83], v[188:191], v[212:215], v[80:83]
	v_mfma_f32_16x16x32_bf16 v[68:71], v[180:183], v[220:223], v[68:71]
	v_mfma_f32_16x16x32_bf16 v[64:67], v[188:191], v[220:223], v[64:67]
	v_mfma_f32_16x16x32_bf16 v[116:119], v[184:187], v[200:203], v[116:119]
	v_mfma_f32_16x16x32_bf16 v[112:115], v[192:195], v[200:203], v[112:115]
	v_mfma_f32_16x16x32_bf16 v[100:103], v[184:187], v[208:211], v[100:103]
	v_mfma_f32_16x16x32_bf16 v[96:99], v[192:195], v[208:211], v[96:99]
	v_mfma_f32_16x16x32_bf16 v[84:87], v[184:187], v[216:219], v[84:87]
	v_mfma_f32_16x16x32_bf16 v[80:83], v[192:195], v[216:219], v[80:83]
	v_mfma_f32_16x16x32_bf16 v[68:71], v[184:187], v[224:227], v[68:71]
	v_mfma_f32_16x16x32_bf16 v[64:67], v[192:195], v[224:227], v[64:67]
	s_barrier
	s_add_i32 s37, s37, s42
	v_lshl_add_u64 v[146:147], s[2:3], 0, v[156:157]
	s_mov_b32 m0, s37
	ds_read_b128 v[196:199], v167 offset:16384
	ds_read_b128 v[200:203], v167 offset:17408
	ds_read_b128 v[204:207], v167 offset:18432
	ds_read_b128 v[208:211], v167 offset:19456
	ds_read_b128 v[212:215], v167 offset:20480
	ds_read_b128 v[216:219], v167 offset:21504
	ds_read_b128 v[220:223], v167 offset:22528
	ds_read_b128 v[224:227], v167 offset:23552
	global_load_lds_dwordx4 v[146:147], off
	s_add_i32 m0, s37, 0x2000
	v_lshl_add_u64 v[162:163], s[2:3], 0, v[128:129]
	s_add_u32 s2, s2, s10
	s_addc_u32 s3, s3, s11
	s_add_i32 s37, s91, s42
	global_load_lds_dwordx4 v[162:163], off
	v_lshl_add_u64 v[228:229], s[2:3], 0, v[156:157]
	s_mov_b32 m0, s37
	v_lshl_add_u64 v[230:231], s[2:3], 0, v[128:129]
	global_load_lds_dwordx4 v[228:229], off
	s_add_i32 m0, s37, 0x2000
	v_lshl_add_u64 v[238:239], s[6:7], 0, v[132:133]
	global_load_lds_dwordx4 v[230:231], off
	s_mov_b32 m0, s43
	v_lshl_add_u64 v[240:241], s[6:7], 0, v[130:131]
	global_load_lds_dwordx4 v[238:239], off
	s_mov_b32 m0, s44
	s_nop 0
	global_load_lds_dwordx4 v[240:241], off
	s_waitcnt vmcnt(8)
	s_waitcnt lgkmcnt(0)
	s_barrier
	s_waitcnt lgkmcnt(0)
	v_mfma_f32_16x16x32_bf16 v[60:63], v[140:143], v[196:199], v[60:63]
	v_mfma_f32_16x16x32_bf16 v[56:59], v[172:175], v[196:199], v[56:59]
	v_mfma_f32_16x16x32_bf16 v[44:47], v[140:143], v[204:207], v[44:47]
	v_mfma_f32_16x16x32_bf16 v[40:43], v[172:175], v[204:207], v[40:43]
	v_mfma_f32_16x16x32_bf16 v[28:31], v[140:143], v[212:215], v[28:31]
	v_mfma_f32_16x16x32_bf16 v[24:27], v[172:175], v[212:215], v[24:27]
	v_mfma_f32_16x16x32_bf16 v[12:15], v[140:143], v[220:223], v[12:15]
	v_mfma_f32_16x16x32_bf16 v[8:11], v[172:175], v[220:223], v[8:11]
	v_mfma_f32_16x16x32_bf16 v[60:63], v[168:171], v[200:203], v[60:63]
	v_mfma_f32_16x16x32_bf16 v[56:59], v[176:179], v[200:203], v[56:59]
	v_mfma_f32_16x16x32_bf16 v[44:47], v[168:171], v[208:211], v[44:47]
	v_mfma_f32_16x16x32_bf16 v[40:43], v[176:179], v[208:211], v[40:43]
	v_mfma_f32_16x16x32_bf16 v[28:31], v[168:171], v[216:219], v[28:31]
	v_mfma_f32_16x16x32_bf16 v[24:27], v[176:179], v[216:219], v[24:27]
	v_mfma_f32_16x16x32_bf16 v[12:15], v[168:171], v[224:227], v[12:15]
	v_mfma_f32_16x16x32_bf16 v[8:11], v[176:179], v[224:227], v[8:11]
	v_mfma_f32_16x16x32_bf16 v[52:55], v[180:183], v[196:199], v[52:55]
	v_mfma_f32_16x16x32_bf16 v[48:51], v[188:191], v[196:199], v[48:51]
	v_mfma_f32_16x16x32_bf16 v[36:39], v[180:183], v[204:207], v[36:39]
	v_mfma_f32_16x16x32_bf16 v[32:35], v[188:191], v[204:207], v[32:35]
	v_mfma_f32_16x16x32_bf16 v[20:23], v[180:183], v[212:215], v[20:23]
	v_mfma_f32_16x16x32_bf16 v[16:19], v[188:191], v[212:215], v[16:19]
	v_mfma_f32_16x16x32_bf16 v[4:7], v[180:183], v[220:223], v[4:7]
	v_mfma_f32_16x16x32_bf16 v[0:3], v[188:191], v[220:223], v[0:3]
	v_mfma_f32_16x16x32_bf16 v[52:55], v[184:187], v[200:203], v[52:55]
	v_mfma_f32_16x16x32_bf16 v[48:51], v[192:195], v[200:203], v[48:51]
	v_mfma_f32_16x16x32_bf16 v[36:39], v[184:187], v[208:211], v[36:39]
	v_mfma_f32_16x16x32_bf16 v[32:35], v[192:195], v[208:211], v[32:35]
	v_mfma_f32_16x16x32_bf16 v[20:23], v[184:187], v[216:219], v[20:23]
	v_mfma_f32_16x16x32_bf16 v[16:19], v[192:195], v[216:219], v[16:19]
	v_mfma_f32_16x16x32_bf16 v[4:7], v[184:187], v[224:227], v[4:7]
	v_mfma_f32_16x16x32_bf16 v[0:3], v[192:195], v[224:227], v[0:3]
	s_barrier
; #define PG8_STAGE(bufoff, gbase, voff) do { _Pragma("unroll") for (int _i = 0; _i < 2; ++_i) \
;         __builtin_amdgcn_global_load_lds((const unsigned*)((const char*)(gbase) + (voff)[_i]), (PG8_LAS unsigned*)(lds + (bufoff) + ldsw + _i * 8192), 16, 0, 0); } while (0)
; #define PG8_LDA(dst, b, h) do { _Pragma("unroll") for (int m = 0; m < 4; ++m) _Pragma("unroll") for (int k = 0; k < 2; ++k) dst[m][k] = *(const PG8_LAS bf16x8*)(lds + PG8_SA(b, h) + aoff + m * 2048 + k * 1024); } while (0)
; #define PG8_LDB(dst, b, h) do { _Pragma("unroll") for (int n = 0; n < 2; ++n) _Pragma("unroll") for (int k = 0; k < 2; ++k) dst[n][k] = *(const PG8_LAS bf16x8*)(lds + PG8_SB(b, h) + boff + n * 2048 + k * 1024); } while (0)
; #define PG8_MMA(ai, bj, At, Bt) do { __builtin_amdgcn_s_setprio(1); _Pragma("unroll") for (int m = 0; m < 4; ++m) _Pragma("unroll") for (int n = 0; n < 2; ++n) _Pragma("unroll") for (int k = 0; k < 2; ++k) \
;         acc[ai][bj][m][n] = __builtin_amdgcn_mfma_f32_16x16x32_bf16(Bt[n][k], At[m][k], acc[ai][bj][m][n], 0, 0, 0); __builtin_amdgcn_s_setprio(0); } while (0)
; #define PG8_WAIT_V(n) asm volatile("s_waitcnt vmcnt(" #n ")" ::: "memory")
; #define PG8_WAIT_L(n) asm volatile("s_waitcnt lgkmcnt(" #n ")" ::: "memory")
; #define PG8_BAR __builtin_amdgcn_s_barrier()
; #define PG8_SCHED __builtin_amdgcn_sched_barrier(0)
; template <class Epi, class Sched, bool ALIGN_EPI = false, bool SP2 = false>
; __device__ __forceinline__ void gemm_phase(PG8_LAS unsigned char* lds, const Gemm g, const Sched& S, const Epi& E, int tid_in) {
;     ...
;             PG8_LDB(B0, 1, 0); PG8_LDB(B1, 1, 1); PG8_SCHED; PG8_LDA(At, 1, 0); PG8_STAGE(PG8_SA(0, 1), a2 + hstep, voffA);
;             PG8_WAIT_V(8); PG8_WAIT_L(0); PG8_BAR; PG8_MMA(0, 0, At, B0); PG8_MMA(0, 1, At, B1); PG8_BAR; PG8_SCHED;
;             PG8_LDA(At, 1, 1); PG8_STAGE(PG8_SB(1, 0), b3, voffB); PG8_STAGE(PG8_SB(1, 1), b3 + hstep, voffB); PG8_STAGE(PG8_SA(1, 0), a3, voffA);
;             PG8_WAIT_V(8); PG8_WAIT_L(0); PG8_BAR; PG8_MMA(1, 0, At, B0); PG8_MMA(1, 1, At, B1); PG8_BAR; PG8_SCHED;
	s_add_i32 s37, 0, 0x18000
	v_add_u32_e32 v144, s37, v151
	s_add_i32 s91, 0, 0x1c000
	ds_read_b128 v[140:143], v144
	ds_read_b128 v[168:171], v144 offset:1024
	ds_read_b128 v[172:175], v144 offset:2048
	ds_read_b128 v[176:179], v144 offset:3072
	v_add_u32_e32 v144, s91, v151
	ds_read_b128 v[180:183], v144
	ds_read_b128 v[184:187], v144 offset:1024
	ds_read_b128 v[188:191], v144 offset:2048
	ds_read_b128 v[192:195], v144 offset:3072
	s_add_u32 s2, s6, s10
	s_addc_u32 s3, s7, s11
	s_mov_b32 m0, s45
	v_lshl_add_u64 v[242:243], s[2:3], 0, v[132:133]
	ds_read_b128 v[196:199], v167 offset:32768
	ds_read_b128 v[200:203], v167 offset:33792
	ds_read_b128 v[204:207], v167 offset:34816
	ds_read_b128 v[208:211], v167 offset:35840
	ds_read_b128 v[212:215], v167 offset:36864
	ds_read_b128 v[216:219], v167 offset:37888
	ds_read_b128 v[220:223], v167 offset:38912
	ds_read_b128 v[224:227], v167 offset:39936
	global_load_lds_dwordx4 v[242:243], off
	v_lshl_add_u64 v[242:243], s[2:3], 0, v[130:131]
	s_mov_b32 m0, s46
	s_nop 0
	global_load_lds_dwordx4 v[242:243], off
	s_waitcnt vmcnt(8)
	s_waitcnt lgkmcnt(0)
	s_barrier
	s_waitcnt lgkmcnt(0)
	v_mfma_f32_16x16x32_bf16 v[124:127], v[140:143], v[196:199], v[124:127]
	v_mfma_f32_16x16x32_bf16 v[120:123], v[172:175], v[196:199], v[120:123]
	v_mfma_f32_16x16x32_bf16 v[108:111], v[140:143], v[204:207], v[108:111]
	v_mfma_f32_16x16x32_bf16 v[104:107], v[172:175], v[204:207], v[104:107]
	v_mfma_f32_16x16x32_bf16 v[92:95], v[140:143], v[212:215], v[92:95]
	v_mfma_f32_16x16x32_bf16 v[88:91], v[172:175], v[212:215], v[88:91]
	v_mfma_f32_16x16x32_bf16 v[76:79], v[140:143], v[220:223], v[76:79]
	v_mfma_f32_16x16x32_bf16 v[72:75], v[172:175], v[220:223], v[72:75]
	v_mfma_f32_16x16x32_bf16 v[124:127], v[168:171], v[200:203], v[124:127]
	v_mfma_f32_16x16x32_bf16 v[120:123], v[176:179], v[200:203], v[120:123]
	v_mfma_f32_16x16x32_bf16 v[108:111], v[168:171], v[208:211], v[108:111]
	v_mfma_f32_16x16x32_bf16 v[104:107], v[176:179], v[208:211], v[104:107]
	v_mfma_f32_16x16x32_bf16 v[92:95], v[168:171], v[216:219], v[92:95]
	v_mfma_f32_16x16x32_bf16 v[88:91], v[176:179], v[216:219], v[88:91]
	v_mfma_f32_16x16x32_bf16 v[76:79], v[168:171], v[224:227], v[76:79]
	v_mfma_f32_16x16x32_bf16 v[72:75], v[176:179], v[224:227], v[72:75]
	v_mfma_f32_16x16x32_bf16 v[116:119], v[180:183], v[196:199], v[116:119]
	v_mfma_f32_16x16x32_bf16 v[112:115], v[188:191], v[196:199], v[112:115]
	v_mfma_f32_16x16x32_bf16 v[100:103], v[180:183], v[204:207], v[100:103]
	v_mfma_f32_16x16x32_bf16 v[96:99], v[188:191], v[204:207], v[96:99]
	v_mfma_f32_16x16x32_bf16 v[84:87], v[180:183], v[212:215], v[84:87]
	v_mfma_f32_16x16x32_bf16 v[80:83], v[188:191], v[212:215], v[80:83]
	v_mfma_f32_16x16x32_bf16 v[68:71], v[180:183], v[220:223], v[68:71]
	v_mfma_f32_16x16x32_bf16 v[64:67], v[188:191], v[220:223], v[64:67]
	v_mfma_f32_16x16x32_bf16 v[116:119], v[184:187], v[200:203], v[116:119]
	v_mfma_f32_16x16x32_bf16 v[112:115], v[192:195], v[200:203], v[112:115]
	v_mfma_f32_16x16x32_bf16 v[100:103], v[184:187], v[208:211], v[100:103]
	v_mfma_f32_16x16x32_bf16 v[96:99], v[192:195], v[208:211], v[96:99]
	v_mfma_f32_16x16x32_bf16 v[84:87], v[184:187], v[216:219], v[84:87]
	v_mfma_f32_16x16x32_bf16 v[80:83], v[192:195], v[216:219], v[80:83]
	v_mfma_f32_16x16x32_bf16 v[68:71], v[184:187], v[224:227], v[68:71]
	v_mfma_f32_16x16x32_bf16 v[64:67], v[192:195], v[224:227], v[64:67]
	s_barrier
	s_add_i32 s2, s37, s42
	v_lshl_add_u64 v[146:147], v[146:147], 0, s[64:65]
	s_mov_b32 m0, s2
	ds_read_b128 v[196:199], v167 offset:49152
	ds_read_b128 v[200:203], v167 offset:50176
	ds_read_b128 v[204:207], v167 offset:51200
	ds_read_b128 v[208:211], v167 offset:52224
	ds_read_b128 v[212:215], v167 offset:53248
	ds_read_b128 v[216:219], v167 offset:54272
	ds_read_b128 v[220:223], v167 offset:55296
	ds_read_b128 v[224:227], v167 offset:56320
	global_load_lds_dwordx4 v[146:147], off
	v_lshl_add_u64 v[146:147], v[162:163], 0, s[64:65]
	s_add_i32 m0, s2, 0x2000
	s_add_i32 s2, s91, s42
	global_load_lds_dwordx4 v[146:147], off
	v_lshl_add_u64 v[146:147], v[228:229], 0, s[64:65]
	s_mov_b32 m0, s2
	s_nop 0
	global_load_lds_dwordx4 v[146:147], off
	v_lshl_add_u64 v[146:147], v[230:231], 0, s[64:65]
	s_add_i32 m0, s2, 0x2000
	s_nop 0
	global_load_lds_dwordx4 v[146:147], off
	v_lshl_add_u64 v[146:147], v[238:239], 0, s[64:65]
	s_mov_b32 m0, s56
	s_nop 0
	global_load_lds_dwordx4 v[146:147], off
	v_lshl_add_u64 v[146:147], v[240:241], 0, s[64:65]
	s_mov_b32 m0, s57
	s_nop 0
	global_load_lds_dwordx4 v[146:147], off
	s_waitcnt vmcnt(8)
	s_waitcnt lgkmcnt(0)
	s_barrier
	s_waitcnt lgkmcnt(0)
	v_mfma_f32_16x16x32_bf16 v[60:63], v[140:143], v[196:199], v[60:63]
	v_mfma_f32_16x16x32_bf16 v[56:59], v[172:175], v[196:199], v[56:59]
	v_mfma_f32_16x16x32_bf16 v[44:47], v[140:143], v[204:207], v[44:47]
	v_mfma_f32_16x16x32_bf16 v[40:43], v[172:175], v[204:207], v[40:43]
	v_mfma_f32_16x16x32_bf16 v[28:31], v[140:143], v[212:215], v[28:31]
	v_mfma_f32_16x16x32_bf16 v[24:27], v[172:175], v[212:215], v[24:27]
	v_mfma_f32_16x16x32_bf16 v[12:15], v[140:143], v[220:223], v[12:15]
	v_mfma_f32_16x16x32_bf16 v[8:11], v[172:175], v[220:223], v[8:11]
	v_mfma_f32_16x16x32_bf16 v[60:63], v[168:171], v[200:203], v[60:63]
	v_mfma_f32_16x16x32_bf16 v[56:59], v[176:179], v[200:203], v[56:59]
	v_mfma_f32_16x16x32_bf16 v[44:47], v[168:171], v[208:211], v[44:47]
	v_mfma_f32_16x16x32_bf16 v[40:43], v[176:179], v[208:211], v[40:43]
	v_mfma_f32_16x16x32_bf16 v[28:31], v[168:171], v[216:219], v[28:31]
	v_mfma_f32_16x16x32_bf16 v[24:27], v[176:179], v[216:219], v[24:27]
	v_mfma_f32_16x16x32_bf16 v[12:15], v[168:171], v[224:227], v[12:15]
	v_mfma_f32_16x16x32_bf16 v[8:11], v[176:179], v[224:227], v[8:11]
	v_mfma_f32_16x16x32_bf16 v[52:55], v[180:183], v[196:199], v[52:55]
	v_mfma_f32_16x16x32_bf16 v[48:51], v[188:191], v[196:199], v[48:51]
	v_mfma_f32_16x16x32_bf16 v[36:39], v[180:183], v[204:207], v[36:39]
	v_mfma_f32_16x16x32_bf16 v[32:35], v[188:191], v[204:207], v[32:35]
	v_mfma_f32_16x16x32_bf16 v[20:23], v[180:183], v[212:215], v[20:23]
	v_mfma_f32_16x16x32_bf16 v[16:19], v[188:191], v[212:215], v[16:19]
	v_mfma_f32_16x16x32_bf16 v[4:7], v[180:183], v[220:223], v[4:7]
	v_mfma_f32_16x16x32_bf16 v[0:3], v[188:191], v[220:223], v[0:3]
	v_mfma_f32_16x16x32_bf16 v[52:55], v[184:187], v[200:203], v[52:55]
	v_mfma_f32_16x16x32_bf16 v[48:51], v[192:195], v[200:203], v[48:51]
	s_add_u32 s0, s0, 0x100
	v_mfma_f32_16x16x32_bf16 v[36:39], v[184:187], v[208:211], v[36:39]
	s_addc_u32 s1, s1, 0
	v_mfma_f32_16x16x32_bf16 v[32:35], v[192:195], v[208:211], v[32:35]
	s_add_u32 s22, s22, 0x100
	v_mfma_f32_16x16x32_bf16 v[20:23], v[184:187], v[216:219], v[20:23]
	s_addc_u32 s23, s23, 0
	v_mfma_f32_16x16x32_bf16 v[16:19], v[192:195], v[216:219], v[16:19]
	s_cmp_ge_i32 s36, s52
	v_mfma_f32_16x16x32_bf16 v[4:7], v[184:187], v[224:227], v[4:7]
	s_mov_b32 s6, s36
	v_mfma_f32_16x16x32_bf16 v[0:3], v[192:195], v[224:227], v[0:3]
	s_barrier
	s_cbranch_scc0 .LBB0_928

; #define PG8_STAGE(bufoff, gbase, voff) do { _Pragma("unroll") for (int _i = 0; _i < 2; ++_i) \
;         __builtin_amdgcn_global_load_lds((const unsigned*)((const char*)(gbase) + (voff)[_i]), (PG8_LAS unsigned*)(lds + (bufoff) + ldsw + _i * 8192), 16, 0, 0); } while (0)
; #define PG8_LDA(dst, b, h) do { _Pragma("unroll") for (int m = 0; m < 4; ++m) _Pragma("unroll") for (int k = 0; k < 2; ++k) dst[m][k] = *(const PG8_LAS bf16x8*)(lds + PG8_SA(b, h) + aoff + m * 2048 + k * 1024); } while (0)
; #define PG8_LDB(dst, b, h) do { _Pragma("unroll") for (int n = 0; n < 2; ++n) _Pragma("unroll") for (int k = 0; k < 2; ++k) dst[n][k] = *(const PG8_LAS bf16x8*)(lds + PG8_SB(b, h) + boff + n * 2048 + k * 1024); } while (0)
; #define PG8_MMA(ai, bj, At, Bt) do { __builtin_amdgcn_s_setprio(1); _Pragma("unroll") for (int m = 0; m < 4; ++m) _Pragma("unroll") for (int n = 0; n < 2; ++n) _Pragma("unroll") for (int k = 0; k < 2; ++k) \
;         acc[ai][bj][m][n] = __builtin_amdgcn_mfma_f32_16x16x32_bf16(Bt[n][k], At[m][k], acc[ai][bj][m][n], 0, 0, 0); __builtin_amdgcn_s_setprio(0); } while (0)
; #define PG8_WAIT_V(n) asm volatile("s_waitcnt vmcnt(" #n ")" ::: "memory")
; #define PG8_WAIT_L(n) asm volatile("s_waitcnt lgkmcnt(" #n ")" ::: "memory")
; #define PG8_BAR __builtin_amdgcn_s_barrier()
; #define PG8_SCHED __builtin_amdgcn_sched_barrier(0)
; template <class Epi, class Sched, bool ALIGN_EPI = false, bool SP2 = false>
; __device__ __forceinline__ void gemm_phase(PG8_LAS unsigned char* lds, const Gemm g, const Sched& S, const Epi& E, int tid_in) {
;     ...
;                 for (int n = 0; n < 2; ++n) acc[a][b][m][n] = (f32x4){0.f, 0.f, 0.f, 0.f};
;     ...
;             PG8_LDB(B0, 0, 0); PG8_LDB(B1, 0, 1); PG8_SCHED; PG8_LDA(At, 0, 0); PG8_STAGE(PG8_SA(1, 1), a1 + hstep, voffA);
;             PG8_WAIT_V(8); PG8_WAIT_L(0); PG8_BAR; PG8_MMA(0, 0, At, B0); PG8_MMA(0, 1, At, B1); PG8_BAR; PG8_SCHED;
;             PG8_LDA(At, 0, 1); PG8_STAGE(PG8_SB(0, 0), b2, voffB); PG8_STAGE(PG8_SB(0, 1), b2 + hstep, voffB); PG8_STAGE(PG8_SA(0, 0), a2, voffA);
;             PG8_WAIT_V(8); PG8_WAIT_L(0); PG8_BAR; PG8_MMA(1, 0, At, B0); PG8_MMA(1, 1, At, B1); PG8_BAR; PG8_SCHED;
.Lpeel_enter_g4:
	s_add_u32 s0, s0, 0x80
	s_addc_u32 s1, s1, 0
	s_add_u32 s55, s22, 0x100
	s_addc_u32 s92, s23, 0
	s_mov_b32 s22, 0
	s_add_i32 s36, s22, 2
	s_add_u32 s37, s0, 0x80
	s_addc_u32 s23, s1, 0
	s_add_i32 s93, 0, 0x10000
	s_cmp_eq_u32 s88, s22
	s_cselect_b32 s23, s7, s23
	s_cselect_b32 s22, s6, s37
	s_cselect_b32 vcc_hi, s45, s92
	s_cselect_b32 vcc_lo, s44, s55
	s_add_i32 s37, 0, 0x14000
	v_add_u32_e32 v146, s93, v237
	v_add_u32_e32 v154, s37, v237
	ds_read_b128 v[134:137], v146
	ds_read_b128 v[138:141], v146 offset:1024
	ds_read_b128 v[142:145], v146 offset:2048
	ds_read_b128 v[146:149], v146 offset:3072
	ds_read_b128 v[150:153], v154
	ds_read_b128 v[166:169], v154 offset:1024
	ds_read_b128 v[170:173], v154 offset:2048
	ds_read_b128 v[174:177], v154 offset:3072
	v_lshl_add_u64 v[154:155], s[0:1], 0, v[130:131]
	s_add_i32 m0, s47, 0xc000
	ds_read_b128 v[178:181], v241
	ds_read_b128 v[182:185], v241 offset:1024
	ds_read_b128 v[186:189], v241 offset:2048
	ds_read_b128 v[190:193], v241 offset:3072
	ds_read_b128 v[194:197], v241 offset:4096
	ds_read_b128 v[198:201], v241 offset:5120
	ds_read_b128 v[202:205], v241 offset:6144
	ds_read_b128 v[206:209], v241 offset:7168
	global_load_lds_dwordx4 v[154:155], off
	v_lshl_add_u64 v[154:155], s[0:1], 0, v[132:133]
	s_add_i32 m0, s47, 0xe000
	s_nop 0
	global_load_lds_dwordx4 v[154:155], off
	s_waitcnt vmcnt(8)
	s_waitcnt lgkmcnt(0)
	s_barrier
	s_waitcnt lgkmcnt(0)
	v_mfma_f32_16x16x32_bf16 v[124:127], v[134:137], v[178:181], 0
	v_mfma_f32_16x16x32_bf16 v[120:123], v[142:145], v[178:181], 0
	v_mfma_f32_16x16x32_bf16 v[108:111], v[134:137], v[186:189], 0
	v_mfma_f32_16x16x32_bf16 v[104:107], v[142:145], v[186:189], 0
	v_mfma_f32_16x16x32_bf16 v[92:95], v[134:137], v[194:197], 0
	v_mfma_f32_16x16x32_bf16 v[88:91], v[142:145], v[194:197], 0
	v_mfma_f32_16x16x32_bf16 v[76:79], v[134:137], v[202:205], 0
	v_mfma_f32_16x16x32_bf16 v[72:75], v[142:145], v[202:205], 0
	v_mfma_f32_16x16x32_bf16 v[124:127], v[138:141], v[182:185], v[124:127]
	v_mfma_f32_16x16x32_bf16 v[120:123], v[146:149], v[182:185], v[120:123]
	v_mfma_f32_16x16x32_bf16 v[108:111], v[138:141], v[190:193], v[108:111]
	v_mfma_f32_16x16x32_bf16 v[104:107], v[146:149], v[190:193], v[104:107]
	v_mfma_f32_16x16x32_bf16 v[92:95], v[138:141], v[198:201], v[92:95]
	v_mfma_f32_16x16x32_bf16 v[88:91], v[146:149], v[198:201], v[88:91]
	v_mfma_f32_16x16x32_bf16 v[76:79], v[138:141], v[206:209], v[76:79]
	v_mfma_f32_16x16x32_bf16 v[72:75], v[146:149], v[206:209], v[72:75]
	v_mfma_f32_16x16x32_bf16 v[116:119], v[150:153], v[178:181], 0
	v_mfma_f32_16x16x32_bf16 v[112:115], v[170:173], v[178:181], 0
	v_mfma_f32_16x16x32_bf16 v[100:103], v[150:153], v[186:189], 0
	v_mfma_f32_16x16x32_bf16 v[96:99], v[170:173], v[186:189], 0
	v_mfma_f32_16x16x32_bf16 v[84:87], v[150:153], v[194:197], 0
	v_mfma_f32_16x16x32_bf16 v[80:83], v[170:173], v[194:197], 0
	v_mfma_f32_16x16x32_bf16 v[68:71], v[150:153], v[202:205], 0
	v_mfma_f32_16x16x32_bf16 v[64:67], v[170:173], v[202:205], 0
	v_mfma_f32_16x16x32_bf16 v[116:119], v[166:169], v[182:185], v[116:119]
	v_mfma_f32_16x16x32_bf16 v[112:115], v[174:177], v[182:185], v[112:115]
	v_mfma_f32_16x16x32_bf16 v[100:103], v[166:169], v[190:193], v[100:103]
	v_mfma_f32_16x16x32_bf16 v[96:99], v[174:177], v[190:193], v[96:99]
	v_mfma_f32_16x16x32_bf16 v[84:87], v[166:169], v[198:201], v[84:87]
	v_mfma_f32_16x16x32_bf16 v[80:83], v[174:177], v[198:201], v[80:83]
	v_mfma_f32_16x16x32_bf16 v[68:71], v[166:169], v[206:209], v[68:71]
	v_mfma_f32_16x16x32_bf16 v[64:67], v[174:177], v[206:209], v[64:67]
	s_barrier
	s_add_i32 s93, s93, s46
	v_lshl_add_u64 v[154:155], vcc, 0, v[156:157]
	s_mov_b32 m0, s93
	ds_read_b128 v[178:181], v241 offset:16384
	ds_read_b128 v[182:185], v241 offset:17408
	ds_read_b128 v[186:189], v241 offset:18432
	ds_read_b128 v[190:193], v241 offset:19456
	ds_read_b128 v[194:197], v241 offset:20480
	ds_read_b128 v[198:201], v241 offset:21504
	ds_read_b128 v[202:205], v241 offset:22528
	ds_read_b128 v[206:209], v241 offset:23552
	global_load_lds_dwordx4 v[154:155], off
	s_add_i32 m0, s93, 0x2000
	v_lshl_add_u64 v[162:163], vcc, 0, v[128:129]
	s_add_u32 vcc_lo, vcc_lo, s10
	s_addc_u32 vcc_hi, vcc_hi, s11
	s_add_i32 s37, s37, s46
	global_load_lds_dwordx4 v[162:163], off
	v_lshl_add_u64 v[210:211], vcc, 0, v[156:157]
	s_mov_b32 m0, s37
	v_lshl_add_u64 v[212:213], vcc, 0, v[128:129]
	global_load_lds_dwordx4 v[210:211], off
	s_add_i32 m0, s37, 0x2000
	v_lshl_add_u64 v[214:215], s[22:23], 0, v[156:157]
	global_load_lds_dwordx4 v[212:213], off
	s_mov_b32 m0, s47
	v_lshl_add_u64 v[216:217], s[22:23], 0, v[128:129]
	global_load_lds_dwordx4 v[214:215], off
	s_mov_b32 m0, s52
	s_nop 0
	global_load_lds_dwordx4 v[216:217], off
	s_waitcnt vmcnt(8)
	s_waitcnt lgkmcnt(0)
	s_barrier
; #define PG8_STAGE(bufoff, gbase, voff) do { _Pragma("unroll") for (int _i = 0; _i < 2; ++_i) \
;         __builtin_amdgcn_global_load_lds((const unsigned*)((const char*)(gbase) + (voff)[_i]), (PG8_LAS unsigned*)(lds + (bufoff) + ldsw + _i * 8192), 16, 0, 0); } while (0)
; #define PG8_LDA(dst, b, h) do { _Pragma("unroll") for (int m = 0; m < 4; ++m) _Pragma("unroll") for (int k = 0; k < 2; ++k) dst[m][k] = *(const PG8_LAS bf16x8*)(lds + PG8_SA(b, h) + aoff + m * 2048 + k * 1024); } while (0)
; #define PG8_LDB(dst, b, h) do { _Pragma("unroll") for (int n = 0; n < 2; ++n) _Pragma("unroll") for (int k = 0; k < 2; ++k) dst[n][k] = *(const PG8_LAS bf16x8*)(lds + PG8_SB(b, h) + boff + n * 2048 + k * 1024); } while (0)
; #define PG8_MMA(ai, bj, At, Bt) do { __builtin_amdgcn_s_setprio(1); _Pragma("unroll") for (int m = 0; m < 4; ++m) _Pragma("unroll") for (int n = 0; n < 2; ++n) _Pragma("unroll") for (int k = 0; k < 2; ++k) \
;         acc[ai][bj][m][n] = __builtin_amdgcn_mfma_f32_16x16x32_bf16(Bt[n][k], At[m][k], acc[ai][bj][m][n], 0, 0, 0); __builtin_amdgcn_s_setprio(0); } while (0)
; #define PG8_WAIT_V(n) asm volatile("s_waitcnt vmcnt(" #n ")" ::: "memory")
; #define PG8_WAIT_L(n) asm volatile("s_waitcnt lgkmcnt(" #n ")" ::: "memory")
; #define PG8_BAR __builtin_amdgcn_s_barrier()
; #define PG8_SCHED __builtin_amdgcn_sched_barrier(0)
; template <class Epi, class Sched, bool ALIGN_EPI = false, bool SP2 = false>
; __device__ __forceinline__ void gemm_phase(PG8_LAS unsigned char* lds, const Gemm g, const Sched& S, const Epi& E, int tid_in) {
;     ...
;             PG8_WAIT_V(8); PG8_WAIT_L(0); PG8_BAR; PG8_MMA(1, 0, At, B0); PG8_MMA(1, 1, At, B1); PG8_BAR; PG8_SCHED;
;             PG8_LDB(B0, 1, 0); PG8_LDB(B1, 1, 1); PG8_SCHED; PG8_LDA(At, 1, 0); PG8_STAGE(PG8_SA(0, 1), a2 + hstep, voffA);
;             PG8_WAIT_V(8); PG8_WAIT_L(0); PG8_BAR; PG8_MMA(0, 0, At, B0); PG8_MMA(0, 1, At, B1); PG8_BAR; PG8_SCHED;
	s_waitcnt lgkmcnt(0)
	v_mfma_f32_16x16x32_bf16 v[60:63], v[134:137], v[178:181], 0
	v_mfma_f32_16x16x32_bf16 v[56:59], v[142:145], v[178:181], 0
	v_mfma_f32_16x16x32_bf16 v[44:47], v[134:137], v[186:189], 0
	v_mfma_f32_16x16x32_bf16 v[40:43], v[142:145], v[186:189], 0
	v_mfma_f32_16x16x32_bf16 v[28:31], v[134:137], v[194:197], 0
	v_mfma_f32_16x16x32_bf16 v[24:27], v[142:145], v[194:197], 0
	v_mfma_f32_16x16x32_bf16 v[12:15], v[134:137], v[202:205], 0
	v_mfma_f32_16x16x32_bf16 v[8:11], v[142:145], v[202:205], 0
	v_mfma_f32_16x16x32_bf16 v[60:63], v[138:141], v[182:185], v[60:63]
	v_mfma_f32_16x16x32_bf16 v[56:59], v[146:149], v[182:185], v[56:59]
	v_mfma_f32_16x16x32_bf16 v[44:47], v[138:141], v[190:193], v[44:47]
	v_mfma_f32_16x16x32_bf16 v[40:43], v[146:149], v[190:193], v[40:43]
	v_mfma_f32_16x16x32_bf16 v[28:31], v[138:141], v[198:201], v[28:31]
	v_mfma_f32_16x16x32_bf16 v[24:27], v[146:149], v[198:201], v[24:27]
	v_mfma_f32_16x16x32_bf16 v[12:15], v[138:141], v[206:209], v[12:15]
	v_mfma_f32_16x16x32_bf16 v[8:11], v[146:149], v[206:209], v[8:11]
	v_mfma_f32_16x16x32_bf16 v[52:55], v[150:153], v[178:181], 0
	v_mfma_f32_16x16x32_bf16 v[48:51], v[170:173], v[178:181], 0
	v_mfma_f32_16x16x32_bf16 v[36:39], v[150:153], v[186:189], 0
	v_mfma_f32_16x16x32_bf16 v[32:35], v[170:173], v[186:189], 0
	v_mfma_f32_16x16x32_bf16 v[20:23], v[150:153], v[194:197], 0
	v_mfma_f32_16x16x32_bf16 v[16:19], v[170:173], v[194:197], 0
	v_mfma_f32_16x16x32_bf16 v[4:7], v[150:153], v[202:205], 0
	v_mfma_f32_16x16x32_bf16 v[0:3], v[170:173], v[202:205], 0
	v_mfma_f32_16x16x32_bf16 v[52:55], v[166:169], v[182:185], v[52:55]
	v_mfma_f32_16x16x32_bf16 v[48:51], v[174:177], v[182:185], v[48:51]
	v_mfma_f32_16x16x32_bf16 v[36:39], v[166:169], v[190:193], v[36:39]
	v_mfma_f32_16x16x32_bf16 v[32:35], v[174:177], v[190:193], v[32:35]
	v_mfma_f32_16x16x32_bf16 v[20:23], v[166:169], v[198:201], v[20:23]
	v_mfma_f32_16x16x32_bf16 v[16:19], v[174:177], v[198:201], v[16:19]
	v_mfma_f32_16x16x32_bf16 v[4:7], v[166:169], v[206:209], v[4:7]
	v_mfma_f32_16x16x32_bf16 v[0:3], v[174:177], v[206:209], v[0:3]
	s_barrier
	s_add_i32 s37, 0, 0x18000
	s_add_i32 s93, 0, 0x1c000
	v_add_u32_e32 v146, s37, v237
	v_add_u32_e32 v174, s93, v237
	ds_read_b128 v[134:137], v146
	ds_read_b128 v[138:141], v146 offset:1024
	ds_read_b128 v[142:145], v146 offset:2048
	ds_read_b128 v[146:149], v146 offset:3072
	ds_read_b128 v[150:153], v174
	ds_read_b128 v[166:169], v174 offset:1024
	ds_read_b128 v[170:173], v174 offset:2048
	ds_read_b128 v[174:177], v174 offset:3072
	s_add_u32 s22, s22, s10
	s_addc_u32 s23, s23, s11
	s_mov_b32 m0, s53
	v_lshl_add_u64 v[218:219], s[22:23], 0, v[156:157]
	ds_read_b128 v[178:181], v241 offset:32768
	ds_read_b128 v[182:185], v241 offset:33792
	ds_read_b128 v[186:189], v241 offset:34816
	ds_read_b128 v[190:193], v241 offset:35840
	ds_read_b128 v[194:197], v241 offset:36864
	ds_read_b128 v[198:201], v241 offset:37888
	ds_read_b128 v[202:205], v241 offset:38912
	ds_read_b128 v[206:209], v241 offset:39936
	global_load_lds_dwordx4 v[218:219], off
	v_lshl_add_u64 v[218:219], s[22:23], 0, v[128:129]
	s_mov_b32 m0, s56
	s_nop 0
	global_load_lds_dwordx4 v[218:219], off
	s_waitcnt vmcnt(8)
	s_waitcnt lgkmcnt(0)
	s_barrier
	s_waitcnt lgkmcnt(0)
	v_mfma_f32_16x16x32_bf16 v[124:127], v[134:137], v[178:181], v[124:127]
	v_mfma_f32_16x16x32_bf16 v[120:123], v[142:145], v[178:181], v[120:123]
	v_mfma_f32_16x16x32_bf16 v[108:111], v[134:137], v[186:189], v[108:111]
	v_mfma_f32_16x16x32_bf16 v[104:107], v[142:145], v[186:189], v[104:107]
	v_mfma_f32_16x16x32_bf16 v[92:95], v[134:137], v[194:197], v[92:95]
	v_mfma_f32_16x16x32_bf16 v[88:91], v[142:145], v[194:197], v[88:91]
	v_mfma_f32_16x16x32_bf16 v[76:79], v[134:137], v[202:205], v[76:79]
	v_mfma_f32_16x16x32_bf16 v[72:75], v[142:145], v[202:205], v[72:75]
	v_mfma_f32_16x16x32_bf16 v[124:127], v[138:141], v[182:185], v[124:127]
	v_mfma_f32_16x16x32_bf16 v[120:123], v[146:149], v[182:185], v[120:123]
	v_mfma_f32_16x16x32_bf16 v[108:111], v[138:141], v[190:193], v[108:111]
	v_mfma_f32_16x16x32_bf16 v[104:107], v[146:149], v[190:193], v[104:107]
	v_mfma_f32_16x16x32_bf16 v[92:95], v[138:141], v[198:201], v[92:95]
	v_mfma_f32_16x16x32_bf16 v[88:91], v[146:149], v[198:201], v[88:91]
	v_mfma_f32_16x16x32_bf16 v[76:79], v[138:141], v[206:209], v[76:79]
	v_mfma_f32_16x16x32_bf16 v[72:75], v[146:149], v[206:209], v[72:75]
	v_mfma_f32_16x16x32_bf16 v[116:119], v[150:153], v[178:181], v[116:119]
	v_mfma_f32_16x16x32_bf16 v[112:115], v[170:173], v[178:181], v[112:115]
	v_mfma_f32_16x16x32_bf16 v[100:103], v[150:153], v[186:189], v[100:103]
	v_mfma_f32_16x16x32_bf16 v[96:99], v[170:173], v[186:189], v[96:99]
	v_mfma_f32_16x16x32_bf16 v[84:87], v[150:153], v[194:197], v[84:87]
	v_mfma_f32_16x16x32_bf16 v[80:83], v[170:173], v[194:197], v[80:83]
	v_mfma_f32_16x16x32_bf16 v[68:71], v[150:153], v[202:205], v[68:71]
	v_mfma_f32_16x16x32_bf16 v[64:67], v[170:173], v[202:205], v[64:67]
	v_mfma_f32_16x16x32_bf16 v[116:119], v[166:169], v[182:185], v[116:119]
	v_mfma_f32_16x16x32_bf16 v[112:115], v[174:177], v[182:185], v[112:115]
	v_mfma_f32_16x16x32_bf16 v[100:103], v[166:169], v[190:193], v[100:103]
	v_mfma_f32_16x16x32_bf16 v[96:99], v[174:177], v[190:193], v[96:99]
	v_mfma_f32_16x16x32_bf16 v[84:87], v[166:169], v[198:201], v[84:87]
	v_mfma_f32_16x16x32_bf16 v[80:83], v[174:177], v[198:201], v[80:83]
	v_mfma_f32_16x16x32_bf16 v[68:71], v[166:169], v[206:209], v[68:71]
	v_mfma_f32_16x16x32_bf16 v[64:67], v[174:177], v[206:209], v[64:67]
	s_barrier
; #define PG8_STAGE(bufoff, gbase, voff) do { _Pragma("unroll") for (int _i = 0; _i < 2; ++_i) \
;         __builtin_amdgcn_global_load_lds((const unsigned*)((const char*)(gbase) + (voff)[_i]), (PG8_LAS unsigned*)(lds + (bufoff) + ldsw + _i * 8192), 16, 0, 0); } while (0)
; #define PG8_LDA(dst, b, h) do { _Pragma("unroll") for (int m = 0; m < 4; ++m) _Pragma("unroll") for (int k = 0; k < 2; ++k) dst[m][k] = *(const PG8_LAS bf16x8*)(lds + PG8_SA(b, h) + aoff + m * 2048 + k * 1024); } while (0)
; #define PG8_LDB(dst, b, h) do { _Pragma("unroll") for (int n = 0; n < 2; ++n) _Pragma("unroll") for (int k = 0; k < 2; ++k) dst[n][k] = *(const PG8_LAS bf16x8*)(lds + PG8_SB(b, h) + boff + n * 2048 + k * 1024); } while (0)
; #define PG8_MMA(ai, bj, At, Bt) do { __builtin_amdgcn_s_setprio(1); _Pragma("unroll") for (int m = 0; m < 4; ++m) _Pragma("unroll") for (int n = 0; n < 2; ++n) _Pragma("unroll") for (int k = 0; k < 2; ++k) \
;         acc[ai][bj][m][n] = __builtin_amdgcn_mfma_f32_16x16x32_bf16(Bt[n][k], At[m][k], acc[ai][bj][m][n], 0, 0, 0); __builtin_amdgcn_s_setprio(0); } while (0)
; #define PG8_WAIT_V(n) asm volatile("s_waitcnt vmcnt(" #n ")" ::: "memory")
; #define PG8_WAIT_L(n) asm volatile("s_waitcnt lgkmcnt(" #n ")" ::: "memory")
; #define PG8_BAR __builtin_amdgcn_s_barrier()
; #define PG8_SCHED __builtin_amdgcn_sched_barrier(0)
; template <class Epi, class Sched, bool ALIGN_EPI = false, bool SP2 = false>
; __device__ __forceinline__ void gemm_phase(PG8_LAS unsigned char* lds, const Gemm g, const Sched& S, const Epi& E, int tid_in) {
;     ...
;             PG8_LDB(B0, 0, 0); PG8_LDB(B1, 0, 1); PG8_SCHED; PG8_LDA(At, 0, 0); PG8_STAGE(PG8_SA(1, 1), a1 + hstep, voffA);
;             PG8_WAIT_V(8); PG8_WAIT_L(0); PG8_BAR; PG8_MMA(0, 0, At, B0); PG8_MMA(0, 1, At, B1); PG8_BAR; PG8_SCHED;
;     ...
;             PG8_LDA(At, 1, 1); PG8_STAGE(PG8_SB(1, 0), b3, voffB); PG8_STAGE(PG8_SB(1, 1), b3 + hstep, voffB); PG8_STAGE(PG8_SA(1, 0), a3, voffA);
;             PG8_WAIT_V(8); PG8_WAIT_L(0); PG8_BAR; PG8_MMA(1, 0, At, B0); PG8_MMA(1, 1, At, B1); PG8_BAR; PG8_SCHED;
	s_add_i32 s22, s37, s46
	v_lshl_add_u64 v[154:155], v[154:155], 0, s[64:65]
	s_mov_b32 m0, s22
	ds_read_b128 v[178:181], v241 offset:49152
	ds_read_b128 v[182:185], v241 offset:50176
	ds_read_b128 v[186:189], v241 offset:51200
	ds_read_b128 v[190:193], v241 offset:52224
	ds_read_b128 v[194:197], v241 offset:53248
	ds_read_b128 v[198:201], v241 offset:54272
	ds_read_b128 v[202:205], v241 offset:55296
	ds_read_b128 v[206:209], v241 offset:56320
	global_load_lds_dwordx4 v[154:155], off
	v_lshl_add_u64 v[154:155], v[162:163], 0, s[64:65]
	s_add_i32 m0, s22, 0x2000
	s_add_i32 s22, s93, s46
	global_load_lds_dwordx4 v[154:155], off
	v_lshl_add_u64 v[154:155], v[210:211], 0, s[64:65]
	s_mov_b32 m0, s22
	s_nop 0
	global_load_lds_dwordx4 v[154:155], off
	v_lshl_add_u64 v[154:155], v[212:213], 0, s[64:65]
	s_add_i32 m0, s22, 0x2000
	s_nop 0
	global_load_lds_dwordx4 v[154:155], off
	v_lshl_add_u64 v[154:155], v[214:215], 0, s[64:65]
	s_mov_b32 m0, s66
	s_nop 0
	global_load_lds_dwordx4 v[154:155], off
	v_lshl_add_u64 v[154:155], v[216:217], 0, s[64:65]
	s_mov_b32 m0, s67
	s_nop 0
	global_load_lds_dwordx4 v[154:155], off
	s_waitcnt vmcnt(8)
	s_waitcnt lgkmcnt(0)
	s_barrier
	s_waitcnt lgkmcnt(0)
	v_mfma_f32_16x16x32_bf16 v[60:63], v[134:137], v[178:181], v[60:63]
	v_mfma_f32_16x16x32_bf16 v[56:59], v[142:145], v[178:181], v[56:59]
	v_mfma_f32_16x16x32_bf16 v[44:47], v[134:137], v[186:189], v[44:47]
	v_mfma_f32_16x16x32_bf16 v[40:43], v[142:145], v[186:189], v[40:43]
	v_mfma_f32_16x16x32_bf16 v[28:31], v[134:137], v[194:197], v[28:31]
	v_mfma_f32_16x16x32_bf16 v[24:27], v[142:145], v[194:197], v[24:27]
	v_mfma_f32_16x16x32_bf16 v[12:15], v[134:137], v[202:205], v[12:15]
	v_mfma_f32_16x16x32_bf16 v[8:11], v[142:145], v[202:205], v[8:11]
	v_mfma_f32_16x16x32_bf16 v[60:63], v[138:141], v[182:185], v[60:63]
	v_mfma_f32_16x16x32_bf16 v[56:59], v[146:149], v[182:185], v[56:59]
	v_mfma_f32_16x16x32_bf16 v[44:47], v[138:141], v[190:193], v[44:47]
	v_mfma_f32_16x16x32_bf16 v[40:43], v[146:149], v[190:193], v[40:43]
	v_mfma_f32_16x16x32_bf16 v[28:31], v[138:141], v[198:201], v[28:31]
	v_mfma_f32_16x16x32_bf16 v[24:27], v[146:149], v[198:201], v[24:27]
	v_mfma_f32_16x16x32_bf16 v[12:15], v[138:141], v[206:209], v[12:15]
	v_mfma_f32_16x16x32_bf16 v[8:11], v[146:149], v[206:209], v[8:11]
	v_mfma_f32_16x16x32_bf16 v[52:55], v[150:153], v[178:181], v[52:55]
	v_mfma_f32_16x16x32_bf16 v[48:51], v[170:173], v[178:181], v[48:51]
	v_mfma_f32_16x16x32_bf16 v[36:39], v[150:153], v[186:189], v[36:39]
	v_mfma_f32_16x16x32_bf16 v[32:35], v[170:173], v[186:189], v[32:35]
	v_mfma_f32_16x16x32_bf16 v[20:23], v[150:153], v[194:197], v[20:23]
	v_mfma_f32_16x16x32_bf16 v[16:19], v[170:173], v[194:197], v[16:19]
	v_mfma_f32_16x16x32_bf16 v[4:7], v[150:153], v[202:205], v[4:7]
	v_mfma_f32_16x16x32_bf16 v[0:3], v[170:173], v[202:205], v[0:3]
	v_mfma_f32_16x16x32_bf16 v[52:55], v[166:169], v[182:185], v[52:55]
	v_mfma_f32_16x16x32_bf16 v[48:51], v[174:177], v[182:185], v[48:51]
	s_add_u32 s0, s0, 0x100
	v_mfma_f32_16x16x32_bf16 v[36:39], v[166:169], v[190:193], v[36:39]
	s_addc_u32 s1, s1, 0
	v_mfma_f32_16x16x32_bf16 v[32:35], v[174:177], v[190:193], v[32:35]
	s_add_u32 s55, s55, 0x100
	v_mfma_f32_16x16x32_bf16 v[20:23], v[166:169], v[198:201], v[20:23]
	s_addc_u32 s92, s92, 0
	v_mfma_f32_16x16x32_bf16 v[16:19], v[174:177], v[198:201], v[16:19]
	s_cmp_ge_i32 s36, s63
	v_mfma_f32_16x16x32_bf16 v[4:7], v[166:169], v[206:209], v[4:7]
	s_mov_b32 s22, s36
	v_mfma_f32_16x16x32_bf16 v[0:3], v[174:177], v[206:209], v[0:3]
	s_barrier
	s_cbranch_scc0 .LBB0_1024
	s_branch .Lpeel_exit_g4
.LBB0_1024:
	s_add_i32 s36, s22, 2
	s_add_u32 s37, s0, 0x80
	s_addc_u32 s23, s1, 0
	s_add_i32 s93, 0, 0x10000
	s_cmp_eq_u32 s88, s22
	s_cselect_b32 s23, s7, s23
	s_cselect_b32 s22, s6, s37
	s_cselect_b32 vcc_hi, s45, s92
	s_cselect_b32 vcc_lo, s44, s55
	s_add_i32 s37, 0, 0x14000
	v_add_u32_e32 v146, s93, v237
	v_add_u32_e32 v154, s37, v237
	ds_read_b128 v[134:137], v146
	ds_read_b128 v[138:141], v146 offset:1024
	ds_read_b128 v[142:145], v146 offset:2048
	ds_read_b128 v[146:149], v146 offset:3072
	ds_read_b128 v[150:153], v154
	ds_read_b128 v[166:169], v154 offset:1024
	ds_read_b128 v[170:173], v154 offset:2048
	ds_read_b128 v[174:177], v154 offset:3072
	v_lshl_add_u64 v[154:155], s[0:1], 0, v[130:131]
	s_add_i32 m0, s47, 0xc000
	ds_read_b128 v[178:181], v241
	ds_read_b128 v[182:185], v241 offset:1024
	ds_read_b128 v[186:189], v241 offset:2048
	ds_read_b128 v[190:193], v241 offset:3072
	ds_read_b128 v[194:197], v241 offset:4096
	ds_read_b128 v[198:201], v241 offset:5120
	ds_read_b128 v[202:205], v241 offset:6144
	ds_read_b128 v[206:209], v241 offset:7168
	global_load_lds_dwordx4 v[154:155], off
	v_lshl_add_u64 v[154:155], s[0:1], 0, v[132:133]
	s_add_i32 m0, s47, 0xe000
	s_nop 0
	global_load_lds_dwordx4 v[154:155], off
	s_waitcnt vmcnt(8)
	s_waitcnt lgkmcnt(0)
	s_barrier
; #define PG8_STAGE(bufoff, gbase, voff) do { _Pragma("unroll") for (int _i = 0; _i < 2; ++_i) \
;         __builtin_amdgcn_global_load_lds((const unsigned*)((const char*)(gbase) + (voff)[_i]), (PG8_LAS unsigned*)(lds + (bufoff) + ldsw + _i * 8192), 16, 0, 0); } while (0)
; #define PG8_LDA(dst, b, h) do { _Pragma("unroll") for (int m = 0; m < 4; ++m) _Pragma("unroll") for (int k = 0; k < 2; ++k) dst[m][k] = *(const PG8_LAS bf16x8*)(lds + PG8_SA(b, h) + aoff + m * 2048 + k * 1024); } while (0)
; #define PG8_LDB(dst, b, h) do { _Pragma("unroll") for (int n = 0; n < 2; ++n) _Pragma("unroll") for (int k = 0; k < 2; ++k) dst[n][k] = *(const PG8_LAS bf16x8*)(lds + PG8_SB(b, h) + boff + n * 2048 + k * 1024); } while (0)
; #define PG8_MMA(ai, bj, At, Bt) do { __builtin_amdgcn_s_setprio(1); _Pragma("unroll") for (int m = 0; m < 4; ++m) _Pragma("unroll") for (int n = 0; n < 2; ++n) _Pragma("unroll") for (int k = 0; k < 2; ++k) \
;         acc[ai][bj][m][n] = __builtin_amdgcn_mfma_f32_16x16x32_bf16(Bt[n][k], At[m][k], acc[ai][bj][m][n], 0, 0, 0); __builtin_amdgcn_s_setprio(0); } while (0)
; #define PG8_WAIT_V(n) asm volatile("s_waitcnt vmcnt(" #n ")" ::: "memory")
; #define PG8_WAIT_L(n) asm volatile("s_waitcnt lgkmcnt(" #n ")" ::: "memory")
; #define PG8_BAR __builtin_amdgcn_s_barrier()
; #define PG8_SCHED __builtin_amdgcn_sched_barrier(0)
; template <class Epi, class Sched, bool ALIGN_EPI = false, bool SP2 = false>
; __device__ __forceinline__ void gemm_phase(PG8_LAS unsigned char* lds, const Gemm g, const Sched& S, const Epi& E, int tid_in) {
;     ...
;             PG8_WAIT_V(8); PG8_WAIT_L(0); PG8_BAR; PG8_MMA(0, 0, At, B0); PG8_MMA(0, 1, At, B1); PG8_BAR; PG8_SCHED;
;             PG8_LDA(At, 0, 1); PG8_STAGE(PG8_SB(0, 0), b2, voffB); PG8_STAGE(PG8_SB(0, 1), b2 + hstep, voffB); PG8_STAGE(PG8_SA(0, 0), a2, voffA);
;             PG8_WAIT_V(8); PG8_WAIT_L(0); PG8_BAR; PG8_MMA(1, 0, At, B0); PG8_MMA(1, 1, At, B1); PG8_BAR; PG8_SCHED;
;             PG8_LDB(B0, 1, 0); PG8_LDB(B1, 1, 1); PG8_SCHED; PG8_LDA(At, 1, 0); PG8_STAGE(PG8_SA(0, 1), a2 + hstep, voffA);
;             PG8_WAIT_V(8); PG8_WAIT_L(0); PG8_BAR; PG8_MMA(0, 0, At, B0); PG8_MMA(0, 1, At, B1); PG8_BAR; PG8_SCHED;
	s_waitcnt lgkmcnt(0)
	v_mfma_f32_16x16x32_bf16 v[124:127], v[134:137], v[178:181], v[124:127]
	v_mfma_f32_16x16x32_bf16 v[120:123], v[142:145], v[178:181], v[120:123]
	v_mfma_f32_16x16x32_bf16 v[108:111], v[134:137], v[186:189], v[108:111]
	v_mfma_f32_16x16x32_bf16 v[104:107], v[142:145], v[186:189], v[104:107]
	v_mfma_f32_16x16x32_bf16 v[92:95], v[134:137], v[194:197], v[92:95]
	v_mfma_f32_16x16x32_bf16 v[88:91], v[142:145], v[194:197], v[88:91]
	v_mfma_f32_16x16x32_bf16 v[76:79], v[134:137], v[202:205], v[76:79]
	v_mfma_f32_16x16x32_bf16 v[72:75], v[142:145], v[202:205], v[72:75]
	v_mfma_f32_16x16x32_bf16 v[124:127], v[138:141], v[182:185], v[124:127]
	v_mfma_f32_16x16x32_bf16 v[120:123], v[146:149], v[182:185], v[120:123]
	v_mfma_f32_16x16x32_bf16 v[108:111], v[138:141], v[190:193], v[108:111]
	v_mfma_f32_16x16x32_bf16 v[104:107], v[146:149], v[190:193], v[104:107]
	v_mfma_f32_16x16x32_bf16 v[92:95], v[138:141], v[198:201], v[92:95]
	v_mfma_f32_16x16x32_bf16 v[88:91], v[146:149], v[198:201], v[88:91]
	v_mfma_f32_16x16x32_bf16 v[76:79], v[138:141], v[206:209], v[76:79]
	v_mfma_f32_16x16x32_bf16 v[72:75], v[146:149], v[206:209], v[72:75]
	v_mfma_f32_16x16x32_bf16 v[116:119], v[150:153], v[178:181], v[116:119]
	v_mfma_f32_16x16x32_bf16 v[112:115], v[170:173], v[178:181], v[112:115]
	v_mfma_f32_16x16x32_bf16 v[100:103], v[150:153], v[186:189], v[100:103]
	v_mfma_f32_16x16x32_bf16 v[96:99], v[170:173], v[186:189], v[96:99]
	v_mfma_f32_16x16x32_bf16 v[84:87], v[150:153], v[194:197], v[84:87]
	v_mfma_f32_16x16x32_bf16 v[80:83], v[170:173], v[194:197], v[80:83]
	v_mfma_f32_16x16x32_bf16 v[68:71], v[150:153], v[202:205], v[68:71]
	v_mfma_f32_16x16x32_bf16 v[64:67], v[170:173], v[202:205], v[64:67]
	v_mfma_f32_16x16x32_bf16 v[116:119], v[166:169], v[182:185], v[116:119]
	v_mfma_f32_16x16x32_bf16 v[112:115], v[174:177], v[182:185], v[112:115]
	v_mfma_f32_16x16x32_bf16 v[100:103], v[166:169], v[190:193], v[100:103]
	v_mfma_f32_16x16x32_bf16 v[96:99], v[174:177], v[190:193], v[96:99]
	v_mfma_f32_16x16x32_bf16 v[84:87], v[166:169], v[198:201], v[84:87]
	v_mfma_f32_16x16x32_bf16 v[80:83], v[174:177], v[198:201], v[80:83]
	v_mfma_f32_16x16x32_bf16 v[68:71], v[166:169], v[206:209], v[68:71]
	v_mfma_f32_16x16x32_bf16 v[64:67], v[174:177], v[206:209], v[64:67]
	s_barrier
	s_add_i32 s93, s93, s46
	v_lshl_add_u64 v[154:155], vcc, 0, v[156:157]
	s_mov_b32 m0, s93
	ds_read_b128 v[178:181], v241 offset:16384
	ds_read_b128 v[182:185], v241 offset:17408
	ds_read_b128 v[186:189], v241 offset:18432
	ds_read_b128 v[190:193], v241 offset:19456
	ds_read_b128 v[194:197], v241 offset:20480
	ds_read_b128 v[198:201], v241 offset:21504
	ds_read_b128 v[202:205], v241 offset:22528
	ds_read_b128 v[206:209], v241 offset:23552
	global_load_lds_dwordx4 v[154:155], off
	s_add_i32 m0, s93, 0x2000
	v_lshl_add_u64 v[162:163], vcc, 0, v[128:129]
	s_add_u32 vcc_lo, vcc_lo, s10
	s_addc_u32 vcc_hi, vcc_hi, s11
	s_add_i32 s37, s37, s46
	global_load_lds_dwordx4 v[162:163], off
	v_lshl_add_u64 v[210:211], vcc, 0, v[156:157]
	s_mov_b32 m0, s37
	v_lshl_add_u64 v[212:213], vcc, 0, v[128:129]
	global_load_lds_dwordx4 v[210:211], off
	s_add_i32 m0, s37, 0x2000
	v_lshl_add_u64 v[214:215], s[22:23], 0, v[156:157]
	global_load_lds_dwordx4 v[212:213], off
	s_mov_b32 m0, s47
	v_lshl_add_u64 v[216:217], s[22:23], 0, v[128:129]
	global_load_lds_dwordx4 v[214:215], off
	s_mov_b32 m0, s52
	s_nop 0
	global_load_lds_dwordx4 v[216:217], off
	s_waitcnt vmcnt(8)
	s_waitcnt lgkmcnt(0)
	s_barrier
	s_waitcnt lgkmcnt(0)
	v_mfma_f32_16x16x32_bf16 v[60:63], v[134:137], v[178:181], v[60:63]
	v_mfma_f32_16x16x32_bf16 v[56:59], v[142:145], v[178:181], v[56:59]
	v_mfma_f32_16x16x32_bf16 v[44:47], v[134:137], v[186:189], v[44:47]
	v_mfma_f32_16x16x32_bf16 v[40:43], v[142:145], v[186:189], v[40:43]
	v_mfma_f32_16x16x32_bf16 v[28:31], v[134:137], v[194:197], v[28:31]
	v_mfma_f32_16x16x32_bf16 v[24:27], v[142:145], v[194:197], v[24:27]
	v_mfma_f32_16x16x32_bf16 v[12:15], v[134:137], v[202:205], v[12:15]
	v_mfma_f32_16x16x32_bf16 v[8:11], v[142:145], v[202:205], v[8:11]
	v_mfma_f32_16x16x32_bf16 v[60:63], v[138:141], v[182:185], v[60:63]
	v_mfma_f32_16x16x32_bf16 v[56:59], v[146:149], v[182:185], v[56:59]
	v_mfma_f32_16x16x32_bf16 v[44:47], v[138:141], v[190:193], v[44:47]
	v_mfma_f32_16x16x32_bf16 v[40:43], v[146:149], v[190:193], v[40:43]
	v_mfma_f32_16x16x32_bf16 v[28:31], v[138:141], v[198:201], v[28:31]
	v_mfma_f32_16x16x32_bf16 v[24:27], v[146:149], v[198:201], v[24:27]
	v_mfma_f32_16x16x32_bf16 v[12:15], v[138:141], v[206:209], v[12:15]
	v_mfma_f32_16x16x32_bf16 v[8:11], v[146:149], v[206:209], v[8:11]
	v_mfma_f32_16x16x32_bf16 v[52:55], v[150:153], v[178:181], v[52:55]
	v_mfma_f32_16x16x32_bf16 v[48:51], v[170:173], v[178:181], v[48:51]
	v_mfma_f32_16x16x32_bf16 v[36:39], v[150:153], v[186:189], v[36:39]
	v_mfma_f32_16x16x32_bf16 v[32:35], v[170:173], v[186:189], v[32:35]
	v_mfma_f32_16x16x32_bf16 v[20:23], v[150:153], v[194:197], v[20:23]
	v_mfma_f32_16x16x32_bf16 v[16:19], v[170:173], v[194:197], v[16:19]
	v_mfma_f32_16x16x32_bf16 v[4:7], v[150:153], v[202:205], v[4:7]
	v_mfma_f32_16x16x32_bf16 v[0:3], v[170:173], v[202:205], v[0:3]
	v_mfma_f32_16x16x32_bf16 v[52:55], v[166:169], v[182:185], v[52:55]
	v_mfma_f32_16x16x32_bf16 v[48:51], v[174:177], v[182:185], v[48:51]
	v_mfma_f32_16x16x32_bf16 v[36:39], v[166:169], v[190:193], v[36:39]
	v_mfma_f32_16x16x32_bf16 v[32:35], v[174:177], v[190:193], v[32:35]
	v_mfma_f32_16x16x32_bf16 v[20:23], v[166:169], v[198:201], v[20:23]
	v_mfma_f32_16x16x32_bf16 v[16:19], v[174:177], v[198:201], v[16:19]
	v_mfma_f32_16x16x32_bf16 v[4:7], v[166:169], v[206:209], v[4:7]
	v_mfma_f32_16x16x32_bf16 v[0:3], v[174:177], v[206:209], v[0:3]
	s_barrier
; #define PG8_STAGE(bufoff, gbase, voff) do { _Pragma("unroll") for (int _i = 0; _i < 2; ++_i) \
;         __builtin_amdgcn_global_load_lds((const unsigned*)((const char*)(gbase) + (voff)[_i]), (PG8_LAS unsigned*)(lds + (bufoff) + ldsw + _i * 8192), 16, 0, 0); } while (0)
; #define PG8_LDA(dst, b, h) do { _Pragma("unroll") for (int m = 0; m < 4; ++m) _Pragma("unroll") for (int k = 0; k < 2; ++k) dst[m][k] = *(const PG8_LAS bf16x8*)(lds + PG8_SA(b, h) + aoff + m * 2048 + k * 1024); } while (0)
; #define PG8_LDB(dst, b, h) do { _Pragma("unroll") for (int n = 0; n < 2; ++n) _Pragma("unroll") for (int k = 0; k < 2; ++k) dst[n][k] = *(const PG8_LAS bf16x8*)(lds + PG8_SB(b, h) + boff + n * 2048 + k * 1024); } while (0)
; #define PG8_MMA(ai, bj, At, Bt) do { __builtin_amdgcn_s_setprio(1); _Pragma("unroll") for (int m = 0; m < 4; ++m) _Pragma("unroll") for (int n = 0; n < 2; ++n) _Pragma("unroll") for (int k = 0; k < 2; ++k) \
;         acc[ai][bj][m][n] = __builtin_amdgcn_mfma_f32_16x16x32_bf16(Bt[n][k], At[m][k], acc[ai][bj][m][n], 0, 0, 0); __builtin_amdgcn_s_setprio(0); } while (0)
; #define PG8_WAIT_V(n) asm volatile("s_waitcnt vmcnt(" #n ")" ::: "memory")
; #define PG8_WAIT_L(n) asm volatile("s_waitcnt lgkmcnt(" #n ")" ::: "memory")
; #define PG8_BAR __builtin_amdgcn_s_barrier()
; #define PG8_SCHED __builtin_amdgcn_sched_barrier(0)
; template <class Epi, class Sched, bool ALIGN_EPI = false, bool SP2 = false>
; __device__ __forceinline__ void gemm_phase(PG8_LAS unsigned char* lds, const Gemm g, const Sched& S, const Epi& E, int tid_in) {
;     ...
;             PG8_LDB(B0, 1, 0); PG8_LDB(B1, 1, 1); PG8_SCHED; PG8_LDA(At, 1, 0); PG8_STAGE(PG8_SA(0, 1), a2 + hstep, voffA);
;             PG8_WAIT_V(8); PG8_WAIT_L(0); PG8_BAR; PG8_MMA(0, 0, At, B0); PG8_MMA(0, 1, At, B1); PG8_BAR; PG8_SCHED;
;             PG8_LDA(At, 1, 1); PG8_STAGE(PG8_SB(1, 0), b3, voffB); PG8_STAGE(PG8_SB(1, 1), b3 + hstep, voffB); PG8_STAGE(PG8_SA(1, 0), a3, voffA);
;             PG8_WAIT_V(8); PG8_WAIT_L(0); PG8_BAR; PG8_MMA(1, 0, At, B0); PG8_MMA(1, 1, At, B1); PG8_BAR; PG8_SCHED;
	s_add_i32 s37, 0, 0x18000
	s_add_i32 s93, 0, 0x1c000
	v_add_u32_e32 v146, s37, v237
	v_add_u32_e32 v174, s93, v237
	ds_read_b128 v[134:137], v146
	ds_read_b128 v[138:141], v146 offset:1024
	ds_read_b128 v[142:145], v146 offset:2048
	ds_read_b128 v[146:149], v146 offset:3072
	ds_read_b128 v[150:153], v174
	ds_read_b128 v[166:169], v174 offset:1024
	ds_read_b128 v[170:173], v174 offset:2048
	ds_read_b128 v[174:177], v174 offset:3072
	s_add_u32 s22, s22, s10
	s_addc_u32 s23, s23, s11
	s_mov_b32 m0, s53
	v_lshl_add_u64 v[218:219], s[22:23], 0, v[156:157]
	ds_read_b128 v[178:181], v241 offset:32768
	ds_read_b128 v[182:185], v241 offset:33792
	ds_read_b128 v[186:189], v241 offset:34816
	ds_read_b128 v[190:193], v241 offset:35840
	ds_read_b128 v[194:197], v241 offset:36864
	ds_read_b128 v[198:201], v241 offset:37888
	ds_read_b128 v[202:205], v241 offset:38912
	ds_read_b128 v[206:209], v241 offset:39936
	global_load_lds_dwordx4 v[218:219], off
	v_lshl_add_u64 v[218:219], s[22:23], 0, v[128:129]
	s_mov_b32 m0, s56
	s_nop 0
	global_load_lds_dwordx4 v[218:219], off
	s_waitcnt vmcnt(8)
	s_waitcnt lgkmcnt(0)
	s_barrier
	s_waitcnt lgkmcnt(0)
	v_mfma_f32_16x16x32_bf16 v[124:127], v[134:137], v[178:181], v[124:127]
	v_mfma_f32_16x16x32_bf16 v[120:123], v[142:145], v[178:181], v[120:123]
	v_mfma_f32_16x16x32_bf16 v[108:111], v[134:137], v[186:189], v[108:111]
	v_mfma_f32_16x16x32_bf16 v[104:107], v[142:145], v[186:189], v[104:107]
	v_mfma_f32_16x16x32_bf16 v[92:95], v[134:137], v[194:197], v[92:95]
	v_mfma_f32_16x16x32_bf16 v[88:91], v[142:145], v[194:197], v[88:91]
	v_mfma_f32_16x16x32_bf16 v[76:79], v[134:137], v[202:205], v[76:79]
	v_mfma_f32_16x16x32_bf16 v[72:75], v[142:145], v[202:205], v[72:75]
	v_mfma_f32_16x16x32_bf16 v[124:127], v[138:141], v[182:185], v[124:127]
	v_mfma_f32_16x16x32_bf16 v[120:123], v[146:149], v[182:185], v[120:123]
	v_mfma_f32_16x16x32_bf16 v[108:111], v[138:141], v[190:193], v[108:111]
	v_mfma_f32_16x16x32_bf16 v[104:107], v[146:149], v[190:193], v[104:107]
	v_mfma_f32_16x16x32_bf16 v[92:95], v[138:141], v[198:201], v[92:95]
	v_mfma_f32_16x16x32_bf16 v[88:91], v[146:149], v[198:201], v[88:91]
	v_mfma_f32_16x16x32_bf16 v[76:79], v[138:141], v[206:209], v[76:79]
	v_mfma_f32_16x16x32_bf16 v[72:75], v[146:149], v[206:209], v[72:75]
	v_mfma_f32_16x16x32_bf16 v[116:119], v[150:153], v[178:181], v[116:119]
	v_mfma_f32_16x16x32_bf16 v[112:115], v[170:173], v[178:181], v[112:115]
	v_mfma_f32_16x16x32_bf16 v[100:103], v[150:153], v[186:189], v[100:103]
	v_mfma_f32_16x16x32_bf16 v[96:99], v[170:173], v[186:189], v[96:99]
	v_mfma_f32_16x16x32_bf16 v[84:87], v[150:153], v[194:197], v[84:87]
	v_mfma_f32_16x16x32_bf16 v[80:83], v[170:173], v[194:197], v[80:83]
	v_mfma_f32_16x16x32_bf16 v[68:71], v[150:153], v[202:205], v[68:71]
	v_mfma_f32_16x16x32_bf16 v[64:67], v[170:173], v[202:205], v[64:67]
	v_mfma_f32_16x16x32_bf16 v[116:119], v[166:169], v[182:185], v[116:119]
	v_mfma_f32_16x16x32_bf16 v[112:115], v[174:177], v[182:185], v[112:115]
	v_mfma_f32_16x16x32_bf16 v[100:103], v[166:169], v[190:193], v[100:103]
	v_mfma_f32_16x16x32_bf16 v[96:99], v[174:177], v[190:193], v[96:99]
	v_mfma_f32_16x16x32_bf16 v[84:87], v[166:169], v[198:201], v[84:87]
	v_mfma_f32_16x16x32_bf16 v[80:83], v[174:177], v[198:201], v[80:83]
	v_mfma_f32_16x16x32_bf16 v[68:71], v[166:169], v[206:209], v[68:71]
	v_mfma_f32_16x16x32_bf16 v[64:67], v[174:177], v[206:209], v[64:67]
	s_barrier
	s_add_i32 s22, s37, s46
	v_lshl_add_u64 v[154:155], v[154:155], 0, s[64:65]
	s_mov_b32 m0, s22
	ds_read_b128 v[178:181], v241 offset:49152
	ds_read_b128 v[182:185], v241 offset:50176
	ds_read_b128 v[186:189], v241 offset:51200
	ds_read_b128 v[190:193], v241 offset:52224
	ds_read_b128 v[194:197], v241 offset:53248
	ds_read_b128 v[198:201], v241 offset:54272
	ds_read_b128 v[202:205], v241 offset:55296
	ds_read_b128 v[206:209], v241 offset:56320
	global_load_lds_dwordx4 v[154:155], off
	v_lshl_add_u64 v[154:155], v[162:163], 0, s[64:65]
	s_add_i32 m0, s22, 0x2000
	s_add_i32 s22, s93, s46
	global_load_lds_dwordx4 v[154:155], off
	v_lshl_add_u64 v[154:155], v[210:211], 0, s[64:65]
	s_mov_b32 m0, s22
	s_nop 0
	global_load_lds_dwordx4 v[154:155], off
	v_lshl_add_u64 v[154:155], v[212:213], 0, s[64:65]
	s_add_i32 m0, s22, 0x2000
	s_nop 0
	global_load_lds_dwordx4 v[154:155], off
	v_lshl_add_u64 v[154:155], v[214:215], 0, s[64:65]
	s_mov_b32 m0, s66
	s_nop 0
	global_load_lds_dwordx4 v[154:155], off
	v_lshl_add_u64 v[154:155], v[216:217], 0, s[64:65]
	s_mov_b32 m0, s67
	s_nop 0
	global_load_lds_dwordx4 v[154:155], off
	s_waitcnt vmcnt(8)
	s_waitcnt lgkmcnt(0)
	s_barrier
	s_waitcnt lgkmcnt(0)
	v_mfma_f32_16x16x32_bf16 v[60:63], v[134:137], v[178:181], v[60:63]
	v_mfma_f32_16x16x32_bf16 v[56:59], v[142:145], v[178:181], v[56:59]
	v_mfma_f32_16x16x32_bf16 v[44:47], v[134:137], v[186:189], v[44:47]
	v_mfma_f32_16x16x32_bf16 v[40:43], v[142:145], v[186:189], v[40:43]
	v_mfma_f32_16x16x32_bf16 v[28:31], v[134:137], v[194:197], v[28:31]
	v_mfma_f32_16x16x32_bf16 v[24:27], v[142:145], v[194:197], v[24:27]
	v_mfma_f32_16x16x32_bf16 v[12:15], v[134:137], v[202:205], v[12:15]
	v_mfma_f32_16x16x32_bf16 v[8:11], v[142:145], v[202:205], v[8:11]
	v_mfma_f32_16x16x32_bf16 v[60:63], v[138:141], v[182:185], v[60:63]
	v_mfma_f32_16x16x32_bf16 v[56:59], v[146:149], v[182:185], v[56:59]
	v_mfma_f32_16x16x32_bf16 v[44:47], v[138:141], v[190:193], v[44:47]
	v_mfma_f32_16x16x32_bf16 v[40:43], v[146:149], v[190:193], v[40:43]
	v_mfma_f32_16x16x32_bf16 v[28:31], v[138:141], v[198:201], v[28:31]
	v_mfma_f32_16x16x32_bf16 v[24:27], v[146:149], v[198:201], v[24:27]
	v_mfma_f32_16x16x32_bf16 v[12:15], v[138:141], v[206:209], v[12:15]
	v_mfma_f32_16x16x32_bf16 v[8:11], v[146:149], v[206:209], v[8:11]
	v_mfma_f32_16x16x32_bf16 v[52:55], v[150:153], v[178:181], v[52:55]
	v_mfma_f32_16x16x32_bf16 v[48:51], v[170:173], v[178:181], v[48:51]
	v_mfma_f32_16x16x32_bf16 v[36:39], v[150:153], v[186:189], v[36:39]
	v_mfma_f32_16x16x32_bf16 v[32:35], v[170:173], v[186:189], v[32:35]
	v_mfma_f32_16x16x32_bf16 v[20:23], v[150:153], v[194:197], v[20:23]
	v_mfma_f32_16x16x32_bf16 v[16:19], v[170:173], v[194:197], v[16:19]
	v_mfma_f32_16x16x32_bf16 v[4:7], v[150:153], v[202:205], v[4:7]
	v_mfma_f32_16x16x32_bf16 v[0:3], v[170:173], v[202:205], v[0:3]
	v_mfma_f32_16x16x32_bf16 v[52:55], v[166:169], v[182:185], v[52:55]
	v_mfma_f32_16x16x32_bf16 v[48:51], v[174:177], v[182:185], v[48:51]
	s_add_u32 s0, s0, 0x100
	v_mfma_f32_16x16x32_bf16 v[36:39], v[166:169], v[190:193], v[36:39]
	s_addc_u32 s1, s1, 0
	v_mfma_f32_16x16x32_bf16 v[32:35], v[174:177], v[190:193], v[32:35]
	s_add_u32 s55, s55, 0x100
	v_mfma_f32_16x16x32_bf16 v[20:23], v[166:169], v[198:201], v[20:23]
	s_addc_u32 s92, s92, 0
	v_mfma_f32_16x16x32_bf16 v[16:19], v[174:177], v[198:201], v[16:19]
	s_cmp_ge_i32 s36, s63
	v_mfma_f32_16x16x32_bf16 v[4:7], v[166:169], v[206:209], v[4:7]
	s_mov_b32 s22, s36
	v_mfma_f32_16x16x32_bf16 v[0:3], v[174:177], v[206:209], v[0:3]
	s_barrier
	s_cbranch_scc0 .LBB0_1024
